# GEMM main loops: redundant lgkmcnt(0) right after each barrier removed (the pre-barrier wait already drained LDS reads)
# speedup vs baseline: 1.0060x; 1.0003x over previous
; #define PG8_STAGE(bufoff, gbase, voff) do { _Pragma("unroll") for (int _i = 0; _i < 2; ++_i) \
;         __builtin_amdgcn_global_load_lds((const unsigned*)((const char*)(gbase) + (voff)[_i]), (LAS unsigned*)(lds + (bufoff) + ldsw + _i * 8192), 16, 0, 0); } while (0)
; #define PG8_LDA(dst, b, h) do { _Pragma("unroll") for (int m = 0; m < 4; ++m) _Pragma("unroll") for (int k = 0; k < 2; ++k) dst[m][k] = *(const LAS bf16x8*)(lds + PG8_SA(b, h) + aoff + m * 2048 + k * 1024); } while (0)
; #define PG8_LDB(dst, b, h) do { _Pragma("unroll") for (int n = 0; n < 2; ++n) _Pragma("unroll") for (int k = 0; k < 2; ++k) dst[n][k] = *(const LAS bf16x8*)(lds + PG8_SB(b, h) + boff + n * 2048 + k * 1024); } while (0)
; #define PG8_MMA(ai, bj, At, Bt) do { __builtin_amdgcn_s_setprio(1); _Pragma("unroll") for (int m = 0; m < 4; ++m) _Pragma("unroll") for (int n = 0; n < 2; ++n) _Pragma("unroll") for (int k = 0; k < 2; ++k) \
;         acc[ai][bj][m][n] = __builtin_amdgcn_mfma_f32_16x16x32_bf16(Bt[n][k], At[m][k], acc[ai][bj][m][n], 0, 0, 0); __builtin_amdgcn_s_setprio(0); } while (0)
; #define PG8_WAIT_V(n) asm volatile("s_waitcnt vmcnt(" #n ")" ::: "memory")
; #define PG8_WAIT_L(n) asm volatile("s_waitcnt lgkmcnt(" #n ")" ::: "memory")
; #define PG8_BAR __builtin_amdgcn_s_barrier()
; #define PG8_SCHED __builtin_amdgcn_sched_barrier(0)
; template <class Epi>
; __device__ __forceinline__ void gemm_phase(LAS unsigned char* lds, const Gemm g, const Sched& S, const Epi& E) {
;     ...
;             const bool last = (t == nt - 2);
;             const char* a1 = cA + (size_t)(t + 1) * kstep;
;             const char* a2 = last ? nA : cA + (size_t)(t + 2) * kstep; const char* b2 = last ? nB : cB + (size_t)(t + 2) * kstep;
;             const char* a3 = a2 + kstep; const char* b3 = b2 + kstep;
;             PG8_LDB(B0, 0, 0); PG8_LDB(B1, 0, 1); PG8_SCHED; PG8_LDA(At, 0, 0); PG8_STAGE(PG8_SA(1, 1), a1 + hstepA, voffA);
;             PG8_WAIT_V(8); PG8_WAIT_L(0); PG8_BAR; PG8_MMA(0, 0, At, B0); PG8_MMA(0, 1, At, B1); PG8_BAR; PG8_SCHED;
;             PG8_LDA(At, 0, 1); PG8_STAGE(PG8_SB(0, 0), b2, voffB); PG8_STAGE(PG8_SB(0, 1), b2 + hstepB, voffB); PG8_STAGE(PG8_SA(0, 0), a2, voffA);
;             PG8_WAIT_V(8); PG8_WAIT_L(0); PG8_BAR; PG8_MMA(1, 0, At, B0); PG8_MMA(1, 1, At, B1); PG8_BAR; PG8_SCHED;
.LBB0_163:
	ds_read_b128 v[148:151], v145
	ds_read_b128 v[152:155], v145 offset:1024
	ds_read_b128 v[156:159], v145 offset:2048
	ds_read_b128 v[160:163], v145 offset:3072
	ds_read_b128 v[164:167], v146
	ds_read_b128 v[168:171], v146 offset:1024
	ds_read_b128 v[172:175], v146 offset:2048
	ds_read_b128 v[176:179], v146 offset:3072
	s_add_u32 s44, s40, 0xfffc0080
	s_addc_u32 s45, s41, -1
	s_cmp_eq_u32 s67, 12
	s_cselect_b32 s47, s21, s45
	s_cselect_b32 s46, s27, s44
	s_cselect_b32 s45, s15, s66
	s_cselect_b32 s44, s64, s65
	v_lshl_add_u64 v[140:141], s[40:41], 0, v[136:137]
	s_add_i32 m0, s29, 0xc000
	ds_read_b128 v[180:183], v147
	ds_read_b128 v[184:187], v147 offset:1024
	ds_read_b128 v[188:191], v147 offset:2048
	ds_read_b128 v[192:195], v147 offset:3072
	ds_read_b128 v[196:199], v147 offset:4096
	ds_read_b128 v[204:207], v147 offset:5120
	ds_read_b128 v[208:211], v147 offset:6144
	ds_read_b128 v[212:215], v147 offset:7168
	global_load_lds_dwordx4 v[140:141], off
	v_lshl_add_u64 v[140:141], s[40:41], 0, v[138:139]
	s_add_i32 m0, s29, 0xe000
	s_nop 0
	global_load_lds_dwordx4 v[140:141], off
	s_waitcnt vmcnt(8)
	s_waitcnt lgkmcnt(0)
	s_barrier
	s_setprio 1
	v_mfma_f32_16x16x32_bf16 v[116:119], v[148:151], v[180:183], v[116:119]
	v_mfma_f32_16x16x32_bf16 v[124:127], v[156:159], v[180:183], v[124:127]
	v_mfma_f32_16x16x32_bf16 v[100:103], v[148:151], v[188:191], v[100:103]
	v_mfma_f32_16x16x32_bf16 v[108:111], v[156:159], v[188:191], v[108:111]
	v_mfma_f32_16x16x32_bf16 v[84:87], v[148:151], v[196:199], v[84:87]
	v_mfma_f32_16x16x32_bf16 v[92:95], v[156:159], v[196:199], v[92:95]
	v_mfma_f32_16x16x32_bf16 v[68:71], v[148:151], v[208:211], v[68:71]
	v_mfma_f32_16x16x32_bf16 v[76:79], v[156:159], v[208:211], v[76:79]
	v_mfma_f32_16x16x32_bf16 v[116:119], v[152:155], v[184:187], v[116:119]
	v_mfma_f32_16x16x32_bf16 v[124:127], v[160:163], v[184:187], v[124:127]
	v_mfma_f32_16x16x32_bf16 v[100:103], v[152:155], v[192:195], v[100:103]
	v_mfma_f32_16x16x32_bf16 v[108:111], v[160:163], v[192:195], v[108:111]
	v_mfma_f32_16x16x32_bf16 v[84:87], v[152:155], v[204:207], v[84:87]
	v_mfma_f32_16x16x32_bf16 v[92:95], v[160:163], v[204:207], v[92:95]
	v_mfma_f32_16x16x32_bf16 v[68:71], v[152:155], v[212:215], v[68:71]
	v_mfma_f32_16x16x32_bf16 v[76:79], v[160:163], v[212:215], v[76:79]
	v_mfma_f32_16x16x32_bf16 v[112:115], v[164:167], v[180:183], v[112:115]
	v_mfma_f32_16x16x32_bf16 v[120:123], v[172:175], v[180:183], v[120:123]
	v_mfma_f32_16x16x32_bf16 v[96:99], v[164:167], v[188:191], v[96:99]
	v_mfma_f32_16x16x32_bf16 v[104:107], v[172:175], v[188:191], v[104:107]
	v_mfma_f32_16x16x32_bf16 v[80:83], v[164:167], v[196:199], v[80:83]
	v_mfma_f32_16x16x32_bf16 v[88:91], v[172:175], v[196:199], v[88:91]
	v_mfma_f32_16x16x32_bf16 v[64:67], v[164:167], v[208:211], v[64:67]
	v_mfma_f32_16x16x32_bf16 v[72:75], v[172:175], v[208:211], v[72:75]
	v_mfma_f32_16x16x32_bf16 v[112:115], v[168:171], v[184:187], v[112:115]
	v_mfma_f32_16x16x32_bf16 v[120:123], v[176:179], v[184:187], v[120:123]
	v_mfma_f32_16x16x32_bf16 v[96:99], v[168:171], v[192:195], v[96:99]
	v_mfma_f32_16x16x32_bf16 v[104:107], v[176:179], v[192:195], v[104:107]
	v_mfma_f32_16x16x32_bf16 v[80:83], v[168:171], v[204:207], v[80:83]
	v_mfma_f32_16x16x32_bf16 v[88:91], v[176:179], v[204:207], v[88:91]
	v_mfma_f32_16x16x32_bf16 v[64:67], v[168:171], v[212:215], v[64:67]
	v_mfma_f32_16x16x32_bf16 v[72:75], v[176:179], v[212:215], v[72:75]
	s_setprio 0
	s_barrier
	s_add_i32 s78, s60, s53
	v_lshl_add_u64 v[140:141], s[44:45], 0, v[130:131]
	s_mov_b32 m0, s78
	ds_read_b128 v[180:183], v147 offset:16384
	ds_read_b128 v[184:187], v147 offset:17408
	ds_read_b128 v[188:191], v147 offset:18432
	ds_read_b128 v[192:195], v147 offset:19456
	ds_read_b128 v[196:199], v147 offset:20480
	ds_read_b128 v[204:207], v147 offset:21504
	ds_read_b128 v[208:211], v147 offset:22528
	ds_read_b128 v[212:215], v147 offset:23552
	global_load_lds_dwordx4 v[140:141], off
	s_add_i32 m0, s78, 0x2000
	s_add_u32 s78, s44, 0x40000
	v_lshl_add_u64 v[200:201], s[44:45], 0, v[134:135]
	s_addc_u32 s79, s45, 0
	s_add_i32 s82, s61, s53
	global_load_lds_dwordx4 v[200:201], off
	v_lshl_add_u64 v[216:217], s[78:79], 0, v[130:131]
	s_mov_b32 m0, s82
	v_lshl_add_u64 v[218:219], s[46:47], 0, v[132:133]
	global_load_lds_dwordx4 v[216:217], off
	v_lshl_add_u64 v[216:217], s[78:79], 0, v[134:135]
	s_add_i32 m0, s82, 0x2000
	s_nop 0
	global_load_lds_dwordx4 v[216:217], off
	v_lshl_add_u64 v[216:217], s[46:47], 0, v[128:129]
	s_mov_b32 m0, s29
	s_nop 0
	global_load_lds_dwordx4 v[216:217], off
	s_mov_b32 m0, s54
	s_nop 0
	global_load_lds_dwordx4 v[218:219], off
	s_waitcnt vmcnt(8)
	s_waitcnt lgkmcnt(0)
	s_barrier
; #define PG8_STAGE(bufoff, gbase, voff) do { _Pragma("unroll") for (int _i = 0; _i < 2; ++_i) \
;         __builtin_amdgcn_global_load_lds((const unsigned*)((const char*)(gbase) + (voff)[_i]), (LAS unsigned*)(lds + (bufoff) + ldsw + _i * 8192), 16, 0, 0); } while (0)
; #define PG8_LDA(dst, b, h) do { _Pragma("unroll") for (int m = 0; m < 4; ++m) _Pragma("unroll") for (int k = 0; k < 2; ++k) dst[m][k] = *(const LAS bf16x8*)(lds + PG8_SA(b, h) + aoff + m * 2048 + k * 1024); } while (0)
; #define PG8_LDB(dst, b, h) do { _Pragma("unroll") for (int n = 0; n < 2; ++n) _Pragma("unroll") for (int k = 0; k < 2; ++k) dst[n][k] = *(const LAS bf16x8*)(lds + PG8_SB(b, h) + boff + n * 2048 + k * 1024); } while (0)
; #define PG8_MMA(ai, bj, At, Bt) do { __builtin_amdgcn_s_setprio(1); _Pragma("unroll") for (int m = 0; m < 4; ++m) _Pragma("unroll") for (int n = 0; n < 2; ++n) _Pragma("unroll") for (int k = 0; k < 2; ++k) \
;         acc[ai][bj][m][n] = __builtin_amdgcn_mfma_f32_16x16x32_bf16(Bt[n][k], At[m][k], acc[ai][bj][m][n], 0, 0, 0); __builtin_amdgcn_s_setprio(0); } while (0)
; #define PG8_WAIT_V(n) asm volatile("s_waitcnt vmcnt(" #n ")" ::: "memory")
; #define PG8_WAIT_L(n) asm volatile("s_waitcnt lgkmcnt(" #n ")" ::: "memory")
; #define PG8_BAR __builtin_amdgcn_s_barrier()
; #define PG8_SCHED __builtin_amdgcn_sched_barrier(0)
; template <class Epi>
; __device__ __forceinline__ void gemm_phase(LAS unsigned char* lds, const Gemm g, const Sched& S, const Epi& E) {
;     ...
;             PG8_WAIT_V(8); PG8_WAIT_L(0); PG8_BAR; PG8_MMA(1, 0, At, B0); PG8_MMA(1, 1, At, B1); PG8_BAR; PG8_SCHED;
;             PG8_LDB(B0, 1, 0); PG8_LDB(B1, 1, 1); PG8_SCHED; PG8_LDA(At, 1, 0); PG8_STAGE(PG8_SA(0, 1), a2 + hstepA, voffA);
;             PG8_WAIT_V(8); PG8_WAIT_L(0); PG8_BAR; PG8_MMA(0, 0, At, B0); PG8_MMA(0, 1, At, B1); PG8_BAR; PG8_SCHED;
	s_setprio 1
	v_mfma_f32_16x16x32_bf16 v[52:55], v[148:151], v[180:183], v[52:55]
	v_mfma_f32_16x16x32_bf16 v[60:63], v[156:159], v[180:183], v[60:63]
	v_mfma_f32_16x16x32_bf16 v[36:39], v[148:151], v[188:191], v[36:39]
	v_mfma_f32_16x16x32_bf16 v[44:47], v[156:159], v[188:191], v[44:47]
	v_mfma_f32_16x16x32_bf16 v[20:23], v[148:151], v[196:199], v[20:23]
	v_mfma_f32_16x16x32_bf16 v[28:31], v[156:159], v[196:199], v[28:31]
	v_mfma_f32_16x16x32_bf16 v[4:7], v[148:151], v[208:211], v[4:7]
	v_mfma_f32_16x16x32_bf16 v[12:15], v[156:159], v[208:211], v[12:15]
	v_mfma_f32_16x16x32_bf16 v[52:55], v[152:155], v[184:187], v[52:55]
	v_mfma_f32_16x16x32_bf16 v[60:63], v[160:163], v[184:187], v[60:63]
	v_mfma_f32_16x16x32_bf16 v[36:39], v[152:155], v[192:195], v[36:39]
	v_mfma_f32_16x16x32_bf16 v[44:47], v[160:163], v[192:195], v[44:47]
	v_mfma_f32_16x16x32_bf16 v[20:23], v[152:155], v[204:207], v[20:23]
	v_mfma_f32_16x16x32_bf16 v[28:31], v[160:163], v[204:207], v[28:31]
	v_mfma_f32_16x16x32_bf16 v[4:7], v[152:155], v[212:215], v[4:7]
	v_mfma_f32_16x16x32_bf16 v[12:15], v[160:163], v[212:215], v[12:15]
	v_mfma_f32_16x16x32_bf16 v[48:51], v[164:167], v[180:183], v[48:51]
	v_mfma_f32_16x16x32_bf16 v[56:59], v[172:175], v[180:183], v[56:59]
	v_mfma_f32_16x16x32_bf16 v[32:35], v[164:167], v[188:191], v[32:35]
	v_mfma_f32_16x16x32_bf16 v[40:43], v[172:175], v[188:191], v[40:43]
	v_mfma_f32_16x16x32_bf16 v[16:19], v[164:167], v[196:199], v[16:19]
	v_mfma_f32_16x16x32_bf16 v[24:27], v[172:175], v[196:199], v[24:27]
	v_mfma_f32_16x16x32_bf16 v[0:3], v[164:167], v[208:211], v[0:3]
	v_mfma_f32_16x16x32_bf16 v[8:11], v[172:175], v[208:211], v[8:11]
	v_mfma_f32_16x16x32_bf16 v[48:51], v[168:171], v[184:187], v[48:51]
	v_mfma_f32_16x16x32_bf16 v[56:59], v[176:179], v[184:187], v[56:59]
	v_mfma_f32_16x16x32_bf16 v[32:35], v[168:171], v[192:195], v[32:35]
	v_mfma_f32_16x16x32_bf16 v[40:43], v[176:179], v[192:195], v[40:43]
	v_mfma_f32_16x16x32_bf16 v[16:19], v[168:171], v[204:207], v[16:19]
	v_mfma_f32_16x16x32_bf16 v[24:27], v[176:179], v[204:207], v[24:27]
	v_mfma_f32_16x16x32_bf16 v[0:3], v[168:171], v[212:215], v[0:3]
	v_mfma_f32_16x16x32_bf16 v[8:11], v[176:179], v[212:215], v[8:11]
	s_setprio 0
	s_barrier
	s_add_i32 s78, 0, 0x18000
	s_add_i32 s79, 0, 0x1c000
	v_add_u32_e32 v160, s78, v143
	v_add_u32_e32 v176, s79, v143
	ds_read_b128 v[148:151], v160
	ds_read_b128 v[152:155], v160 offset:1024
	ds_read_b128 v[156:159], v160 offset:2048
	ds_read_b128 v[160:163], v160 offset:3072
	ds_read_b128 v[164:167], v176
	ds_read_b128 v[168:171], v176 offset:1024
	ds_read_b128 v[172:175], v176 offset:2048
	ds_read_b128 v[176:179], v176 offset:3072
	s_add_u32 s46, s46, 0x40000
	s_addc_u32 s47, s47, 0
	s_mov_b32 m0, s55
	v_lshl_add_u64 v[220:221], s[46:47], 0, v[128:129]
	ds_read_b128 v[180:183], v147 offset:32768
	ds_read_b128 v[184:187], v147 offset:33792
	ds_read_b128 v[188:191], v147 offset:34816
	ds_read_b128 v[192:195], v147 offset:35840
	ds_read_b128 v[196:199], v147 offset:36864
	ds_read_b128 v[204:207], v147 offset:37888
	ds_read_b128 v[208:211], v147 offset:38912
	ds_read_b128 v[212:215], v147 offset:39936
	global_load_lds_dwordx4 v[220:221], off
	v_lshl_add_u64 v[220:221], s[46:47], 0, v[132:133]
	s_mov_b32 m0, s56
	s_nop 0
	global_load_lds_dwordx4 v[220:221], off
	s_waitcnt vmcnt(8)
	s_waitcnt lgkmcnt(0)
	s_barrier
	s_setprio 1
	v_mfma_f32_16x16x32_bf16 v[116:119], v[148:151], v[180:183], v[116:119]
	v_mfma_f32_16x16x32_bf16 v[124:127], v[156:159], v[180:183], v[124:127]
	v_mfma_f32_16x16x32_bf16 v[100:103], v[148:151], v[188:191], v[100:103]
	v_mfma_f32_16x16x32_bf16 v[108:111], v[156:159], v[188:191], v[108:111]
	v_mfma_f32_16x16x32_bf16 v[84:87], v[148:151], v[196:199], v[84:87]
	v_mfma_f32_16x16x32_bf16 v[92:95], v[156:159], v[196:199], v[92:95]
	v_mfma_f32_16x16x32_bf16 v[68:71], v[148:151], v[208:211], v[68:71]
	v_mfma_f32_16x16x32_bf16 v[76:79], v[156:159], v[208:211], v[76:79]
	v_mfma_f32_16x16x32_bf16 v[116:119], v[152:155], v[184:187], v[116:119]
	v_mfma_f32_16x16x32_bf16 v[124:127], v[160:163], v[184:187], v[124:127]
	v_mfma_f32_16x16x32_bf16 v[100:103], v[152:155], v[192:195], v[100:103]
	v_mfma_f32_16x16x32_bf16 v[108:111], v[160:163], v[192:195], v[108:111]
	v_mfma_f32_16x16x32_bf16 v[84:87], v[152:155], v[204:207], v[84:87]
	v_mfma_f32_16x16x32_bf16 v[92:95], v[160:163], v[204:207], v[92:95]
	v_mfma_f32_16x16x32_bf16 v[68:71], v[152:155], v[212:215], v[68:71]
	v_mfma_f32_16x16x32_bf16 v[76:79], v[160:163], v[212:215], v[76:79]
	v_mfma_f32_16x16x32_bf16 v[112:115], v[164:167], v[180:183], v[112:115]
	v_mfma_f32_16x16x32_bf16 v[120:123], v[172:175], v[180:183], v[120:123]
	v_mfma_f32_16x16x32_bf16 v[96:99], v[164:167], v[188:191], v[96:99]
	v_mfma_f32_16x16x32_bf16 v[104:107], v[172:175], v[188:191], v[104:107]
	v_mfma_f32_16x16x32_bf16 v[80:83], v[164:167], v[196:199], v[80:83]
	v_mfma_f32_16x16x32_bf16 v[88:91], v[172:175], v[196:199], v[88:91]
	v_mfma_f32_16x16x32_bf16 v[64:67], v[164:167], v[208:211], v[64:67]
	v_mfma_f32_16x16x32_bf16 v[72:75], v[172:175], v[208:211], v[72:75]
	v_mfma_f32_16x16x32_bf16 v[112:115], v[168:171], v[184:187], v[112:115]
	v_mfma_f32_16x16x32_bf16 v[120:123], v[176:179], v[184:187], v[120:123]
	v_mfma_f32_16x16x32_bf16 v[96:99], v[168:171], v[192:195], v[96:99]
	v_mfma_f32_16x16x32_bf16 v[104:107], v[176:179], v[192:195], v[104:107]
	v_mfma_f32_16x16x32_bf16 v[80:83], v[168:171], v[204:207], v[80:83]
	v_mfma_f32_16x16x32_bf16 v[88:91], v[176:179], v[204:207], v[88:91]
	v_mfma_f32_16x16x32_bf16 v[64:67], v[168:171], v[212:215], v[64:67]
	v_mfma_f32_16x16x32_bf16 v[72:75], v[176:179], v[212:215], v[72:75]
	s_setprio 0
	s_barrier
; #define PG8_STAGE(bufoff, gbase, voff) do { _Pragma("unroll") for (int _i = 0; _i < 2; ++_i) \
;         __builtin_amdgcn_global_load_lds((const unsigned*)((const char*)(gbase) + (voff)[_i]), (LAS unsigned*)(lds + (bufoff) + ldsw + _i * 8192), 16, 0, 0); } while (0)
; #define PG8_LDA(dst, b, h) do { _Pragma("unroll") for (int m = 0; m < 4; ++m) _Pragma("unroll") for (int k = 0; k < 2; ++k) dst[m][k] = *(const LAS bf16x8*)(lds + PG8_SA(b, h) + aoff + m * 2048 + k * 1024); } while (0)
; #define PG8_MMA(ai, bj, At, Bt) do { __builtin_amdgcn_s_setprio(1); _Pragma("unroll") for (int m = 0; m < 4; ++m) _Pragma("unroll") for (int n = 0; n < 2; ++n) _Pragma("unroll") for (int k = 0; k < 2; ++k) \
;         acc[ai][bj][m][n] = __builtin_amdgcn_mfma_f32_16x16x32_bf16(Bt[n][k], At[m][k], acc[ai][bj][m][n], 0, 0, 0); __builtin_amdgcn_s_setprio(0); } while (0)
; #define PG8_WAIT_V(n) asm volatile("s_waitcnt vmcnt(" #n ")" ::: "memory")
; #define PG8_WAIT_L(n) asm volatile("s_waitcnt lgkmcnt(" #n ")" ::: "memory")
; #define PG8_BAR __builtin_amdgcn_s_barrier()
; #define PG8_SCHED __builtin_amdgcn_sched_barrier(0)
; template <class Epi>
; __device__ __forceinline__ void gemm_phase(LAS unsigned char* lds, const Gemm g, const Sched& S, const Epi& E) {
;     ...
;             PG8_LDA(At, 1, 1); PG8_STAGE(PG8_SB(1, 0), b3, voffB); PG8_STAGE(PG8_SB(1, 1), b3 + hstepB, voffB); PG8_STAGE(PG8_SA(1, 0), a3, voffA);
;             PG8_WAIT_V(8); PG8_WAIT_L(0); PG8_BAR; PG8_MMA(1, 0, At, B0); PG8_MMA(1, 1, At, B1); PG8_BAR; PG8_SCHED;
;         }
;         if (wr == 0) PG8_BAR;
	s_add_i32 s46, s78, s53
	v_lshl_add_u64 v[140:141], v[140:141], 0, s[4:5]
	s_mov_b32 m0, s46
	ds_read_b128 v[180:183], v147 offset:49152
	ds_read_b128 v[184:187], v147 offset:50176
	ds_read_b128 v[188:191], v147 offset:51200
	ds_read_b128 v[192:195], v147 offset:52224
	ds_read_b128 v[196:199], v147 offset:53248
	ds_read_b128 v[204:207], v147 offset:54272
	ds_read_b128 v[208:211], v147 offset:55296
	ds_read_b128 v[212:215], v147 offset:56320
	global_load_lds_dwordx4 v[140:141], off
	s_add_i32 m0, s46, 0x2000
	s_add_u32 s44, s44, 0x40080
	v_lshl_add_u64 v[140:141], v[200:201], 0, s[4:5]
	s_addc_u32 s45, s45, 0
	s_add_i32 s46, s79, s53
	global_load_lds_dwordx4 v[140:141], off
	v_lshl_add_u64 v[140:141], s[44:45], 0, v[130:131]
	s_mov_b32 m0, s46
	s_nop 0
	global_load_lds_dwordx4 v[140:141], off
	v_lshl_add_u64 v[140:141], s[44:45], 0, v[134:135]
	s_add_i32 m0, s46, 0x2000
	s_nop 0
	global_load_lds_dwordx4 v[140:141], off
	v_lshl_add_u64 v[140:141], v[216:217], 0, s[4:5]
	s_mov_b32 m0, s58
	s_nop 0
	global_load_lds_dwordx4 v[140:141], off
	v_lshl_add_u64 v[140:141], v[218:219], 0, s[4:5]
	s_mov_b32 m0, s59
	s_nop 0
	global_load_lds_dwordx4 v[140:141], off
	s_waitcnt vmcnt(8)
	s_waitcnt lgkmcnt(0)
	s_barrier
	s_setprio 1
	v_mfma_f32_16x16x32_bf16 v[52:55], v[148:151], v[180:183], v[52:55]
	v_mfma_f32_16x16x32_bf16 v[60:63], v[156:159], v[180:183], v[60:63]
	v_mfma_f32_16x16x32_bf16 v[36:39], v[148:151], v[188:191], v[36:39]
	v_mfma_f32_16x16x32_bf16 v[44:47], v[156:159], v[188:191], v[44:47]
	v_mfma_f32_16x16x32_bf16 v[20:23], v[148:151], v[196:199], v[20:23]
	v_mfma_f32_16x16x32_bf16 v[28:31], v[156:159], v[196:199], v[28:31]
	v_mfma_f32_16x16x32_bf16 v[4:7], v[148:151], v[208:211], v[4:7]
	v_mfma_f32_16x16x32_bf16 v[12:15], v[156:159], v[208:211], v[12:15]
	v_mfma_f32_16x16x32_bf16 v[52:55], v[152:155], v[184:187], v[52:55]
	v_mfma_f32_16x16x32_bf16 v[60:63], v[160:163], v[184:187], v[60:63]
	v_mfma_f32_16x16x32_bf16 v[36:39], v[152:155], v[192:195], v[36:39]
	v_mfma_f32_16x16x32_bf16 v[44:47], v[160:163], v[192:195], v[44:47]
	v_mfma_f32_16x16x32_bf16 v[20:23], v[152:155], v[204:207], v[20:23]
	v_mfma_f32_16x16x32_bf16 v[28:31], v[160:163], v[204:207], v[28:31]
	v_mfma_f32_16x16x32_bf16 v[4:7], v[152:155], v[212:215], v[4:7]
	v_mfma_f32_16x16x32_bf16 v[12:15], v[160:163], v[212:215], v[12:15]
	v_mfma_f32_16x16x32_bf16 v[48:51], v[164:167], v[180:183], v[48:51]
	v_mfma_f32_16x16x32_bf16 v[56:59], v[172:175], v[180:183], v[56:59]
	v_mfma_f32_16x16x32_bf16 v[32:35], v[164:167], v[188:191], v[32:35]
	v_mfma_f32_16x16x32_bf16 v[40:43], v[172:175], v[188:191], v[40:43]
	v_mfma_f32_16x16x32_bf16 v[16:19], v[164:167], v[196:199], v[16:19]
	v_mfma_f32_16x16x32_bf16 v[24:27], v[172:175], v[196:199], v[24:27]
	v_mfma_f32_16x16x32_bf16 v[0:3], v[164:167], v[208:211], v[0:3]
	v_mfma_f32_16x16x32_bf16 v[8:11], v[172:175], v[208:211], v[8:11]
	v_mfma_f32_16x16x32_bf16 v[48:51], v[168:171], v[184:187], v[48:51]
	v_mfma_f32_16x16x32_bf16 v[56:59], v[176:179], v[184:187], v[56:59]
	v_mfma_f32_16x16x32_bf16 v[32:35], v[168:171], v[192:195], v[32:35]
	v_mfma_f32_16x16x32_bf16 v[40:43], v[176:179], v[192:195], v[40:43]
	v_mfma_f32_16x16x32_bf16 v[16:19], v[168:171], v[204:207], v[16:19]
	v_mfma_f32_16x16x32_bf16 v[24:27], v[176:179], v[204:207], v[24:27]
	v_mfma_f32_16x16x32_bf16 v[0:3], v[168:171], v[212:215], v[0:3]
	v_mfma_f32_16x16x32_bf16 v[8:11], v[176:179], v[212:215], v[8:11]
	s_setprio 0
	s_barrier
	s_add_i32 s67, s67, 2
	s_add_u32 s40, s40, 0x100
	s_addc_u32 s41, s41, 0
	s_add_u32 s65, s65, 0x100
	s_addc_u32 s66, s66, 0
	s_cmp_gt_u32 s67, 13
	s_cbranch_scc0 .LBB0_163
	s_and_b64 vcc, exec, s[6:7]
	s_cbranch_vccz .LBB0_166
	s_barrier

; #define PG8_STAGE(bufoff, gbase, voff) do { _Pragma("unroll") for (int _i = 0; _i < 2; ++_i) \
;         __builtin_amdgcn_global_load_lds((const unsigned*)((const char*)(gbase) + (voff)[_i]), (LAS unsigned*)(lds + (bufoff) + ldsw + _i * 8192), 16, 0, 0); } while (0)
; #define PG8_LDA(dst, b, h) do { _Pragma("unroll") for (int m = 0; m < 4; ++m) _Pragma("unroll") for (int k = 0; k < 2; ++k) dst[m][k] = *(const LAS bf16x8*)(lds + PG8_SA(b, h) + aoff + m * 2048 + k * 1024); } while (0)
; #define PG8_LDB(dst, b, h) do { _Pragma("unroll") for (int n = 0; n < 2; ++n) _Pragma("unroll") for (int k = 0; k < 2; ++k) dst[n][k] = *(const LAS bf16x8*)(lds + PG8_SB(b, h) + boff + n * 2048 + k * 1024); } while (0)
; #define PG8_MMA(ai, bj, At, Bt) do { __builtin_amdgcn_s_setprio(1); _Pragma("unroll") for (int m = 0; m < 4; ++m) _Pragma("unroll") for (int n = 0; n < 2; ++n) _Pragma("unroll") for (int k = 0; k < 2; ++k) \
;         acc[ai][bj][m][n] = __builtin_amdgcn_mfma_f32_16x16x32_bf16(Bt[n][k], At[m][k], acc[ai][bj][m][n], 0, 0, 0); __builtin_amdgcn_s_setprio(0); } while (0)
; #define PG8_WAIT_V(n) asm volatile("s_waitcnt vmcnt(" #n ")" ::: "memory")
; #define PG8_WAIT_L(n) asm volatile("s_waitcnt lgkmcnt(" #n ")" ::: "memory")
; #define PG8_BAR __builtin_amdgcn_s_barrier()
; #define PG8_SCHED __builtin_amdgcn_sched_barrier(0)
; template <class Epi>
; __device__ __forceinline__ void gemm_phase(LAS unsigned char* lds, const Gemm g, const Sched& S, const Epi& E) {
;     ...
;             const bool last = (t == nt - 2);
;             const char* a1 = cA + (size_t)(t + 1) * kstep;
;             const char* a2 = last ? nA : cA + (size_t)(t + 2) * kstep; const char* b2 = last ? nB : cB + (size_t)(t + 2) * kstep;
;             const char* a3 = a2 + kstep; const char* b3 = b2 + kstep;
;             PG8_LDB(B0, 0, 0); PG8_LDB(B1, 0, 1); PG8_SCHED; PG8_LDA(At, 0, 0); PG8_STAGE(PG8_SA(1, 1), a1 + hstepA, voffA);
;             PG8_WAIT_V(8); PG8_WAIT_L(0); PG8_BAR; PG8_MMA(0, 0, At, B0); PG8_MMA(0, 1, At, B1); PG8_BAR; PG8_SCHED;
;             PG8_LDA(At, 0, 1); PG8_STAGE(PG8_SB(0, 0), b2, voffB); PG8_STAGE(PG8_SB(0, 1), b2 + hstepB, voffB); PG8_STAGE(PG8_SA(0, 0), a2, voffA);
;             PG8_WAIT_V(8); PG8_WAIT_L(0); PG8_BAR; PG8_MMA(1, 0, At, B0); PG8_MMA(1, 1, At, B1); PG8_BAR; PG8_SCHED;
.LBB0_205:
	ds_read_b128 v[136:139], v145
	ds_read_b128 v[148:151], v145 offset:1024
	ds_read_b128 v[152:155], v145 offset:2048
	ds_read_b128 v[156:159], v145 offset:3072
	ds_read_b128 v[160:163], v146
	ds_read_b128 v[164:167], v146 offset:1024
	ds_read_b128 v[168:171], v146 offset:2048
	ds_read_b128 v[172:175], v146 offset:3072
	s_add_u32 s44, s40, 0xfffc0080
	s_addc_u32 s45, s41, -1
	s_cmp_eq_u32 s66, 12
	s_cselect_b32 s47, s15, s45
	s_cselect_b32 s46, s27, s44
	s_cselect_b32 s45, s21, s65
	s_cselect_b32 s44, s63, s64
	v_lshl_add_u64 v[140:141], s[40:41], 0, v[132:133]
	s_add_i32 m0, s29, 0xc000
	ds_read_b128 v[176:179], v147
	ds_read_b128 v[180:183], v147 offset:1024
	ds_read_b128 v[184:187], v147 offset:2048
	ds_read_b128 v[188:191], v147 offset:3072
	ds_read_b128 v[192:195], v147 offset:4096
	ds_read_b128 v[196:199], v147 offset:5120
	ds_read_b128 v[204:207], v147 offset:6144
	ds_read_b128 v[208:211], v147 offset:7168
	global_load_lds_dwordx4 v[140:141], off
	v_lshl_add_u64 v[140:141], s[40:41], 0, v[134:135]
	s_add_i32 m0, s29, 0xe000
	s_nop 0
	global_load_lds_dwordx4 v[140:141], off
	s_waitcnt vmcnt(8)
	s_waitcnt lgkmcnt(0)
	s_barrier
	s_setprio 1
	v_mfma_f32_16x16x32_bf16 v[124:127], v[136:139], v[176:179], v[124:127]
	v_mfma_f32_16x16x32_bf16 v[120:123], v[152:155], v[176:179], v[120:123]
	v_mfma_f32_16x16x32_bf16 v[108:111], v[136:139], v[184:187], v[108:111]
	v_mfma_f32_16x16x32_bf16 v[104:107], v[152:155], v[184:187], v[104:107]
	v_mfma_f32_16x16x32_bf16 v[92:95], v[136:139], v[192:195], v[92:95]
	v_mfma_f32_16x16x32_bf16 v[88:91], v[152:155], v[192:195], v[88:91]
	v_mfma_f32_16x16x32_bf16 v[76:79], v[136:139], v[204:207], v[76:79]
	v_mfma_f32_16x16x32_bf16 v[72:75], v[152:155], v[204:207], v[72:75]
	v_mfma_f32_16x16x32_bf16 v[124:127], v[148:151], v[180:183], v[124:127]
	v_mfma_f32_16x16x32_bf16 v[120:123], v[156:159], v[180:183], v[120:123]
	v_mfma_f32_16x16x32_bf16 v[108:111], v[148:151], v[188:191], v[108:111]
	v_mfma_f32_16x16x32_bf16 v[104:107], v[156:159], v[188:191], v[104:107]
	v_mfma_f32_16x16x32_bf16 v[92:95], v[148:151], v[196:199], v[92:95]
	v_mfma_f32_16x16x32_bf16 v[88:91], v[156:159], v[196:199], v[88:91]
	v_mfma_f32_16x16x32_bf16 v[76:79], v[148:151], v[208:211], v[76:79]
	v_mfma_f32_16x16x32_bf16 v[72:75], v[156:159], v[208:211], v[72:75]
	v_mfma_f32_16x16x32_bf16 v[116:119], v[160:163], v[176:179], v[116:119]
	v_mfma_f32_16x16x32_bf16 v[112:115], v[168:171], v[176:179], v[112:115]
	v_mfma_f32_16x16x32_bf16 v[100:103], v[160:163], v[184:187], v[100:103]
	v_mfma_f32_16x16x32_bf16 v[96:99], v[168:171], v[184:187], v[96:99]
	v_mfma_f32_16x16x32_bf16 v[84:87], v[160:163], v[192:195], v[84:87]
	v_mfma_f32_16x16x32_bf16 v[80:83], v[168:171], v[192:195], v[80:83]
	v_mfma_f32_16x16x32_bf16 v[68:71], v[160:163], v[204:207], v[68:71]
	v_mfma_f32_16x16x32_bf16 v[64:67], v[168:171], v[204:207], v[64:67]
	v_mfma_f32_16x16x32_bf16 v[116:119], v[164:167], v[180:183], v[116:119]
	v_mfma_f32_16x16x32_bf16 v[112:115], v[172:175], v[180:183], v[112:115]
	v_mfma_f32_16x16x32_bf16 v[100:103], v[164:167], v[188:191], v[100:103]
	v_mfma_f32_16x16x32_bf16 v[96:99], v[172:175], v[188:191], v[96:99]
	v_mfma_f32_16x16x32_bf16 v[84:87], v[164:167], v[196:199], v[84:87]
	v_mfma_f32_16x16x32_bf16 v[80:83], v[172:175], v[196:199], v[80:83]
	v_mfma_f32_16x16x32_bf16 v[68:71], v[164:167], v[208:211], v[68:71]
	v_mfma_f32_16x16x32_bf16 v[64:67], v[172:175], v[208:211], v[64:67]
	s_setprio 0
	s_barrier
	s_add_i32 s67, s61, s52
	v_lshl_add_u64 v[140:141], s[44:45], 0, v[128:129]
	s_mov_b32 m0, s67
	ds_read_b128 v[176:179], v147 offset:16384
	ds_read_b128 v[180:183], v147 offset:17408
	ds_read_b128 v[184:187], v147 offset:18432
	ds_read_b128 v[188:191], v147 offset:19456
	ds_read_b128 v[192:195], v147 offset:20480
	ds_read_b128 v[196:199], v147 offset:21504
	ds_read_b128 v[204:207], v147 offset:22528
	ds_read_b128 v[208:211], v147 offset:23552
	global_load_lds_dwordx4 v[140:141], off
	s_add_i32 m0, s67, 0x2000
	s_add_u32 s78, s44, 0x40000
	v_lshl_add_u64 v[200:201], s[44:45], 0, v[130:131]
	s_addc_u32 s79, s45, 0
	s_add_i32 s67, s62, s52
	global_load_lds_dwordx4 v[200:201], off
	v_lshl_add_u64 v[212:213], s[78:79], 0, v[128:129]
	s_mov_b32 m0, s67
	v_lshl_add_u64 v[214:215], s[46:47], 0, v[130:131]
	global_load_lds_dwordx4 v[212:213], off
	v_lshl_add_u64 v[212:213], s[78:79], 0, v[130:131]
	s_add_i32 m0, s67, 0x2000
	s_nop 0
	global_load_lds_dwordx4 v[212:213], off
	v_lshl_add_u64 v[212:213], s[46:47], 0, v[128:129]
	s_mov_b32 m0, s29
	s_nop 0
	global_load_lds_dwordx4 v[212:213], off
	s_mov_b32 m0, s55
	s_nop 0
	global_load_lds_dwordx4 v[214:215], off
	s_waitcnt vmcnt(8)
	s_waitcnt lgkmcnt(0)
	s_barrier
; #define PG8_STAGE(bufoff, gbase, voff) do { _Pragma("unroll") for (int _i = 0; _i < 2; ++_i) \
;         __builtin_amdgcn_global_load_lds((const unsigned*)((const char*)(gbase) + (voff)[_i]), (LAS unsigned*)(lds + (bufoff) + ldsw + _i * 8192), 16, 0, 0); } while (0)
; #define PG8_LDA(dst, b, h) do { _Pragma("unroll") for (int m = 0; m < 4; ++m) _Pragma("unroll") for (int k = 0; k < 2; ++k) dst[m][k] = *(const LAS bf16x8*)(lds + PG8_SA(b, h) + aoff + m * 2048 + k * 1024); } while (0)
; #define PG8_LDB(dst, b, h) do { _Pragma("unroll") for (int n = 0; n < 2; ++n) _Pragma("unroll") for (int k = 0; k < 2; ++k) dst[n][k] = *(const LAS bf16x8*)(lds + PG8_SB(b, h) + boff + n * 2048 + k * 1024); } while (0)
; #define PG8_MMA(ai, bj, At, Bt) do { __builtin_amdgcn_s_setprio(1); _Pragma("unroll") for (int m = 0; m < 4; ++m) _Pragma("unroll") for (int n = 0; n < 2; ++n) _Pragma("unroll") for (int k = 0; k < 2; ++k) \
;         acc[ai][bj][m][n] = __builtin_amdgcn_mfma_f32_16x16x32_bf16(Bt[n][k], At[m][k], acc[ai][bj][m][n], 0, 0, 0); __builtin_amdgcn_s_setprio(0); } while (0)
; #define PG8_WAIT_V(n) asm volatile("s_waitcnt vmcnt(" #n ")" ::: "memory")
; #define PG8_WAIT_L(n) asm volatile("s_waitcnt lgkmcnt(" #n ")" ::: "memory")
; #define PG8_BAR __builtin_amdgcn_s_barrier()
; #define PG8_SCHED __builtin_amdgcn_sched_barrier(0)
; template <class Epi>
; __device__ __forceinline__ void gemm_phase(LAS unsigned char* lds, const Gemm g, const Sched& S, const Epi& E) {
;     ...
;             PG8_WAIT_V(8); PG8_WAIT_L(0); PG8_BAR; PG8_MMA(1, 0, At, B0); PG8_MMA(1, 1, At, B1); PG8_BAR; PG8_SCHED;
;             PG8_LDB(B0, 1, 0); PG8_LDB(B1, 1, 1); PG8_SCHED; PG8_LDA(At, 1, 0); PG8_STAGE(PG8_SA(0, 1), a2 + hstepA, voffA);
;             PG8_WAIT_V(8); PG8_WAIT_L(0); PG8_BAR; PG8_MMA(0, 0, At, B0); PG8_MMA(0, 1, At, B1); PG8_BAR; PG8_SCHED;
	s_setprio 1
	v_mfma_f32_16x16x32_bf16 v[60:63], v[136:139], v[176:179], v[60:63]
	v_mfma_f32_16x16x32_bf16 v[56:59], v[152:155], v[176:179], v[56:59]
	v_mfma_f32_16x16x32_bf16 v[44:47], v[136:139], v[184:187], v[44:47]
	v_mfma_f32_16x16x32_bf16 v[40:43], v[152:155], v[184:187], v[40:43]
	v_mfma_f32_16x16x32_bf16 v[28:31], v[136:139], v[192:195], v[28:31]
	v_mfma_f32_16x16x32_bf16 v[24:27], v[152:155], v[192:195], v[24:27]
	v_mfma_f32_16x16x32_bf16 v[12:15], v[136:139], v[204:207], v[12:15]
	v_mfma_f32_16x16x32_bf16 v[8:11], v[152:155], v[204:207], v[8:11]
	v_mfma_f32_16x16x32_bf16 v[60:63], v[148:151], v[180:183], v[60:63]
	v_mfma_f32_16x16x32_bf16 v[56:59], v[156:159], v[180:183], v[56:59]
	v_mfma_f32_16x16x32_bf16 v[44:47], v[148:151], v[188:191], v[44:47]
	v_mfma_f32_16x16x32_bf16 v[40:43], v[156:159], v[188:191], v[40:43]
	v_mfma_f32_16x16x32_bf16 v[28:31], v[148:151], v[196:199], v[28:31]
	v_mfma_f32_16x16x32_bf16 v[24:27], v[156:159], v[196:199], v[24:27]
	v_mfma_f32_16x16x32_bf16 v[12:15], v[148:151], v[208:211], v[12:15]
	v_mfma_f32_16x16x32_bf16 v[8:11], v[156:159], v[208:211], v[8:11]
	v_mfma_f32_16x16x32_bf16 v[52:55], v[160:163], v[176:179], v[52:55]
	v_mfma_f32_16x16x32_bf16 v[48:51], v[168:171], v[176:179], v[48:51]
	v_mfma_f32_16x16x32_bf16 v[36:39], v[160:163], v[184:187], v[36:39]
	v_mfma_f32_16x16x32_bf16 v[32:35], v[168:171], v[184:187], v[32:35]
	v_mfma_f32_16x16x32_bf16 v[20:23], v[160:163], v[192:195], v[20:23]
	v_mfma_f32_16x16x32_bf16 v[16:19], v[168:171], v[192:195], v[16:19]
	v_mfma_f32_16x16x32_bf16 v[4:7], v[160:163], v[204:207], v[4:7]
	v_mfma_f32_16x16x32_bf16 v[0:3], v[168:171], v[204:207], v[0:3]
	v_mfma_f32_16x16x32_bf16 v[52:55], v[164:167], v[180:183], v[52:55]
	v_mfma_f32_16x16x32_bf16 v[48:51], v[172:175], v[180:183], v[48:51]
	v_mfma_f32_16x16x32_bf16 v[36:39], v[164:167], v[188:191], v[36:39]
	v_mfma_f32_16x16x32_bf16 v[32:35], v[172:175], v[188:191], v[32:35]
	v_mfma_f32_16x16x32_bf16 v[20:23], v[164:167], v[196:199], v[20:23]
	v_mfma_f32_16x16x32_bf16 v[16:19], v[172:175], v[196:199], v[16:19]
	v_mfma_f32_16x16x32_bf16 v[4:7], v[164:167], v[208:211], v[4:7]
	v_mfma_f32_16x16x32_bf16 v[0:3], v[172:175], v[208:211], v[0:3]
	s_setprio 0
	s_barrier
	s_add_i32 s67, 0, 0x18000
	s_add_i32 s78, 0, 0x1c000
	v_add_u32_e32 v156, s67, v143
	v_add_u32_e32 v172, s78, v143
	ds_read_b128 v[136:139], v156
	ds_read_b128 v[148:151], v156 offset:1024
	ds_read_b128 v[152:155], v156 offset:2048
	ds_read_b128 v[156:159], v156 offset:3072
	ds_read_b128 v[160:163], v172
	ds_read_b128 v[164:167], v172 offset:1024
	ds_read_b128 v[168:171], v172 offset:2048
	ds_read_b128 v[172:175], v172 offset:3072
	s_add_u32 s46, s46, 0x40000
	s_addc_u32 s47, s47, 0
	s_mov_b32 m0, s56
	v_lshl_add_u64 v[216:217], s[46:47], 0, v[128:129]
	ds_read_b128 v[176:179], v147 offset:32768
	ds_read_b128 v[180:183], v147 offset:33792
	ds_read_b128 v[184:187], v147 offset:34816
	ds_read_b128 v[188:191], v147 offset:35840
	ds_read_b128 v[192:195], v147 offset:36864
	ds_read_b128 v[196:199], v147 offset:37888
	ds_read_b128 v[204:207], v147 offset:38912
	ds_read_b128 v[208:211], v147 offset:39936
	global_load_lds_dwordx4 v[216:217], off
	v_lshl_add_u64 v[216:217], s[46:47], 0, v[130:131]
	s_mov_b32 m0, s57
	s_nop 0
	global_load_lds_dwordx4 v[216:217], off
	s_waitcnt vmcnt(8)
	s_waitcnt lgkmcnt(0)
	s_barrier
	s_setprio 1
	v_mfma_f32_16x16x32_bf16 v[124:127], v[136:139], v[176:179], v[124:127]
	v_mfma_f32_16x16x32_bf16 v[120:123], v[152:155], v[176:179], v[120:123]
	v_mfma_f32_16x16x32_bf16 v[108:111], v[136:139], v[184:187], v[108:111]
	v_mfma_f32_16x16x32_bf16 v[104:107], v[152:155], v[184:187], v[104:107]
	v_mfma_f32_16x16x32_bf16 v[92:95], v[136:139], v[192:195], v[92:95]
	v_mfma_f32_16x16x32_bf16 v[88:91], v[152:155], v[192:195], v[88:91]
	v_mfma_f32_16x16x32_bf16 v[76:79], v[136:139], v[204:207], v[76:79]
	v_mfma_f32_16x16x32_bf16 v[72:75], v[152:155], v[204:207], v[72:75]
	v_mfma_f32_16x16x32_bf16 v[124:127], v[148:151], v[180:183], v[124:127]
	v_mfma_f32_16x16x32_bf16 v[120:123], v[156:159], v[180:183], v[120:123]
	v_mfma_f32_16x16x32_bf16 v[108:111], v[148:151], v[188:191], v[108:111]
	v_mfma_f32_16x16x32_bf16 v[104:107], v[156:159], v[188:191], v[104:107]
	v_mfma_f32_16x16x32_bf16 v[92:95], v[148:151], v[196:199], v[92:95]
	v_mfma_f32_16x16x32_bf16 v[88:91], v[156:159], v[196:199], v[88:91]
	v_mfma_f32_16x16x32_bf16 v[76:79], v[148:151], v[208:211], v[76:79]
	v_mfma_f32_16x16x32_bf16 v[72:75], v[156:159], v[208:211], v[72:75]
	v_mfma_f32_16x16x32_bf16 v[116:119], v[160:163], v[176:179], v[116:119]
	v_mfma_f32_16x16x32_bf16 v[112:115], v[168:171], v[176:179], v[112:115]
	v_mfma_f32_16x16x32_bf16 v[100:103], v[160:163], v[184:187], v[100:103]
	v_mfma_f32_16x16x32_bf16 v[96:99], v[168:171], v[184:187], v[96:99]
	v_mfma_f32_16x16x32_bf16 v[84:87], v[160:163], v[192:195], v[84:87]
	v_mfma_f32_16x16x32_bf16 v[80:83], v[168:171], v[192:195], v[80:83]
	v_mfma_f32_16x16x32_bf16 v[68:71], v[160:163], v[204:207], v[68:71]
	v_mfma_f32_16x16x32_bf16 v[64:67], v[168:171], v[204:207], v[64:67]
	v_mfma_f32_16x16x32_bf16 v[116:119], v[164:167], v[180:183], v[116:119]
	v_mfma_f32_16x16x32_bf16 v[112:115], v[172:175], v[180:183], v[112:115]
	v_mfma_f32_16x16x32_bf16 v[100:103], v[164:167], v[188:191], v[100:103]
	v_mfma_f32_16x16x32_bf16 v[96:99], v[172:175], v[188:191], v[96:99]
	v_mfma_f32_16x16x32_bf16 v[84:87], v[164:167], v[196:199], v[84:87]
	v_mfma_f32_16x16x32_bf16 v[80:83], v[172:175], v[196:199], v[80:83]
	v_mfma_f32_16x16x32_bf16 v[68:71], v[164:167], v[208:211], v[68:71]
	v_mfma_f32_16x16x32_bf16 v[64:67], v[172:175], v[208:211], v[64:67]
	s_setprio 0
	s_barrier
; #define PG8_STAGE(bufoff, gbase, voff) do { _Pragma("unroll") for (int _i = 0; _i < 2; ++_i) \
;         __builtin_amdgcn_global_load_lds((const unsigned*)((const char*)(gbase) + (voff)[_i]), (LAS unsigned*)(lds + (bufoff) + ldsw + _i * 8192), 16, 0, 0); } while (0)
; #define PG8_LDA(dst, b, h) do { _Pragma("unroll") for (int m = 0; m < 4; ++m) _Pragma("unroll") for (int k = 0; k < 2; ++k) dst[m][k] = *(const LAS bf16x8*)(lds + PG8_SA(b, h) + aoff + m * 2048 + k * 1024); } while (0)
; #define PG8_MMA(ai, bj, At, Bt) do { __builtin_amdgcn_s_setprio(1); _Pragma("unroll") for (int m = 0; m < 4; ++m) _Pragma("unroll") for (int n = 0; n < 2; ++n) _Pragma("unroll") for (int k = 0; k < 2; ++k) \
;         acc[ai][bj][m][n] = __builtin_amdgcn_mfma_f32_16x16x32_bf16(Bt[n][k], At[m][k], acc[ai][bj][m][n], 0, 0, 0); __builtin_amdgcn_s_setprio(0); } while (0)
; #define PG8_WAIT_V(n) asm volatile("s_waitcnt vmcnt(" #n ")" ::: "memory")
; #define PG8_WAIT_L(n) asm volatile("s_waitcnt lgkmcnt(" #n ")" ::: "memory")
; #define PG8_BAR __builtin_amdgcn_s_barrier()
; #define PG8_SCHED __builtin_amdgcn_sched_barrier(0)
; template <class Epi>
; __device__ __forceinline__ void gemm_phase(LAS unsigned char* lds, const Gemm g, const Sched& S, const Epi& E) {
;     ...
;             PG8_LDA(At, 1, 1); PG8_STAGE(PG8_SB(1, 0), b3, voffB); PG8_STAGE(PG8_SB(1, 1), b3 + hstepB, voffB); PG8_STAGE(PG8_SA(1, 0), a3, voffA);
;             PG8_WAIT_V(8); PG8_WAIT_L(0); PG8_BAR; PG8_MMA(1, 0, At, B0); PG8_MMA(1, 1, At, B1); PG8_BAR; PG8_SCHED;
;         }
;         if (wr == 0) PG8_BAR;
	s_add_i32 s46, s67, s52
	v_lshl_add_u64 v[140:141], v[140:141], 0, s[4:5]
	s_mov_b32 m0, s46
	ds_read_b128 v[176:179], v147 offset:49152
	ds_read_b128 v[180:183], v147 offset:50176
	ds_read_b128 v[184:187], v147 offset:51200
	ds_read_b128 v[188:191], v147 offset:52224
	ds_read_b128 v[192:195], v147 offset:53248
	ds_read_b128 v[196:199], v147 offset:54272
	ds_read_b128 v[204:207], v147 offset:55296
	ds_read_b128 v[208:211], v147 offset:56320
	global_load_lds_dwordx4 v[140:141], off
	s_add_i32 m0, s46, 0x2000
	s_add_u32 s44, s44, 0x40080
	v_lshl_add_u64 v[140:141], v[200:201], 0, s[4:5]
	s_addc_u32 s45, s45, 0
	s_add_i32 s46, s78, s52
	global_load_lds_dwordx4 v[140:141], off
	v_lshl_add_u64 v[140:141], s[44:45], 0, v[128:129]
	s_mov_b32 m0, s46
	s_nop 0
	global_load_lds_dwordx4 v[140:141], off
	v_lshl_add_u64 v[140:141], s[44:45], 0, v[130:131]
	s_add_i32 m0, s46, 0x2000
	s_nop 0
	global_load_lds_dwordx4 v[140:141], off
	v_lshl_add_u64 v[140:141], v[212:213], 0, s[4:5]
	s_mov_b32 m0, s59
	s_nop 0
	global_load_lds_dwordx4 v[140:141], off
	v_lshl_add_u64 v[140:141], v[214:215], 0, s[4:5]
	s_mov_b32 m0, s60
	s_nop 0
	global_load_lds_dwordx4 v[140:141], off
	s_waitcnt vmcnt(8)
	s_waitcnt lgkmcnt(0)
	s_barrier
	s_setprio 1
	v_mfma_f32_16x16x32_bf16 v[60:63], v[136:139], v[176:179], v[60:63]
	v_mfma_f32_16x16x32_bf16 v[56:59], v[152:155], v[176:179], v[56:59]
	v_mfma_f32_16x16x32_bf16 v[44:47], v[136:139], v[184:187], v[44:47]
	v_mfma_f32_16x16x32_bf16 v[40:43], v[152:155], v[184:187], v[40:43]
	v_mfma_f32_16x16x32_bf16 v[28:31], v[136:139], v[192:195], v[28:31]
	v_mfma_f32_16x16x32_bf16 v[24:27], v[152:155], v[192:195], v[24:27]
	v_mfma_f32_16x16x32_bf16 v[12:15], v[136:139], v[204:207], v[12:15]
	v_mfma_f32_16x16x32_bf16 v[8:11], v[152:155], v[204:207], v[8:11]
	v_mfma_f32_16x16x32_bf16 v[60:63], v[148:151], v[180:183], v[60:63]
	v_mfma_f32_16x16x32_bf16 v[56:59], v[156:159], v[180:183], v[56:59]
	v_mfma_f32_16x16x32_bf16 v[44:47], v[148:151], v[188:191], v[44:47]
	v_mfma_f32_16x16x32_bf16 v[40:43], v[156:159], v[188:191], v[40:43]
	v_mfma_f32_16x16x32_bf16 v[28:31], v[148:151], v[196:199], v[28:31]
	v_mfma_f32_16x16x32_bf16 v[24:27], v[156:159], v[196:199], v[24:27]
	v_mfma_f32_16x16x32_bf16 v[12:15], v[148:151], v[208:211], v[12:15]
	v_mfma_f32_16x16x32_bf16 v[8:11], v[156:159], v[208:211], v[8:11]
	v_mfma_f32_16x16x32_bf16 v[52:55], v[160:163], v[176:179], v[52:55]
	v_mfma_f32_16x16x32_bf16 v[48:51], v[168:171], v[176:179], v[48:51]
	v_mfma_f32_16x16x32_bf16 v[36:39], v[160:163], v[184:187], v[36:39]
	v_mfma_f32_16x16x32_bf16 v[32:35], v[168:171], v[184:187], v[32:35]
	v_mfma_f32_16x16x32_bf16 v[20:23], v[160:163], v[192:195], v[20:23]
	v_mfma_f32_16x16x32_bf16 v[16:19], v[168:171], v[192:195], v[16:19]
	v_mfma_f32_16x16x32_bf16 v[4:7], v[160:163], v[204:207], v[4:7]
	v_mfma_f32_16x16x32_bf16 v[0:3], v[168:171], v[204:207], v[0:3]
	v_mfma_f32_16x16x32_bf16 v[52:55], v[164:167], v[180:183], v[52:55]
	v_mfma_f32_16x16x32_bf16 v[48:51], v[172:175], v[180:183], v[48:51]
	v_mfma_f32_16x16x32_bf16 v[36:39], v[164:167], v[188:191], v[36:39]
	v_mfma_f32_16x16x32_bf16 v[32:35], v[172:175], v[188:191], v[32:35]
	v_mfma_f32_16x16x32_bf16 v[20:23], v[164:167], v[196:199], v[20:23]
	v_mfma_f32_16x16x32_bf16 v[16:19], v[172:175], v[196:199], v[16:19]
	v_mfma_f32_16x16x32_bf16 v[4:7], v[164:167], v[208:211], v[4:7]
	v_mfma_f32_16x16x32_bf16 v[0:3], v[172:175], v[208:211], v[0:3]
	s_setprio 0
	s_barrier
	s_add_i32 s66, s66, 2
	s_add_u32 s40, s40, 0x100
	s_addc_u32 s41, s41, 0
	s_add_u32 s64, s64, 0x100
	s_addc_u32 s65, s65, 0
	s_cmp_gt_u32 s66, 13
	s_cbranch_scc0 .LBB0_205
	s_and_b64 vcc, exec, s[6:7]
	s_cbranch_vccz .LBB0_208
	s_barrier

; #define PG8_STAGE(bufoff, gbase, voff) do { _Pragma("unroll") for (int _i = 0; _i < 2; ++_i) \
;         __builtin_amdgcn_global_load_lds((const unsigned*)((const char*)(gbase) + (voff)[_i]), (LAS unsigned*)(lds + (bufoff) + ldsw + _i * 8192), 16, 0, 0); } while (0)
; #define PG8_LDA(dst, b, h) do { _Pragma("unroll") for (int m = 0; m < 4; ++m) _Pragma("unroll") for (int k = 0; k < 2; ++k) dst[m][k] = *(const LAS bf16x8*)(lds + PG8_SA(b, h) + aoff + m * 2048 + k * 1024); } while (0)
; #define PG8_LDB(dst, b, h) do { _Pragma("unroll") for (int n = 0; n < 2; ++n) _Pragma("unroll") for (int k = 0; k < 2; ++k) dst[n][k] = *(const LAS bf16x8*)(lds + PG8_SB(b, h) + boff + n * 2048 + k * 1024); } while (0)
; #define PG8_MMA(ai, bj, At, Bt) do { __builtin_amdgcn_s_setprio(1); _Pragma("unroll") for (int m = 0; m < 4; ++m) _Pragma("unroll") for (int n = 0; n < 2; ++n) _Pragma("unroll") for (int k = 0; k < 2; ++k) \
;         acc[ai][bj][m][n] = __builtin_amdgcn_mfma_f32_16x16x32_bf16(Bt[n][k], At[m][k], acc[ai][bj][m][n], 0, 0, 0); __builtin_amdgcn_s_setprio(0); } while (0)
; #define PG8_WAIT_V(n) asm volatile("s_waitcnt vmcnt(" #n ")" ::: "memory")
; #define PG8_WAIT_L(n) asm volatile("s_waitcnt lgkmcnt(" #n ")" ::: "memory")
; #define PG8_BAR __builtin_amdgcn_s_barrier()
; #define PG8_SCHED __builtin_amdgcn_sched_barrier(0)
; template <class Epi>
; __device__ __forceinline__ void gemm_phase(LAS unsigned char* lds, const Gemm g, const Sched& S, const Epi& E) {
;     ...
;             const char* a1 = cA + (size_t)(t + 1) * kstep;
;             const char* a2 = last ? nA : cA + (size_t)(t + 2) * kstep; const char* b2 = last ? nB : cB + (size_t)(t + 2) * kstep;
;             const char* a3 = a2 + kstep; const char* b3 = b2 + kstep;
;             PG8_LDB(B0, 0, 0); PG8_LDB(B1, 0, 1); PG8_SCHED; PG8_LDA(At, 0, 0); PG8_STAGE(PG8_SA(1, 1), a1 + hstepA, voffA);
;             PG8_WAIT_V(8); PG8_WAIT_L(0); PG8_BAR; PG8_MMA(0, 0, At, B0); PG8_MMA(0, 1, At, B1); PG8_BAR; PG8_SCHED;
;             PG8_LDA(At, 0, 1); PG8_STAGE(PG8_SB(0, 0), b2, voffB); PG8_STAGE(PG8_SB(0, 1), b2 + hstepB, voffB); PG8_STAGE(PG8_SA(0, 0), a2, voffA);
;             PG8_WAIT_V(8); PG8_WAIT_L(0); PG8_BAR; PG8_MMA(1, 0, At, B0); PG8_MMA(1, 1, At, B1); PG8_BAR; PG8_SCHED;
.LBB0_293:
	ds_read_b128 v[146:149], v143
	ds_read_b128 v[150:153], v143 offset:1024
	ds_read_b128 v[154:157], v143 offset:2048
	ds_read_b128 v[158:161], v143 offset:3072
	ds_read_b128 v[162:165], v144
	ds_read_b128 v[166:169], v144 offset:1024
	ds_read_b128 v[170:173], v144 offset:2048
	ds_read_b128 v[174:177], v144 offset:3072
	s_add_u32 s40, s28, 0xfffc0080
	s_addc_u32 s41, s29, -1
	s_cmp_eq_u32 s66, 12
	s_cselect_b32 s45, s23, s41
	s_cselect_b32 s44, s62, s40
	s_cselect_b32 s41, s15, s65
	s_cselect_b32 s40, s63, s64
	v_lshl_add_u64 v[212:213], s[28:29], 0, v[136:137]
	s_add_i32 m0, s21, 0xc000
	ds_read_b128 v[178:181], v145
	ds_read_b128 v[182:185], v145 offset:1024
	ds_read_b128 v[186:189], v145 offset:2048
	ds_read_b128 v[190:193], v145 offset:3072
	ds_read_b128 v[194:197], v145 offset:4096
	ds_read_b128 v[198:201], v145 offset:5120
	ds_read_b128 v[204:207], v145 offset:6144
	ds_read_b128 v[208:211], v145 offset:7168
	global_load_lds_dwordx4 v[212:213], off
	v_lshl_add_u64 v[212:213], s[28:29], 0, v[138:139]
	s_add_i32 m0, s21, 0xe000
	s_nop 0
	global_load_lds_dwordx4 v[212:213], off
	s_waitcnt vmcnt(8)
	s_waitcnt lgkmcnt(0)
	s_barrier
	s_setprio 1
	v_mfma_f32_16x16x32_bf16 v[124:127], v[146:149], v[178:181], v[124:127]
	v_mfma_f32_16x16x32_bf16 v[120:123], v[154:157], v[178:181], v[120:123]
	v_mfma_f32_16x16x32_bf16 v[116:119], v[146:149], v[186:189], v[116:119]
	v_mfma_f32_16x16x32_bf16 v[112:115], v[154:157], v[186:189], v[112:115]
	v_mfma_f32_16x16x32_bf16 v[100:103], v[146:149], v[194:197], v[100:103]
	v_mfma_f32_16x16x32_bf16 v[96:99], v[154:157], v[194:197], v[96:99]
	v_mfma_f32_16x16x32_bf16 v[84:87], v[146:149], v[204:207], v[84:87]
	v_mfma_f32_16x16x32_bf16 v[80:83], v[154:157], v[204:207], v[80:83]
	v_mfma_f32_16x16x32_bf16 v[124:127], v[150:153], v[182:185], v[124:127]
	v_mfma_f32_16x16x32_bf16 v[120:123], v[158:161], v[182:185], v[120:123]
	v_mfma_f32_16x16x32_bf16 v[116:119], v[150:153], v[190:193], v[116:119]
	v_mfma_f32_16x16x32_bf16 v[112:115], v[158:161], v[190:193], v[112:115]
	v_mfma_f32_16x16x32_bf16 v[100:103], v[150:153], v[198:201], v[100:103]
	v_mfma_f32_16x16x32_bf16 v[96:99], v[158:161], v[198:201], v[96:99]
	v_mfma_f32_16x16x32_bf16 v[84:87], v[150:153], v[208:211], v[84:87]
	v_mfma_f32_16x16x32_bf16 v[80:83], v[158:161], v[208:211], v[80:83]
	v_mfma_f32_16x16x32_bf16 v[108:111], v[162:165], v[178:181], v[108:111]
	v_mfma_f32_16x16x32_bf16 v[104:107], v[170:173], v[178:181], v[104:107]
	v_mfma_f32_16x16x32_bf16 v[92:95], v[162:165], v[186:189], v[92:95]
	v_mfma_f32_16x16x32_bf16 v[88:91], v[170:173], v[186:189], v[88:91]
	v_mfma_f32_16x16x32_bf16 v[76:79], v[162:165], v[194:197], v[76:79]
	v_mfma_f32_16x16x32_bf16 v[72:75], v[170:173], v[194:197], v[72:75]
	v_mfma_f32_16x16x32_bf16 v[68:71], v[162:165], v[204:207], v[68:71]
	v_mfma_f32_16x16x32_bf16 v[64:67], v[170:173], v[204:207], v[64:67]
	v_mfma_f32_16x16x32_bf16 v[108:111], v[166:169], v[182:185], v[108:111]
	v_mfma_f32_16x16x32_bf16 v[104:107], v[174:177], v[182:185], v[104:107]
	v_mfma_f32_16x16x32_bf16 v[92:95], v[166:169], v[190:193], v[92:95]
	v_mfma_f32_16x16x32_bf16 v[88:91], v[174:177], v[190:193], v[88:91]
	v_mfma_f32_16x16x32_bf16 v[76:79], v[166:169], v[198:201], v[76:79]
	v_mfma_f32_16x16x32_bf16 v[72:75], v[174:177], v[198:201], v[72:75]
	v_mfma_f32_16x16x32_bf16 v[68:71], v[166:169], v[208:211], v[68:71]
	v_mfma_f32_16x16x32_bf16 v[64:67], v[174:177], v[208:211], v[64:67]
	s_setprio 0
	s_barrier
	s_add_i32 s67, s59, s52
	v_lshl_add_u64 v[212:213], s[40:41], 0, v[130:131]
	s_mov_b32 m0, s67
	ds_read_b128 v[178:181], v145 offset:16384
	ds_read_b128 v[182:185], v145 offset:17408
	ds_read_b128 v[186:189], v145 offset:18432
	ds_read_b128 v[190:193], v145 offset:19456
	ds_read_b128 v[194:197], v145 offset:20480
	ds_read_b128 v[198:201], v145 offset:21504
	ds_read_b128 v[204:207], v145 offset:22528
	ds_read_b128 v[208:211], v145 offset:23552
	global_load_lds_dwordx4 v[212:213], off
	s_add_i32 m0, s67, 0x2000
	s_add_u32 s78, s40, 0x40000
	v_lshl_add_u64 v[214:215], s[40:41], 0, v[134:135]
	s_addc_u32 s79, s41, 0
	s_add_i32 s67, s60, s52
	global_load_lds_dwordx4 v[214:215], off
	v_lshl_add_u64 v[216:217], s[78:79], 0, v[130:131]
	s_mov_b32 m0, s67
	v_lshl_add_u64 v[218:219], s[44:45], 0, v[132:133]
	global_load_lds_dwordx4 v[216:217], off
	v_lshl_add_u64 v[216:217], s[78:79], 0, v[134:135]
	s_add_i32 m0, s67, 0x2000
	s_nop 0
	global_load_lds_dwordx4 v[216:217], off
	v_lshl_add_u64 v[216:217], s[44:45], 0, v[128:129]
	s_mov_b32 m0, s21
	s_nop 0
	global_load_lds_dwordx4 v[216:217], off
	s_mov_b32 m0, s53
	s_nop 0
	global_load_lds_dwordx4 v[218:219], off
	s_waitcnt vmcnt(8)
	s_waitcnt lgkmcnt(0)
	s_barrier
; #define PG8_STAGE(bufoff, gbase, voff) do { _Pragma("unroll") for (int _i = 0; _i < 2; ++_i) \
;         __builtin_amdgcn_global_load_lds((const unsigned*)((const char*)(gbase) + (voff)[_i]), (LAS unsigned*)(lds + (bufoff) + ldsw + _i * 8192), 16, 0, 0); } while (0)
; #define PG8_LDA(dst, b, h) do { _Pragma("unroll") for (int m = 0; m < 4; ++m) _Pragma("unroll") for (int k = 0; k < 2; ++k) dst[m][k] = *(const LAS bf16x8*)(lds + PG8_SA(b, h) + aoff + m * 2048 + k * 1024); } while (0)
; #define PG8_LDB(dst, b, h) do { _Pragma("unroll") for (int n = 0; n < 2; ++n) _Pragma("unroll") for (int k = 0; k < 2; ++k) dst[n][k] = *(const LAS bf16x8*)(lds + PG8_SB(b, h) + boff + n * 2048 + k * 1024); } while (0)
; #define PG8_MMA(ai, bj, At, Bt) do { __builtin_amdgcn_s_setprio(1); _Pragma("unroll") for (int m = 0; m < 4; ++m) _Pragma("unroll") for (int n = 0; n < 2; ++n) _Pragma("unroll") for (int k = 0; k < 2; ++k) \
;         acc[ai][bj][m][n] = __builtin_amdgcn_mfma_f32_16x16x32_bf16(Bt[n][k], At[m][k], acc[ai][bj][m][n], 0, 0, 0); __builtin_amdgcn_s_setprio(0); } while (0)
; #define PG8_WAIT_V(n) asm volatile("s_waitcnt vmcnt(" #n ")" ::: "memory")
; #define PG8_WAIT_L(n) asm volatile("s_waitcnt lgkmcnt(" #n ")" ::: "memory")
; #define PG8_BAR __builtin_amdgcn_s_barrier()
; #define PG8_SCHED __builtin_amdgcn_sched_barrier(0)
; template <class Epi>
; __device__ __forceinline__ void gemm_phase(LAS unsigned char* lds, const Gemm g, const Sched& S, const Epi& E) {
;     ...
;             PG8_WAIT_V(8); PG8_WAIT_L(0); PG8_BAR; PG8_MMA(1, 0, At, B0); PG8_MMA(1, 1, At, B1); PG8_BAR; PG8_SCHED;
;             PG8_LDB(B0, 1, 0); PG8_LDB(B1, 1, 1); PG8_SCHED; PG8_LDA(At, 1, 0); PG8_STAGE(PG8_SA(0, 1), a2 + hstepA, voffA);
;             PG8_WAIT_V(8); PG8_WAIT_L(0); PG8_BAR; PG8_MMA(0, 0, At, B0); PG8_MMA(0, 1, At, B1); PG8_BAR; PG8_SCHED;
	s_setprio 1
	v_mfma_f32_16x16x32_bf16 v[60:63], v[146:149], v[178:181], v[60:63]
	v_mfma_f32_16x16x32_bf16 v[56:59], v[154:157], v[178:181], v[56:59]
	v_mfma_f32_16x16x32_bf16 v[52:55], v[146:149], v[186:189], v[52:55]
	v_mfma_f32_16x16x32_bf16 v[48:51], v[154:157], v[186:189], v[48:51]
	v_mfma_f32_16x16x32_bf16 v[36:39], v[146:149], v[194:197], v[36:39]
	v_mfma_f32_16x16x32_bf16 v[32:35], v[154:157], v[194:197], v[32:35]
	v_mfma_f32_16x16x32_bf16 v[20:23], v[146:149], v[204:207], v[20:23]
	v_mfma_f32_16x16x32_bf16 v[16:19], v[154:157], v[204:207], v[16:19]
	v_mfma_f32_16x16x32_bf16 v[60:63], v[150:153], v[182:185], v[60:63]
	v_mfma_f32_16x16x32_bf16 v[56:59], v[158:161], v[182:185], v[56:59]
	v_mfma_f32_16x16x32_bf16 v[52:55], v[150:153], v[190:193], v[52:55]
	v_mfma_f32_16x16x32_bf16 v[48:51], v[158:161], v[190:193], v[48:51]
	v_mfma_f32_16x16x32_bf16 v[36:39], v[150:153], v[198:201], v[36:39]
	v_mfma_f32_16x16x32_bf16 v[32:35], v[158:161], v[198:201], v[32:35]
	v_mfma_f32_16x16x32_bf16 v[20:23], v[150:153], v[208:211], v[20:23]
	v_mfma_f32_16x16x32_bf16 v[16:19], v[158:161], v[208:211], v[16:19]
	v_mfma_f32_16x16x32_bf16 v[44:47], v[162:165], v[178:181], v[44:47]
	v_mfma_f32_16x16x32_bf16 v[40:43], v[170:173], v[178:181], v[40:43]
	v_mfma_f32_16x16x32_bf16 v[28:31], v[162:165], v[186:189], v[28:31]
	v_mfma_f32_16x16x32_bf16 v[24:27], v[170:173], v[186:189], v[24:27]
	v_mfma_f32_16x16x32_bf16 v[12:15], v[162:165], v[194:197], v[12:15]
	v_mfma_f32_16x16x32_bf16 v[8:11], v[170:173], v[194:197], v[8:11]
	v_mfma_f32_16x16x32_bf16 v[4:7], v[162:165], v[204:207], v[4:7]
	v_mfma_f32_16x16x32_bf16 v[0:3], v[170:173], v[204:207], v[0:3]
	v_mfma_f32_16x16x32_bf16 v[44:47], v[166:169], v[182:185], v[44:47]
	v_mfma_f32_16x16x32_bf16 v[40:43], v[174:177], v[182:185], v[40:43]
	v_mfma_f32_16x16x32_bf16 v[28:31], v[166:169], v[190:193], v[28:31]
	v_mfma_f32_16x16x32_bf16 v[24:27], v[174:177], v[190:193], v[24:27]
	v_mfma_f32_16x16x32_bf16 v[12:15], v[166:169], v[198:201], v[12:15]
	v_mfma_f32_16x16x32_bf16 v[8:11], v[174:177], v[198:201], v[8:11]
	v_mfma_f32_16x16x32_bf16 v[4:7], v[166:169], v[208:211], v[4:7]
	v_mfma_f32_16x16x32_bf16 v[0:3], v[174:177], v[208:211], v[0:3]
	s_setprio 0
	s_barrier
	s_add_i32 s67, 0, 0x18000
	s_add_i32 s78, 0, 0x1c000
	v_add_u32_e32 v158, s67, v141
	v_add_u32_e32 v174, s78, v141
	ds_read_b128 v[146:149], v158
	ds_read_b128 v[150:153], v158 offset:1024
	ds_read_b128 v[154:157], v158 offset:2048
	ds_read_b128 v[158:161], v158 offset:3072
	ds_read_b128 v[162:165], v174
	ds_read_b128 v[166:169], v174 offset:1024
	ds_read_b128 v[170:173], v174 offset:2048
	ds_read_b128 v[174:177], v174 offset:3072
	s_add_u32 s44, s44, 0x40000
	s_addc_u32 s45, s45, 0
	s_mov_b32 m0, s54
	v_lshl_add_u64 v[220:221], s[44:45], 0, v[128:129]
	ds_read_b128 v[178:181], v145 offset:32768
	ds_read_b128 v[182:185], v145 offset:33792
	ds_read_b128 v[186:189], v145 offset:34816
	ds_read_b128 v[190:193], v145 offset:35840
	ds_read_b128 v[194:197], v145 offset:36864
	ds_read_b128 v[198:201], v145 offset:37888
	ds_read_b128 v[204:207], v145 offset:38912
	ds_read_b128 v[208:211], v145 offset:39936
	global_load_lds_dwordx4 v[220:221], off
	v_lshl_add_u64 v[220:221], s[44:45], 0, v[132:133]
	s_mov_b32 m0, s55
	s_nop 0
	global_load_lds_dwordx4 v[220:221], off
	s_waitcnt vmcnt(8)
	s_waitcnt lgkmcnt(0)
	s_barrier
	s_setprio 1
	v_mfma_f32_16x16x32_bf16 v[124:127], v[146:149], v[178:181], v[124:127]
	v_mfma_f32_16x16x32_bf16 v[120:123], v[154:157], v[178:181], v[120:123]
	v_mfma_f32_16x16x32_bf16 v[116:119], v[146:149], v[186:189], v[116:119]
	v_mfma_f32_16x16x32_bf16 v[112:115], v[154:157], v[186:189], v[112:115]
	v_mfma_f32_16x16x32_bf16 v[100:103], v[146:149], v[194:197], v[100:103]
	v_mfma_f32_16x16x32_bf16 v[96:99], v[154:157], v[194:197], v[96:99]
	v_mfma_f32_16x16x32_bf16 v[84:87], v[146:149], v[204:207], v[84:87]
	v_mfma_f32_16x16x32_bf16 v[80:83], v[154:157], v[204:207], v[80:83]
	v_mfma_f32_16x16x32_bf16 v[124:127], v[150:153], v[182:185], v[124:127]
	v_mfma_f32_16x16x32_bf16 v[120:123], v[158:161], v[182:185], v[120:123]
	v_mfma_f32_16x16x32_bf16 v[116:119], v[150:153], v[190:193], v[116:119]
	v_mfma_f32_16x16x32_bf16 v[112:115], v[158:161], v[190:193], v[112:115]
	v_mfma_f32_16x16x32_bf16 v[100:103], v[150:153], v[198:201], v[100:103]
	v_mfma_f32_16x16x32_bf16 v[96:99], v[158:161], v[198:201], v[96:99]
	v_mfma_f32_16x16x32_bf16 v[84:87], v[150:153], v[208:211], v[84:87]
	v_mfma_f32_16x16x32_bf16 v[80:83], v[158:161], v[208:211], v[80:83]
	v_mfma_f32_16x16x32_bf16 v[108:111], v[162:165], v[178:181], v[108:111]
	v_mfma_f32_16x16x32_bf16 v[104:107], v[170:173], v[178:181], v[104:107]
	v_mfma_f32_16x16x32_bf16 v[92:95], v[162:165], v[186:189], v[92:95]
	v_mfma_f32_16x16x32_bf16 v[88:91], v[170:173], v[186:189], v[88:91]
	v_mfma_f32_16x16x32_bf16 v[76:79], v[162:165], v[194:197], v[76:79]
	v_mfma_f32_16x16x32_bf16 v[72:75], v[170:173], v[194:197], v[72:75]
	v_mfma_f32_16x16x32_bf16 v[68:71], v[162:165], v[204:207], v[68:71]
	v_mfma_f32_16x16x32_bf16 v[64:67], v[170:173], v[204:207], v[64:67]
	v_mfma_f32_16x16x32_bf16 v[108:111], v[166:169], v[182:185], v[108:111]
	v_mfma_f32_16x16x32_bf16 v[104:107], v[174:177], v[182:185], v[104:107]
	v_mfma_f32_16x16x32_bf16 v[92:95], v[166:169], v[190:193], v[92:95]
	v_mfma_f32_16x16x32_bf16 v[88:91], v[174:177], v[190:193], v[88:91]
	v_mfma_f32_16x16x32_bf16 v[76:79], v[166:169], v[198:201], v[76:79]
	v_mfma_f32_16x16x32_bf16 v[72:75], v[174:177], v[198:201], v[72:75]
	v_mfma_f32_16x16x32_bf16 v[68:71], v[166:169], v[208:211], v[68:71]
	v_mfma_f32_16x16x32_bf16 v[64:67], v[174:177], v[208:211], v[64:67]
	s_setprio 0
	s_barrier
; #define PG8_STAGE(bufoff, gbase, voff) do { _Pragma("unroll") for (int _i = 0; _i < 2; ++_i) \
;         __builtin_amdgcn_global_load_lds((const unsigned*)((const char*)(gbase) + (voff)[_i]), (LAS unsigned*)(lds + (bufoff) + ldsw + _i * 8192), 16, 0, 0); } while (0)
; #define PG8_LDA(dst, b, h) do { _Pragma("unroll") for (int m = 0; m < 4; ++m) _Pragma("unroll") for (int k = 0; k < 2; ++k) dst[m][k] = *(const LAS bf16x8*)(lds + PG8_SA(b, h) + aoff + m * 2048 + k * 1024); } while (0)
; #define PG8_MMA(ai, bj, At, Bt) do { __builtin_amdgcn_s_setprio(1); _Pragma("unroll") for (int m = 0; m < 4; ++m) _Pragma("unroll") for (int n = 0; n < 2; ++n) _Pragma("unroll") for (int k = 0; k < 2; ++k) \
;         acc[ai][bj][m][n] = __builtin_amdgcn_mfma_f32_16x16x32_bf16(Bt[n][k], At[m][k], acc[ai][bj][m][n], 0, 0, 0); __builtin_amdgcn_s_setprio(0); } while (0)
; #define PG8_WAIT_V(n) asm volatile("s_waitcnt vmcnt(" #n ")" ::: "memory")
; #define PG8_WAIT_L(n) asm volatile("s_waitcnt lgkmcnt(" #n ")" ::: "memory")
; #define PG8_BAR __builtin_amdgcn_s_barrier()
; #define PG8_SCHED __builtin_amdgcn_sched_barrier(0)
; template <class Epi>
; __device__ __forceinline__ void gemm_phase(LAS unsigned char* lds, const Gemm g, const Sched& S, const Epi& E) {
;     ...
;             PG8_LDA(At, 1, 1); PG8_STAGE(PG8_SB(1, 0), b3, voffB); PG8_STAGE(PG8_SB(1, 1), b3 + hstepB, voffB); PG8_STAGE(PG8_SA(1, 0), a3, voffA);
;             PG8_WAIT_V(8); PG8_WAIT_L(0); PG8_BAR; PG8_MMA(1, 0, At, B0); PG8_MMA(1, 1, At, B1); PG8_BAR; PG8_SCHED;
;         }
;         if (wr == 0) PG8_BAR;
	s_add_i32 s44, s67, s52
	v_lshl_add_u64 v[212:213], v[212:213], 0, s[4:5]
	s_mov_b32 m0, s44
	ds_read_b128 v[178:181], v145 offset:49152
	ds_read_b128 v[182:185], v145 offset:50176
	ds_read_b128 v[186:189], v145 offset:51200
	ds_read_b128 v[190:193], v145 offset:52224
	ds_read_b128 v[194:197], v145 offset:53248
	ds_read_b128 v[198:201], v145 offset:54272
	ds_read_b128 v[204:207], v145 offset:55296
	ds_read_b128 v[208:211], v145 offset:56320
	global_load_lds_dwordx4 v[212:213], off
	s_add_i32 m0, s44, 0x2000
	s_add_u32 s40, s40, 0x40080
	v_lshl_add_u64 v[212:213], v[214:215], 0, s[4:5]
	s_addc_u32 s41, s41, 0
	s_add_i32 s44, s78, s52
	global_load_lds_dwordx4 v[212:213], off
	v_lshl_add_u64 v[212:213], s[40:41], 0, v[130:131]
	s_mov_b32 m0, s44
	s_nop 0
	global_load_lds_dwordx4 v[212:213], off
	v_lshl_add_u64 v[212:213], s[40:41], 0, v[134:135]
	s_add_i32 m0, s44, 0x2000
	s_nop 0
	global_load_lds_dwordx4 v[212:213], off
	v_lshl_add_u64 v[212:213], v[216:217], 0, s[4:5]
	s_mov_b32 m0, s57
	s_nop 0
	global_load_lds_dwordx4 v[212:213], off
	v_lshl_add_u64 v[212:213], v[218:219], 0, s[4:5]
	s_mov_b32 m0, s58
	s_nop 0
	global_load_lds_dwordx4 v[212:213], off
	s_waitcnt vmcnt(8)
	s_waitcnt lgkmcnt(0)
	s_barrier
	s_setprio 1
	v_mfma_f32_16x16x32_bf16 v[60:63], v[146:149], v[178:181], v[60:63]
	v_mfma_f32_16x16x32_bf16 v[56:59], v[154:157], v[178:181], v[56:59]
	v_mfma_f32_16x16x32_bf16 v[52:55], v[146:149], v[186:189], v[52:55]
	v_mfma_f32_16x16x32_bf16 v[48:51], v[154:157], v[186:189], v[48:51]
	v_mfma_f32_16x16x32_bf16 v[36:39], v[146:149], v[194:197], v[36:39]
	v_mfma_f32_16x16x32_bf16 v[32:35], v[154:157], v[194:197], v[32:35]
	v_mfma_f32_16x16x32_bf16 v[20:23], v[146:149], v[204:207], v[20:23]
	v_mfma_f32_16x16x32_bf16 v[16:19], v[154:157], v[204:207], v[16:19]
	v_mfma_f32_16x16x32_bf16 v[60:63], v[150:153], v[182:185], v[60:63]
	v_mfma_f32_16x16x32_bf16 v[56:59], v[158:161], v[182:185], v[56:59]
	v_mfma_f32_16x16x32_bf16 v[52:55], v[150:153], v[190:193], v[52:55]
	v_mfma_f32_16x16x32_bf16 v[48:51], v[158:161], v[190:193], v[48:51]
	v_mfma_f32_16x16x32_bf16 v[36:39], v[150:153], v[198:201], v[36:39]
	v_mfma_f32_16x16x32_bf16 v[32:35], v[158:161], v[198:201], v[32:35]
	v_mfma_f32_16x16x32_bf16 v[20:23], v[150:153], v[208:211], v[20:23]
	v_mfma_f32_16x16x32_bf16 v[16:19], v[158:161], v[208:211], v[16:19]
	v_mfma_f32_16x16x32_bf16 v[44:47], v[162:165], v[178:181], v[44:47]
	v_mfma_f32_16x16x32_bf16 v[40:43], v[170:173], v[178:181], v[40:43]
	v_mfma_f32_16x16x32_bf16 v[28:31], v[162:165], v[186:189], v[28:31]
	v_mfma_f32_16x16x32_bf16 v[24:27], v[170:173], v[186:189], v[24:27]
	v_mfma_f32_16x16x32_bf16 v[12:15], v[162:165], v[194:197], v[12:15]
	v_mfma_f32_16x16x32_bf16 v[8:11], v[170:173], v[194:197], v[8:11]
	v_mfma_f32_16x16x32_bf16 v[4:7], v[162:165], v[204:207], v[4:7]
	v_mfma_f32_16x16x32_bf16 v[0:3], v[170:173], v[204:207], v[0:3]
	v_mfma_f32_16x16x32_bf16 v[44:47], v[166:169], v[182:185], v[44:47]
	v_mfma_f32_16x16x32_bf16 v[40:43], v[174:177], v[182:185], v[40:43]
	v_mfma_f32_16x16x32_bf16 v[28:31], v[166:169], v[190:193], v[28:31]
	v_mfma_f32_16x16x32_bf16 v[24:27], v[174:177], v[190:193], v[24:27]
	v_mfma_f32_16x16x32_bf16 v[12:15], v[166:169], v[198:201], v[12:15]
	v_mfma_f32_16x16x32_bf16 v[8:11], v[174:177], v[198:201], v[8:11]
	v_mfma_f32_16x16x32_bf16 v[4:7], v[166:169], v[208:211], v[4:7]
	v_mfma_f32_16x16x32_bf16 v[0:3], v[174:177], v[208:211], v[0:3]
	s_setprio 0
	s_barrier
	s_add_i32 s66, s66, 2
	s_add_u32 s28, s28, 0x100
	s_addc_u32 s29, s29, 0
	s_add_u32 s64, s64, 0x100
	s_addc_u32 s65, s65, 0
	s_cmp_gt_u32 s66, 13
	s_cbranch_scc0 .LBB0_293
	s_and_b64 vcc, exec, s[6:7]
	s_cbranch_vccz .LBB0_296
	s_barrier

; #define PG8_STAGE(bufoff, gbase, voff) do { _Pragma("unroll") for (int _i = 0; _i < 2; ++_i) \
;         __builtin_amdgcn_global_load_lds((const unsigned*)((const char*)(gbase) + (voff)[_i]), (LAS unsigned*)(lds + (bufoff) + ldsw + _i * 8192), 16, 0, 0); } while (0)
; #define PG8_LDA(dst, b, h) do { _Pragma("unroll") for (int m = 0; m < 4; ++m) _Pragma("unroll") for (int k = 0; k < 2; ++k) dst[m][k] = *(const LAS bf16x8*)(lds + PG8_SA(b, h) + aoff + m * 2048 + k * 1024); } while (0)
; #define PG8_LDB(dst, b, h) do { _Pragma("unroll") for (int n = 0; n < 2; ++n) _Pragma("unroll") for (int k = 0; k < 2; ++k) dst[n][k] = *(const LAS bf16x8*)(lds + PG8_SB(b, h) + boff + n * 2048 + k * 1024); } while (0)
; #define PG8_MMA(ai, bj, At, Bt) do { __builtin_amdgcn_s_setprio(1); _Pragma("unroll") for (int m = 0; m < 4; ++m) _Pragma("unroll") for (int n = 0; n < 2; ++n) _Pragma("unroll") for (int k = 0; k < 2; ++k) \
;         acc[ai][bj][m][n] = __builtin_amdgcn_mfma_f32_16x16x32_bf16(Bt[n][k], At[m][k], acc[ai][bj][m][n], 0, 0, 0); __builtin_amdgcn_s_setprio(0); } while (0)
; #define PG8_WAIT_V(n) asm volatile("s_waitcnt vmcnt(" #n ")" ::: "memory")
; #define PG8_WAIT_L(n) asm volatile("s_waitcnt lgkmcnt(" #n ")" ::: "memory")
; #define PG8_BAR __builtin_amdgcn_s_barrier()
; #define PG8_SCHED __builtin_amdgcn_sched_barrier(0)
; template <class Epi>
; __device__ __forceinline__ void gemm_phase(LAS unsigned char* lds, const Gemm g, const Sched& S, const Epi& E) {
;     ...
;             const char* a1 = cA + (size_t)(t + 1) * kstep;
;             const char* a2 = last ? nA : cA + (size_t)(t + 2) * kstep; const char* b2 = last ? nB : cB + (size_t)(t + 2) * kstep;
;             const char* a3 = a2 + kstep; const char* b3 = b2 + kstep;
;             PG8_LDB(B0, 0, 0); PG8_LDB(B1, 0, 1); PG8_SCHED; PG8_LDA(At, 0, 0); PG8_STAGE(PG8_SA(1, 1), a1 + hstepA, voffA);
;             PG8_WAIT_V(8); PG8_WAIT_L(0); PG8_BAR; PG8_MMA(0, 0, At, B0); PG8_MMA(0, 1, At, B1); PG8_BAR; PG8_SCHED;
;             PG8_LDA(At, 0, 1); PG8_STAGE(PG8_SB(0, 0), b2, voffB); PG8_STAGE(PG8_SB(0, 1), b2 + hstepB, voffB); PG8_STAGE(PG8_SA(0, 0), a2, voffA);
;             PG8_WAIT_V(8); PG8_WAIT_L(0); PG8_BAR; PG8_MMA(1, 0, At, B0); PG8_MMA(1, 1, At, B1); PG8_BAR; PG8_SCHED;
.LBB0_374:
	v_add_u32_e32 v158, s64, v144
	v_add_u32_e32 v174, s65, v144
	s_add_u32 s40, s26, s28
	ds_read_b128 v[146:149], v158
	ds_read_b128 v[150:153], v158 offset:1024
	ds_read_b128 v[154:157], v158 offset:2048
	ds_read_b128 v[158:161], v158 offset:3072
	ds_read_b128 v[162:165], v174
	ds_read_b128 v[166:169], v174 offset:1024
	ds_read_b128 v[170:173], v174 offset:2048
	ds_read_b128 v[174:177], v174 offset:3072
	s_addc_u32 s41, s27, s29
	s_add_u32 s40, s40, 0x100
	s_addc_u32 s41, s41, 0
	s_add_u32 s84, s87, s28
	s_addc_u32 s85, s88, s29
	s_cmpk_eq_i32 s28, 0x1500
	s_cselect_b32 s45, s23, s41
	s_cselect_b32 s44, s22, s40
	s_cselect_b32 s41, s25, s85
	s_cselect_b32 s40, s24, s84
	s_mov_b32 m0, s66
	v_lshl_add_u64 v[186:187], v[140:141], 0, s[28:29]
	ds_read_b128 v[178:181], v145
	ds_read_b128 v[182:185], v145 offset:1024
	ds_read_b128 v[192:195], v145 offset:2048
	ds_read_b128 v[196:199], v145 offset:3072
	ds_read_b128 v[204:207], v145 offset:4096
	ds_read_b128 v[208:211], v145 offset:5120
	ds_read_b128 v[212:215], v145 offset:6144
	ds_read_b128 v[216:219], v145 offset:7168
	global_load_lds_dwordx4 v[186:187], off
	v_lshl_add_u64 v[186:187], v[142:143], 0, s[28:29]
	s_mov_b32 m0, s67
	s_nop 0
	global_load_lds_dwordx4 v[186:187], off
	s_waitcnt vmcnt(8)
	s_waitcnt lgkmcnt(0)
	s_barrier
	s_setprio 1
	v_mfma_f32_16x16x32_bf16 v[124:127], v[146:149], v[178:181], v[124:127]
	v_mfma_f32_16x16x32_bf16 v[120:123], v[154:157], v[178:181], v[120:123]
	v_mfma_f32_16x16x32_bf16 v[108:111], v[146:149], v[192:195], v[108:111]
	v_mfma_f32_16x16x32_bf16 v[104:107], v[154:157], v[192:195], v[104:107]
	v_mfma_f32_16x16x32_bf16 v[92:95], v[146:149], v[204:207], v[92:95]
	v_mfma_f32_16x16x32_bf16 v[88:91], v[154:157], v[204:207], v[88:91]
	v_mfma_f32_16x16x32_bf16 v[76:79], v[146:149], v[212:215], v[76:79]
	v_mfma_f32_16x16x32_bf16 v[72:75], v[154:157], v[212:215], v[72:75]
	v_mfma_f32_16x16x32_bf16 v[124:127], v[150:153], v[182:185], v[124:127]
	v_mfma_f32_16x16x32_bf16 v[120:123], v[158:161], v[182:185], v[120:123]
	v_mfma_f32_16x16x32_bf16 v[108:111], v[150:153], v[196:199], v[108:111]
	v_mfma_f32_16x16x32_bf16 v[104:107], v[158:161], v[196:199], v[104:107]
	v_mfma_f32_16x16x32_bf16 v[92:95], v[150:153], v[208:211], v[92:95]
	v_mfma_f32_16x16x32_bf16 v[88:91], v[158:161], v[208:211], v[88:91]
	v_mfma_f32_16x16x32_bf16 v[76:79], v[150:153], v[216:219], v[76:79]
	v_mfma_f32_16x16x32_bf16 v[72:75], v[158:161], v[216:219], v[72:75]
	v_mfma_f32_16x16x32_bf16 v[116:119], v[162:165], v[178:181], v[116:119]
	v_mfma_f32_16x16x32_bf16 v[112:115], v[170:173], v[178:181], v[112:115]
	v_mfma_f32_16x16x32_bf16 v[100:103], v[162:165], v[192:195], v[100:103]
	v_mfma_f32_16x16x32_bf16 v[96:99], v[170:173], v[192:195], v[96:99]
	v_mfma_f32_16x16x32_bf16 v[84:87], v[162:165], v[204:207], v[84:87]
	v_mfma_f32_16x16x32_bf16 v[80:83], v[170:173], v[204:207], v[80:83]
	v_mfma_f32_16x16x32_bf16 v[68:71], v[162:165], v[212:215], v[68:71]
	v_mfma_f32_16x16x32_bf16 v[64:67], v[170:173], v[212:215], v[64:67]
	v_mfma_f32_16x16x32_bf16 v[116:119], v[166:169], v[182:185], v[116:119]
	v_mfma_f32_16x16x32_bf16 v[112:115], v[174:177], v[182:185], v[112:115]
	v_mfma_f32_16x16x32_bf16 v[100:103], v[166:169], v[196:199], v[100:103]
	v_mfma_f32_16x16x32_bf16 v[96:99], v[174:177], v[196:199], v[96:99]
	v_mfma_f32_16x16x32_bf16 v[84:87], v[166:169], v[208:211], v[84:87]
	v_mfma_f32_16x16x32_bf16 v[80:83], v[174:177], v[208:211], v[80:83]
	v_mfma_f32_16x16x32_bf16 v[68:71], v[166:169], v[216:219], v[68:71]
	v_mfma_f32_16x16x32_bf16 v[64:67], v[174:177], v[216:219], v[64:67]
	s_setprio 0
	s_barrier
	s_mov_b32 m0, s78
	v_lshl_add_u64 v[186:187], s[40:41], 0, v[130:131]
	ds_read_b128 v[178:181], v145 offset:16384
	ds_read_b128 v[182:185], v145 offset:17408
	ds_read_b128 v[192:195], v145 offset:18432
	ds_read_b128 v[196:199], v145 offset:19456
	ds_read_b128 v[204:207], v145 offset:20480
	ds_read_b128 v[208:211], v145 offset:21504
	ds_read_b128 v[212:215], v145 offset:22528
	ds_read_b128 v[216:219], v145 offset:23552
	global_load_lds_dwordx4 v[186:187], off
	s_add_i32 m0, s78, 0x2000
	s_add_u32 s84, s40, 0xb0000
	v_lshl_add_u64 v[200:201], s[40:41], 0, v[134:135]
	s_addc_u32 s85, s41, 0
	s_add_i32 s90, s65, s56
	global_load_lds_dwordx4 v[200:201], off
	v_lshl_add_u64 v[220:221], s[84:85], 0, v[130:131]
	s_mov_b32 m0, s90
	v_lshl_add_u64 v[222:223], s[44:45], 0, v[132:133]
	global_load_lds_dwordx4 v[220:221], off
	v_lshl_add_u64 v[220:221], s[84:85], 0, v[134:135]
	s_add_i32 m0, s90, 0x2000
	s_nop 0
	global_load_lds_dwordx4 v[220:221], off
	v_lshl_add_u64 v[220:221], s[44:45], 0, v[128:129]
	s_mov_b32 m0, s57
	s_nop 0
	global_load_lds_dwordx4 v[220:221], off
	s_mov_b32 m0, s58
	s_nop 0
	global_load_lds_dwordx4 v[222:223], off
	s_waitcnt vmcnt(8)
	s_waitcnt lgkmcnt(0)
	s_barrier
; #define PG8_STAGE(bufoff, gbase, voff) do { _Pragma("unroll") for (int _i = 0; _i < 2; ++_i) \
;         __builtin_amdgcn_global_load_lds((const unsigned*)((const char*)(gbase) + (voff)[_i]), (LAS unsigned*)(lds + (bufoff) + ldsw + _i * 8192), 16, 0, 0); } while (0)
; #define PG8_LDA(dst, b, h) do { _Pragma("unroll") for (int m = 0; m < 4; ++m) _Pragma("unroll") for (int k = 0; k < 2; ++k) dst[m][k] = *(const LAS bf16x8*)(lds + PG8_SA(b, h) + aoff + m * 2048 + k * 1024); } while (0)
; #define PG8_LDB(dst, b, h) do { _Pragma("unroll") for (int n = 0; n < 2; ++n) _Pragma("unroll") for (int k = 0; k < 2; ++k) dst[n][k] = *(const LAS bf16x8*)(lds + PG8_SB(b, h) + boff + n * 2048 + k * 1024); } while (0)
; #define PG8_MMA(ai, bj, At, Bt) do { __builtin_amdgcn_s_setprio(1); _Pragma("unroll") for (int m = 0; m < 4; ++m) _Pragma("unroll") for (int n = 0; n < 2; ++n) _Pragma("unroll") for (int k = 0; k < 2; ++k) \
;         acc[ai][bj][m][n] = __builtin_amdgcn_mfma_f32_16x16x32_bf16(Bt[n][k], At[m][k], acc[ai][bj][m][n], 0, 0, 0); __builtin_amdgcn_s_setprio(0); } while (0)
; #define PG8_WAIT_V(n) asm volatile("s_waitcnt vmcnt(" #n ")" ::: "memory")
; #define PG8_WAIT_L(n) asm volatile("s_waitcnt lgkmcnt(" #n ")" ::: "memory")
; #define PG8_BAR __builtin_amdgcn_s_barrier()
; #define PG8_SCHED __builtin_amdgcn_sched_barrier(0)
; template <class Epi>
; __device__ __forceinline__ void gemm_phase(LAS unsigned char* lds, const Gemm g, const Sched& S, const Epi& E) {
;     ...
;             PG8_WAIT_V(8); PG8_WAIT_L(0); PG8_BAR; PG8_MMA(1, 0, At, B0); PG8_MMA(1, 1, At, B1); PG8_BAR; PG8_SCHED;
;             PG8_LDB(B0, 1, 0); PG8_LDB(B1, 1, 1); PG8_SCHED; PG8_LDA(At, 1, 0); PG8_STAGE(PG8_SA(0, 1), a2 + hstepA, voffA);
;             PG8_WAIT_V(8); PG8_WAIT_L(0); PG8_BAR; PG8_MMA(0, 0, At, B0); PG8_MMA(0, 1, At, B1); PG8_BAR; PG8_SCHED;
	s_setprio 1
	v_mfma_f32_16x16x32_bf16 v[60:63], v[146:149], v[178:181], v[60:63]
	v_mfma_f32_16x16x32_bf16 v[56:59], v[154:157], v[178:181], v[56:59]
	v_mfma_f32_16x16x32_bf16 v[44:47], v[146:149], v[192:195], v[44:47]
	v_mfma_f32_16x16x32_bf16 v[40:43], v[154:157], v[192:195], v[40:43]
	v_mfma_f32_16x16x32_bf16 v[28:31], v[146:149], v[204:207], v[28:31]
	v_mfma_f32_16x16x32_bf16 v[24:27], v[154:157], v[204:207], v[24:27]
	v_mfma_f32_16x16x32_bf16 v[12:15], v[146:149], v[212:215], v[12:15]
	v_mfma_f32_16x16x32_bf16 v[8:11], v[154:157], v[212:215], v[8:11]
	v_mfma_f32_16x16x32_bf16 v[60:63], v[150:153], v[182:185], v[60:63]
	v_mfma_f32_16x16x32_bf16 v[56:59], v[158:161], v[182:185], v[56:59]
	v_mfma_f32_16x16x32_bf16 v[44:47], v[150:153], v[196:199], v[44:47]
	v_mfma_f32_16x16x32_bf16 v[40:43], v[158:161], v[196:199], v[40:43]
	v_mfma_f32_16x16x32_bf16 v[28:31], v[150:153], v[208:211], v[28:31]
	v_mfma_f32_16x16x32_bf16 v[24:27], v[158:161], v[208:211], v[24:27]
	v_mfma_f32_16x16x32_bf16 v[12:15], v[150:153], v[216:219], v[12:15]
	v_mfma_f32_16x16x32_bf16 v[8:11], v[158:161], v[216:219], v[8:11]
	v_mfma_f32_16x16x32_bf16 v[52:55], v[162:165], v[178:181], v[52:55]
	v_mfma_f32_16x16x32_bf16 v[48:51], v[170:173], v[178:181], v[48:51]
	v_mfma_f32_16x16x32_bf16 v[36:39], v[162:165], v[192:195], v[36:39]
	v_mfma_f32_16x16x32_bf16 v[32:35], v[170:173], v[192:195], v[32:35]
	v_mfma_f32_16x16x32_bf16 v[20:23], v[162:165], v[204:207], v[20:23]
	v_mfma_f32_16x16x32_bf16 v[16:19], v[170:173], v[204:207], v[16:19]
	v_mfma_f32_16x16x32_bf16 v[4:7], v[162:165], v[212:215], v[4:7]
	v_mfma_f32_16x16x32_bf16 v[0:3], v[170:173], v[212:215], v[0:3]
	v_mfma_f32_16x16x32_bf16 v[52:55], v[166:169], v[182:185], v[52:55]
	v_mfma_f32_16x16x32_bf16 v[48:51], v[174:177], v[182:185], v[48:51]
	v_mfma_f32_16x16x32_bf16 v[36:39], v[166:169], v[196:199], v[36:39]
	v_mfma_f32_16x16x32_bf16 v[32:35], v[174:177], v[196:199], v[32:35]
	v_mfma_f32_16x16x32_bf16 v[20:23], v[166:169], v[208:211], v[20:23]
	v_mfma_f32_16x16x32_bf16 v[16:19], v[174:177], v[208:211], v[16:19]
	v_mfma_f32_16x16x32_bf16 v[4:7], v[166:169], v[216:219], v[4:7]
	v_mfma_f32_16x16x32_bf16 v[0:3], v[174:177], v[216:219], v[0:3]
	s_setprio 0
	s_barrier
	s_add_i32 s84, 0, 0x18000
	s_add_i32 s85, 0, 0x1c000
	v_add_u32_e32 v158, s84, v144
	v_add_u32_e32 v174, s85, v144
	ds_read_b128 v[146:149], v158
	ds_read_b128 v[150:153], v158 offset:1024
	ds_read_b128 v[154:157], v158 offset:2048
	ds_read_b128 v[158:161], v158 offset:3072
	ds_read_b128 v[162:165], v174
	ds_read_b128 v[166:169], v174 offset:1024
	ds_read_b128 v[170:173], v174 offset:2048
	ds_read_b128 v[174:177], v174 offset:3072
	s_add_u32 s44, s44, 0xb0000
	s_addc_u32 s45, s45, 0
	s_mov_b32 m0, s59
	v_lshl_add_u64 v[224:225], s[44:45], 0, v[128:129]
	ds_read_b128 v[178:181], v145 offset:32768
	ds_read_b128 v[182:185], v145 offset:33792
	ds_read_b128 v[192:195], v145 offset:34816
	ds_read_b128 v[196:199], v145 offset:35840
	ds_read_b128 v[204:207], v145 offset:36864
	ds_read_b128 v[208:211], v145 offset:37888
	ds_read_b128 v[212:215], v145 offset:38912
	ds_read_b128 v[216:219], v145 offset:39936
	global_load_lds_dwordx4 v[224:225], off
	v_lshl_add_u64 v[224:225], s[44:45], 0, v[132:133]
	s_mov_b32 m0, s60
	s_nop 0
	global_load_lds_dwordx4 v[224:225], off
	s_waitcnt vmcnt(8)
	s_waitcnt lgkmcnt(0)
	s_barrier
	s_setprio 1
	v_mfma_f32_16x16x32_bf16 v[124:127], v[146:149], v[178:181], v[124:127]
	v_mfma_f32_16x16x32_bf16 v[120:123], v[154:157], v[178:181], v[120:123]
	v_mfma_f32_16x16x32_bf16 v[108:111], v[146:149], v[192:195], v[108:111]
	v_mfma_f32_16x16x32_bf16 v[104:107], v[154:157], v[192:195], v[104:107]
	v_mfma_f32_16x16x32_bf16 v[92:95], v[146:149], v[204:207], v[92:95]
	v_mfma_f32_16x16x32_bf16 v[88:91], v[154:157], v[204:207], v[88:91]
	v_mfma_f32_16x16x32_bf16 v[76:79], v[146:149], v[212:215], v[76:79]
	v_mfma_f32_16x16x32_bf16 v[72:75], v[154:157], v[212:215], v[72:75]
	v_mfma_f32_16x16x32_bf16 v[124:127], v[150:153], v[182:185], v[124:127]
	v_mfma_f32_16x16x32_bf16 v[120:123], v[158:161], v[182:185], v[120:123]
	v_mfma_f32_16x16x32_bf16 v[108:111], v[150:153], v[196:199], v[108:111]
	v_mfma_f32_16x16x32_bf16 v[104:107], v[158:161], v[196:199], v[104:107]
	v_mfma_f32_16x16x32_bf16 v[92:95], v[150:153], v[208:211], v[92:95]
	v_mfma_f32_16x16x32_bf16 v[88:91], v[158:161], v[208:211], v[88:91]
	v_mfma_f32_16x16x32_bf16 v[76:79], v[150:153], v[216:219], v[76:79]
	v_mfma_f32_16x16x32_bf16 v[72:75], v[158:161], v[216:219], v[72:75]
	v_mfma_f32_16x16x32_bf16 v[116:119], v[162:165], v[178:181], v[116:119]
	v_mfma_f32_16x16x32_bf16 v[112:115], v[170:173], v[178:181], v[112:115]
	v_mfma_f32_16x16x32_bf16 v[100:103], v[162:165], v[192:195], v[100:103]
	v_mfma_f32_16x16x32_bf16 v[96:99], v[170:173], v[192:195], v[96:99]
	v_mfma_f32_16x16x32_bf16 v[84:87], v[162:165], v[204:207], v[84:87]
	v_mfma_f32_16x16x32_bf16 v[80:83], v[170:173], v[204:207], v[80:83]
	v_mfma_f32_16x16x32_bf16 v[68:71], v[162:165], v[212:215], v[68:71]
	v_mfma_f32_16x16x32_bf16 v[64:67], v[170:173], v[212:215], v[64:67]
	v_mfma_f32_16x16x32_bf16 v[116:119], v[166:169], v[182:185], v[116:119]
	v_mfma_f32_16x16x32_bf16 v[112:115], v[174:177], v[182:185], v[112:115]
	v_mfma_f32_16x16x32_bf16 v[100:103], v[166:169], v[196:199], v[100:103]
	v_mfma_f32_16x16x32_bf16 v[96:99], v[174:177], v[196:199], v[96:99]
	v_mfma_f32_16x16x32_bf16 v[84:87], v[166:169], v[208:211], v[84:87]
	v_mfma_f32_16x16x32_bf16 v[80:83], v[174:177], v[208:211], v[80:83]
	v_mfma_f32_16x16x32_bf16 v[68:71], v[166:169], v[216:219], v[68:71]
	v_mfma_f32_16x16x32_bf16 v[64:67], v[174:177], v[216:219], v[64:67]
	s_setprio 0
	s_barrier
; #define PG8_STAGE(bufoff, gbase, voff) do { _Pragma("unroll") for (int _i = 0; _i < 2; ++_i) \
;         __builtin_amdgcn_global_load_lds((const unsigned*)((const char*)(gbase) + (voff)[_i]), (LAS unsigned*)(lds + (bufoff) + ldsw + _i * 8192), 16, 0, 0); } while (0)
; #define PG8_LDA(dst, b, h) do { _Pragma("unroll") for (int m = 0; m < 4; ++m) _Pragma("unroll") for (int k = 0; k < 2; ++k) dst[m][k] = *(const LAS bf16x8*)(lds + PG8_SA(b, h) + aoff + m * 2048 + k * 1024); } while (0)
; #define PG8_MMA(ai, bj, At, Bt) do { __builtin_amdgcn_s_setprio(1); _Pragma("unroll") for (int m = 0; m < 4; ++m) _Pragma("unroll") for (int n = 0; n < 2; ++n) _Pragma("unroll") for (int k = 0; k < 2; ++k) \
;         acc[ai][bj][m][n] = __builtin_amdgcn_mfma_f32_16x16x32_bf16(Bt[n][k], At[m][k], acc[ai][bj][m][n], 0, 0, 0); __builtin_amdgcn_s_setprio(0); } while (0)
; #define PG8_WAIT_V(n) asm volatile("s_waitcnt vmcnt(" #n ")" ::: "memory")
; #define PG8_WAIT_L(n) asm volatile("s_waitcnt lgkmcnt(" #n ")" ::: "memory")
; #define PG8_BAR __builtin_amdgcn_s_barrier()
; #define PG8_SCHED __builtin_amdgcn_sched_barrier(0)
; template <class Epi>
; __device__ __forceinline__ void gemm_phase(LAS unsigned char* lds, const Gemm g, const Sched& S, const Epi& E) {
;     ...
;             PG8_LDA(At, 1, 1); PG8_STAGE(PG8_SB(1, 0), b3, voffB); PG8_STAGE(PG8_SB(1, 1), b3 + hstepB, voffB); PG8_STAGE(PG8_SA(1, 0), a3, voffA);
;             PG8_WAIT_V(8); PG8_WAIT_L(0); PG8_BAR; PG8_MMA(1, 0, At, B0); PG8_MMA(1, 1, At, B1); PG8_BAR; PG8_SCHED;
;         }
;         if (wr == 0) PG8_BAR;
	s_add_i32 s44, s84, s56
	v_lshl_add_u64 v[186:187], v[186:187], 0, s[8:9]
	s_mov_b32 m0, s44
	ds_read_b128 v[178:181], v145 offset:49152
	ds_read_b128 v[182:185], v145 offset:50176
	ds_read_b128 v[192:195], v145 offset:51200
	ds_read_b128 v[196:199], v145 offset:52224
	ds_read_b128 v[204:207], v145 offset:53248
	ds_read_b128 v[208:211], v145 offset:54272
	ds_read_b128 v[212:215], v145 offset:55296
	ds_read_b128 v[216:219], v145 offset:56320
	global_load_lds_dwordx4 v[186:187], off
	s_add_i32 m0, s44, 0x2000
	s_add_u32 s40, s40, 0xb0080
	v_lshl_add_u64 v[186:187], v[200:201], 0, s[8:9]
	s_addc_u32 s41, s41, 0
	s_add_i32 s44, s85, s56
	global_load_lds_dwordx4 v[186:187], off
	v_lshl_add_u64 v[186:187], s[40:41], 0, v[130:131]
	s_mov_b32 m0, s44
	s_nop 0
	global_load_lds_dwordx4 v[186:187], off
	v_lshl_add_u64 v[186:187], s[40:41], 0, v[134:135]
	s_add_i32 m0, s44, 0x2000
	s_nop 0
	global_load_lds_dwordx4 v[186:187], off
	v_lshl_add_u64 v[186:187], v[220:221], 0, s[8:9]
	s_mov_b32 m0, s62
	s_nop 0
	global_load_lds_dwordx4 v[186:187], off
	v_lshl_add_u64 v[186:187], v[222:223], 0, s[8:9]
	s_mov_b32 m0, s63
	s_nop 0
	global_load_lds_dwordx4 v[186:187], off
	s_waitcnt vmcnt(8)
	s_waitcnt lgkmcnt(0)
	s_barrier
	s_setprio 1
	v_mfma_f32_16x16x32_bf16 v[60:63], v[146:149], v[178:181], v[60:63]
	v_mfma_f32_16x16x32_bf16 v[56:59], v[154:157], v[178:181], v[56:59]
	v_mfma_f32_16x16x32_bf16 v[44:47], v[146:149], v[192:195], v[44:47]
	v_mfma_f32_16x16x32_bf16 v[40:43], v[154:157], v[192:195], v[40:43]
	v_mfma_f32_16x16x32_bf16 v[28:31], v[146:149], v[204:207], v[28:31]
	v_mfma_f32_16x16x32_bf16 v[24:27], v[154:157], v[204:207], v[24:27]
	v_mfma_f32_16x16x32_bf16 v[12:15], v[146:149], v[212:215], v[12:15]
	v_mfma_f32_16x16x32_bf16 v[8:11], v[154:157], v[212:215], v[8:11]
	v_mfma_f32_16x16x32_bf16 v[60:63], v[150:153], v[182:185], v[60:63]
	v_mfma_f32_16x16x32_bf16 v[56:59], v[158:161], v[182:185], v[56:59]
	v_mfma_f32_16x16x32_bf16 v[44:47], v[150:153], v[196:199], v[44:47]
	v_mfma_f32_16x16x32_bf16 v[40:43], v[158:161], v[196:199], v[40:43]
	v_mfma_f32_16x16x32_bf16 v[28:31], v[150:153], v[208:211], v[28:31]
	v_mfma_f32_16x16x32_bf16 v[24:27], v[158:161], v[208:211], v[24:27]
	v_mfma_f32_16x16x32_bf16 v[12:15], v[150:153], v[216:219], v[12:15]
	v_mfma_f32_16x16x32_bf16 v[8:11], v[158:161], v[216:219], v[8:11]
	v_mfma_f32_16x16x32_bf16 v[52:55], v[162:165], v[178:181], v[52:55]
	v_mfma_f32_16x16x32_bf16 v[48:51], v[170:173], v[178:181], v[48:51]
	v_mfma_f32_16x16x32_bf16 v[36:39], v[162:165], v[192:195], v[36:39]
	v_mfma_f32_16x16x32_bf16 v[32:35], v[170:173], v[192:195], v[32:35]
	v_mfma_f32_16x16x32_bf16 v[20:23], v[162:165], v[204:207], v[20:23]
	v_mfma_f32_16x16x32_bf16 v[16:19], v[170:173], v[204:207], v[16:19]
	v_mfma_f32_16x16x32_bf16 v[4:7], v[162:165], v[212:215], v[4:7]
	v_mfma_f32_16x16x32_bf16 v[0:3], v[170:173], v[212:215], v[0:3]
	v_mfma_f32_16x16x32_bf16 v[52:55], v[166:169], v[182:185], v[52:55]
	v_mfma_f32_16x16x32_bf16 v[48:51], v[174:177], v[182:185], v[48:51]
	v_mfma_f32_16x16x32_bf16 v[36:39], v[166:169], v[196:199], v[36:39]
	v_mfma_f32_16x16x32_bf16 v[32:35], v[174:177], v[196:199], v[32:35]
	v_mfma_f32_16x16x32_bf16 v[20:23], v[166:169], v[208:211], v[20:23]
	v_mfma_f32_16x16x32_bf16 v[16:19], v[174:177], v[208:211], v[16:19]
	v_mfma_f32_16x16x32_bf16 v[4:7], v[166:169], v[216:219], v[4:7]
	v_mfma_f32_16x16x32_bf16 v[0:3], v[174:177], v[216:219], v[0:3]
	s_setprio 0
	s_barrier
	s_add_i32 s89, s89, 2
	s_add_u32 s28, s28, 0x100
	s_addc_u32 s29, s29, 0
	s_cmp_gt_u32 s89, 41
	s_cbranch_scc0 .LBB0_374
	s_and_b64 vcc, exec, s[14:15]
	s_cbranch_vccz .LBB0_377
	s_barrier

; #define PG8_STAGE(bufoff, gbase, voff) do { _Pragma("unroll") for (int _i = 0; _i < 2; ++_i) \
;         __builtin_amdgcn_global_load_lds((const unsigned*)((const char*)(gbase) + (voff)[_i]), (LAS unsigned*)(lds + (bufoff) + ldsw + _i * 8192), 16, 0, 0); } while (0)
; #define PG8_LDA(dst, b, h) do { _Pragma("unroll") for (int m = 0; m < 4; ++m) _Pragma("unroll") for (int k = 0; k < 2; ++k) dst[m][k] = *(const LAS bf16x8*)(lds + PG8_SA(b, h) + aoff + m * 2048 + k * 1024); } while (0)
; #define PG8_LDB(dst, b, h) do { _Pragma("unroll") for (int n = 0; n < 2; ++n) _Pragma("unroll") for (int k = 0; k < 2; ++k) dst[n][k] = *(const LAS bf16x8*)(lds + PG8_SB(b, h) + boff + n * 2048 + k * 1024); } while (0)
; #define PG8_MMA(ai, bj, At, Bt) do { __builtin_amdgcn_s_setprio(1); _Pragma("unroll") for (int m = 0; m < 4; ++m) _Pragma("unroll") for (int n = 0; n < 2; ++n) _Pragma("unroll") for (int k = 0; k < 2; ++k) \
;         acc[ai][bj][m][n] = __builtin_amdgcn_mfma_f32_16x16x32_bf16(Bt[n][k], At[m][k], acc[ai][bj][m][n], 0, 0, 0); __builtin_amdgcn_s_setprio(0); } while (0)
; #define PG8_WAIT_V(n) asm volatile("s_waitcnt vmcnt(" #n ")" ::: "memory")
; #define PG8_WAIT_L(n) asm volatile("s_waitcnt lgkmcnt(" #n ")" ::: "memory")
; #define PG8_BAR __builtin_amdgcn_s_barrier()
; #define PG8_SCHED __builtin_amdgcn_sched_barrier(0)
; template <class Epi>
; __device__ __forceinline__ void gemm_phase(LAS unsigned char* lds, const Gemm g, const Sched& S, const Epi& E) {
;     ...
;             const char* a1 = cA + (size_t)(t + 1) * kstep;
;             const char* a2 = last ? nA : cA + (size_t)(t + 2) * kstep; const char* b2 = last ? nB : cB + (size_t)(t + 2) * kstep;
;             const char* a3 = a2 + kstep; const char* b3 = b2 + kstep;
;             PG8_LDB(B0, 0, 0); PG8_LDB(B1, 0, 1); PG8_SCHED; PG8_LDA(At, 0, 0); PG8_STAGE(PG8_SA(1, 1), a1 + hstepA, voffA);
;             PG8_WAIT_V(8); PG8_WAIT_L(0); PG8_BAR; PG8_MMA(0, 0, At, B0); PG8_MMA(0, 1, At, B1); PG8_BAR; PG8_SCHED;
;             PG8_LDA(At, 0, 1); PG8_STAGE(PG8_SB(0, 0), b2, voffB); PG8_STAGE(PG8_SB(0, 1), b2 + hstepB, voffB); PG8_STAGE(PG8_SA(0, 0), a2, voffA);
;             PG8_WAIT_V(8); PG8_WAIT_L(0); PG8_BAR; PG8_MMA(1, 0, At, B0); PG8_MMA(1, 1, At, B1); PG8_BAR; PG8_SCHED;
.LBB0_520:
	ds_read_b128 v[128:131], v160
	ds_read_b128 v[132:135], v160 offset:1024
	ds_read_b128 v[152:155], v160 offset:2048
	ds_read_b128 v[164:167], v160 offset:3072
	ds_read_b128 v[168:171], v161
	ds_read_b128 v[172:175], v161 offset:1024
	ds_read_b128 v[176:179], v161 offset:2048
	ds_read_b128 v[180:183], v161 offset:3072
	s_add_u32 s4, s2, 0xfffc0080
	s_addc_u32 s5, s3, -1
	s_cmp_eq_u32 s57, 12
	s_cselect_b32 s53, s0, s5
	s_cselect_b32 s52, s27, s4
	s_cselect_b32 s5, s25, s56
	s_cselect_b32 s4, s54, s55
	v_lshl_add_u64 v[200:201], s[2:3], 0, v[146:147]
	s_add_i32 m0, s10, 0xc000
	ds_read_b128 v[184:187], v162
	ds_read_b128 v[188:191], v162 offset:1024
	ds_read_b128 v[192:195], v162 offset:2048
	ds_read_b128 v[196:199], v162 offset:3072
	ds_read_b128 v[204:207], v162 offset:4096
	ds_read_b128 v[208:211], v162 offset:5120
	ds_read_b128 v[212:215], v162 offset:6144
	ds_read_b128 v[216:219], v162 offset:7168
	global_load_lds_dwordx4 v[200:201], off
	v_lshl_add_u64 v[200:201], s[2:3], 0, v[148:149]
	s_add_i32 m0, s10, 0xe000
	s_nop 0
	global_load_lds_dwordx4 v[200:201], off
	s_waitcnt vmcnt(8)
	s_waitcnt lgkmcnt(0)
	s_barrier
	s_setprio 1
	v_mfma_f32_16x16x32_bf16 v[124:127], v[128:131], v[184:187], v[124:127]
	v_mfma_f32_16x16x32_bf16 v[116:119], v[152:155], v[184:187], v[116:119]
	v_mfma_f32_16x16x32_bf16 v[108:111], v[128:131], v[192:195], v[108:111]
	v_mfma_f32_16x16x32_bf16 v[100:103], v[152:155], v[192:195], v[100:103]
	v_mfma_f32_16x16x32_bf16 v[92:95], v[128:131], v[204:207], v[92:95]
	v_mfma_f32_16x16x32_bf16 v[84:87], v[152:155], v[204:207], v[84:87]
	v_mfma_f32_16x16x32_bf16 v[76:79], v[128:131], v[212:215], v[76:79]
	v_mfma_f32_16x16x32_bf16 v[68:71], v[152:155], v[212:215], v[68:71]
	v_mfma_f32_16x16x32_bf16 v[124:127], v[132:135], v[188:191], v[124:127]
	v_mfma_f32_16x16x32_bf16 v[116:119], v[164:167], v[188:191], v[116:119]
	v_mfma_f32_16x16x32_bf16 v[108:111], v[132:135], v[196:199], v[108:111]
	v_mfma_f32_16x16x32_bf16 v[100:103], v[164:167], v[196:199], v[100:103]
	v_mfma_f32_16x16x32_bf16 v[92:95], v[132:135], v[208:211], v[92:95]
	v_mfma_f32_16x16x32_bf16 v[84:87], v[164:167], v[208:211], v[84:87]
	v_mfma_f32_16x16x32_bf16 v[76:79], v[132:135], v[216:219], v[76:79]
	v_mfma_f32_16x16x32_bf16 v[68:71], v[164:167], v[216:219], v[68:71]
	v_mfma_f32_16x16x32_bf16 v[120:123], v[168:171], v[184:187], v[120:123]
	v_mfma_f32_16x16x32_bf16 v[112:115], v[176:179], v[184:187], v[112:115]
	v_mfma_f32_16x16x32_bf16 v[104:107], v[168:171], v[192:195], v[104:107]
	v_mfma_f32_16x16x32_bf16 v[96:99], v[176:179], v[192:195], v[96:99]
	v_mfma_f32_16x16x32_bf16 v[88:91], v[168:171], v[204:207], v[88:91]
	v_mfma_f32_16x16x32_bf16 v[80:83], v[176:179], v[204:207], v[80:83]
	v_mfma_f32_16x16x32_bf16 v[72:75], v[168:171], v[212:215], v[72:75]
	v_mfma_f32_16x16x32_bf16 v[64:67], v[176:179], v[212:215], v[64:67]
	v_mfma_f32_16x16x32_bf16 v[120:123], v[172:175], v[188:191], v[120:123]
	v_mfma_f32_16x16x32_bf16 v[112:115], v[180:183], v[188:191], v[112:115]
	v_mfma_f32_16x16x32_bf16 v[104:107], v[172:175], v[196:199], v[104:107]
	v_mfma_f32_16x16x32_bf16 v[96:99], v[180:183], v[196:199], v[96:99]
	v_mfma_f32_16x16x32_bf16 v[88:91], v[172:175], v[208:211], v[88:91]
	v_mfma_f32_16x16x32_bf16 v[80:83], v[180:183], v[208:211], v[80:83]
	v_mfma_f32_16x16x32_bf16 v[72:75], v[172:175], v[216:219], v[72:75]
	v_mfma_f32_16x16x32_bf16 v[64:67], v[180:183], v[216:219], v[64:67]
	s_setprio 0
	s_barrier
	s_add_i32 s58, s89, s86
	v_lshl_add_u64 v[200:201], s[4:5], 0, v[138:139]
	s_mov_b32 m0, s58
	ds_read_b128 v[184:187], v162 offset:16384
	ds_read_b128 v[188:191], v162 offset:17408
	ds_read_b128 v[192:195], v162 offset:18432
	ds_read_b128 v[196:199], v162 offset:19456
	ds_read_b128 v[204:207], v162 offset:20480
	ds_read_b128 v[208:211], v162 offset:21504
	ds_read_b128 v[212:215], v162 offset:22528
	ds_read_b128 v[216:219], v162 offset:23552
	global_load_lds_dwordx4 v[200:201], off
	s_add_i32 m0, s58, 0x2000
	s_add_u32 s58, s4, 0x40000
	v_lshl_add_u64 v[220:221], s[4:5], 0, v[142:143]
	s_addc_u32 s59, s5, 0
	s_add_i32 s60, s90, s86
	global_load_lds_dwordx4 v[220:221], off
	v_lshl_add_u64 v[222:223], s[58:59], 0, v[138:139]
	s_mov_b32 m0, s60
	v_lshl_add_u64 v[224:225], s[52:53], 0, v[140:141]
	global_load_lds_dwordx4 v[222:223], off
	v_lshl_add_u64 v[222:223], s[58:59], 0, v[142:143]
	s_add_i32 m0, s60, 0x2000
	s_nop 0
	global_load_lds_dwordx4 v[222:223], off
	v_lshl_add_u64 v[222:223], s[52:53], 0, v[136:137]
	s_mov_b32 m0, s10
	s_nop 0
	global_load_lds_dwordx4 v[222:223], off
	s_mov_b32 m0, s11
	s_nop 0
	global_load_lds_dwordx4 v[224:225], off
	s_waitcnt vmcnt(8)
	s_waitcnt lgkmcnt(0)
	s_barrier
; #define PG8_STAGE(bufoff, gbase, voff) do { _Pragma("unroll") for (int _i = 0; _i < 2; ++_i) \
;         __builtin_amdgcn_global_load_lds((const unsigned*)((const char*)(gbase) + (voff)[_i]), (LAS unsigned*)(lds + (bufoff) + ldsw + _i * 8192), 16, 0, 0); } while (0)
; #define PG8_LDA(dst, b, h) do { _Pragma("unroll") for (int m = 0; m < 4; ++m) _Pragma("unroll") for (int k = 0; k < 2; ++k) dst[m][k] = *(const LAS bf16x8*)(lds + PG8_SA(b, h) + aoff + m * 2048 + k * 1024); } while (0)
; #define PG8_LDB(dst, b, h) do { _Pragma("unroll") for (int n = 0; n < 2; ++n) _Pragma("unroll") for (int k = 0; k < 2; ++k) dst[n][k] = *(const LAS bf16x8*)(lds + PG8_SB(b, h) + boff + n * 2048 + k * 1024); } while (0)
; #define PG8_MMA(ai, bj, At, Bt) do { __builtin_amdgcn_s_setprio(1); _Pragma("unroll") for (int m = 0; m < 4; ++m) _Pragma("unroll") for (int n = 0; n < 2; ++n) _Pragma("unroll") for (int k = 0; k < 2; ++k) \
;         acc[ai][bj][m][n] = __builtin_amdgcn_mfma_f32_16x16x32_bf16(Bt[n][k], At[m][k], acc[ai][bj][m][n], 0, 0, 0); __builtin_amdgcn_s_setprio(0); } while (0)
; #define PG8_WAIT_V(n) asm volatile("s_waitcnt vmcnt(" #n ")" ::: "memory")
; #define PG8_WAIT_L(n) asm volatile("s_waitcnt lgkmcnt(" #n ")" ::: "memory")
; #define PG8_BAR __builtin_amdgcn_s_barrier()
; #define PG8_SCHED __builtin_amdgcn_sched_barrier(0)
; template <class Epi>
; __device__ __forceinline__ void gemm_phase(LAS unsigned char* lds, const Gemm g, const Sched& S, const Epi& E) {
;     ...
;             PG8_WAIT_V(8); PG8_WAIT_L(0); PG8_BAR; PG8_MMA(1, 0, At, B0); PG8_MMA(1, 1, At, B1); PG8_BAR; PG8_SCHED;
;             PG8_LDB(B0, 1, 0); PG8_LDB(B1, 1, 1); PG8_SCHED; PG8_LDA(At, 1, 0); PG8_STAGE(PG8_SA(0, 1), a2 + hstepA, voffA);
;             PG8_WAIT_V(8); PG8_WAIT_L(0); PG8_BAR; PG8_MMA(0, 0, At, B0); PG8_MMA(0, 1, At, B1); PG8_BAR; PG8_SCHED;
	s_setprio 1
	v_mfma_f32_16x16x32_bf16 v[60:63], v[128:131], v[184:187], v[60:63]
	v_mfma_f32_16x16x32_bf16 v[52:55], v[152:155], v[184:187], v[52:55]
	v_mfma_f32_16x16x32_bf16 v[44:47], v[128:131], v[192:195], v[44:47]
	v_mfma_f32_16x16x32_bf16 v[36:39], v[152:155], v[192:195], v[36:39]
	v_mfma_f32_16x16x32_bf16 v[28:31], v[128:131], v[204:207], v[28:31]
	v_mfma_f32_16x16x32_bf16 v[20:23], v[152:155], v[204:207], v[20:23]
	v_mfma_f32_16x16x32_bf16 v[12:15], v[128:131], v[212:215], v[12:15]
	v_mfma_f32_16x16x32_bf16 v[4:7], v[152:155], v[212:215], v[4:7]
	v_mfma_f32_16x16x32_bf16 v[60:63], v[132:135], v[188:191], v[60:63]
	v_mfma_f32_16x16x32_bf16 v[52:55], v[164:167], v[188:191], v[52:55]
	v_mfma_f32_16x16x32_bf16 v[44:47], v[132:135], v[196:199], v[44:47]
	v_mfma_f32_16x16x32_bf16 v[36:39], v[164:167], v[196:199], v[36:39]
	v_mfma_f32_16x16x32_bf16 v[28:31], v[132:135], v[208:211], v[28:31]
	v_mfma_f32_16x16x32_bf16 v[20:23], v[164:167], v[208:211], v[20:23]
	v_mfma_f32_16x16x32_bf16 v[12:15], v[132:135], v[216:219], v[12:15]
	v_mfma_f32_16x16x32_bf16 v[4:7], v[164:167], v[216:219], v[4:7]
	v_mfma_f32_16x16x32_bf16 v[56:59], v[168:171], v[184:187], v[56:59]
	v_mfma_f32_16x16x32_bf16 v[48:51], v[176:179], v[184:187], v[48:51]
	v_mfma_f32_16x16x32_bf16 v[40:43], v[168:171], v[192:195], v[40:43]
	v_mfma_f32_16x16x32_bf16 v[32:35], v[176:179], v[192:195], v[32:35]
	v_mfma_f32_16x16x32_bf16 v[24:27], v[168:171], v[204:207], v[24:27]
	v_mfma_f32_16x16x32_bf16 v[16:19], v[176:179], v[204:207], v[16:19]
	v_mfma_f32_16x16x32_bf16 v[8:11], v[168:171], v[212:215], v[8:11]
	v_mfma_f32_16x16x32_bf16 v[0:3], v[176:179], v[212:215], v[0:3]
	v_mfma_f32_16x16x32_bf16 v[56:59], v[172:175], v[188:191], v[56:59]
	v_mfma_f32_16x16x32_bf16 v[48:51], v[180:183], v[188:191], v[48:51]
	v_mfma_f32_16x16x32_bf16 v[40:43], v[172:175], v[196:199], v[40:43]
	v_mfma_f32_16x16x32_bf16 v[32:35], v[180:183], v[196:199], v[32:35]
	v_mfma_f32_16x16x32_bf16 v[24:27], v[172:175], v[208:211], v[24:27]
	v_mfma_f32_16x16x32_bf16 v[16:19], v[180:183], v[208:211], v[16:19]
	v_mfma_f32_16x16x32_bf16 v[8:11], v[172:175], v[216:219], v[8:11]
	v_mfma_f32_16x16x32_bf16 v[0:3], v[180:183], v[216:219], v[0:3]
	s_setprio 0
	s_barrier
	s_add_i32 s58, 0, 0x18000
	v_add_u32_e32 v144, s58, v158
	s_add_i32 s59, 0, 0x1c000
	ds_read_b128 v[128:131], v144
	ds_read_b128 v[132:135], v144 offset:1024
	ds_read_b128 v[152:155], v144 offset:2048
	ds_read_b128 v[164:167], v144 offset:3072
	v_add_u32_e32 v144, s59, v158
	ds_read_b128 v[168:171], v144
	ds_read_b128 v[172:175], v144 offset:1024
	ds_read_b128 v[176:179], v144 offset:2048
	ds_read_b128 v[180:183], v144 offset:3072
	s_add_u32 s52, s52, 0x40000
	s_addc_u32 s53, s53, 0
	s_mov_b32 m0, s45
	v_lshl_add_u64 v[226:227], s[52:53], 0, v[136:137]
	ds_read_b128 v[184:187], v162 offset:32768
	ds_read_b128 v[188:191], v162 offset:33792
	ds_read_b128 v[192:195], v162 offset:34816
	ds_read_b128 v[196:199], v162 offset:35840
	ds_read_b128 v[204:207], v162 offset:36864
	ds_read_b128 v[208:211], v162 offset:37888
	ds_read_b128 v[212:215], v162 offset:38912
	ds_read_b128 v[216:219], v162 offset:39936
	global_load_lds_dwordx4 v[226:227], off
	v_lshl_add_u64 v[226:227], s[52:53], 0, v[140:141]
	s_mov_b32 m0, s47
	s_nop 0
	global_load_lds_dwordx4 v[226:227], off
	s_waitcnt vmcnt(8)
	s_waitcnt lgkmcnt(0)
	s_barrier
	s_setprio 1
	v_mfma_f32_16x16x32_bf16 v[124:127], v[128:131], v[184:187], v[124:127]
	v_mfma_f32_16x16x32_bf16 v[116:119], v[152:155], v[184:187], v[116:119]
	v_mfma_f32_16x16x32_bf16 v[108:111], v[128:131], v[192:195], v[108:111]
	v_mfma_f32_16x16x32_bf16 v[100:103], v[152:155], v[192:195], v[100:103]
	v_mfma_f32_16x16x32_bf16 v[92:95], v[128:131], v[204:207], v[92:95]
	v_mfma_f32_16x16x32_bf16 v[84:87], v[152:155], v[204:207], v[84:87]
	v_mfma_f32_16x16x32_bf16 v[76:79], v[128:131], v[212:215], v[76:79]
	v_mfma_f32_16x16x32_bf16 v[68:71], v[152:155], v[212:215], v[68:71]
	v_mfma_f32_16x16x32_bf16 v[124:127], v[132:135], v[188:191], v[124:127]
	v_mfma_f32_16x16x32_bf16 v[116:119], v[164:167], v[188:191], v[116:119]
	v_mfma_f32_16x16x32_bf16 v[108:111], v[132:135], v[196:199], v[108:111]
	v_mfma_f32_16x16x32_bf16 v[100:103], v[164:167], v[196:199], v[100:103]
	v_mfma_f32_16x16x32_bf16 v[92:95], v[132:135], v[208:211], v[92:95]
	v_mfma_f32_16x16x32_bf16 v[84:87], v[164:167], v[208:211], v[84:87]
	v_mfma_f32_16x16x32_bf16 v[76:79], v[132:135], v[216:219], v[76:79]
	v_mfma_f32_16x16x32_bf16 v[68:71], v[164:167], v[216:219], v[68:71]
	v_mfma_f32_16x16x32_bf16 v[120:123], v[168:171], v[184:187], v[120:123]
	v_mfma_f32_16x16x32_bf16 v[112:115], v[176:179], v[184:187], v[112:115]
	v_mfma_f32_16x16x32_bf16 v[104:107], v[168:171], v[192:195], v[104:107]
	v_mfma_f32_16x16x32_bf16 v[96:99], v[176:179], v[192:195], v[96:99]
	v_mfma_f32_16x16x32_bf16 v[88:91], v[168:171], v[204:207], v[88:91]
	v_mfma_f32_16x16x32_bf16 v[80:83], v[176:179], v[204:207], v[80:83]
	v_mfma_f32_16x16x32_bf16 v[72:75], v[168:171], v[212:215], v[72:75]
	v_mfma_f32_16x16x32_bf16 v[64:67], v[176:179], v[212:215], v[64:67]
	v_mfma_f32_16x16x32_bf16 v[120:123], v[172:175], v[188:191], v[120:123]
	v_mfma_f32_16x16x32_bf16 v[112:115], v[180:183], v[188:191], v[112:115]
	v_mfma_f32_16x16x32_bf16 v[104:107], v[172:175], v[196:199], v[104:107]
	v_mfma_f32_16x16x32_bf16 v[96:99], v[180:183], v[196:199], v[96:99]
	v_mfma_f32_16x16x32_bf16 v[88:91], v[172:175], v[208:211], v[88:91]
	v_mfma_f32_16x16x32_bf16 v[80:83], v[180:183], v[208:211], v[80:83]
	v_mfma_f32_16x16x32_bf16 v[72:75], v[172:175], v[216:219], v[72:75]
	v_mfma_f32_16x16x32_bf16 v[64:67], v[180:183], v[216:219], v[64:67]
	s_setprio 0
	s_barrier
; #define PG8_STAGE(bufoff, gbase, voff) do { _Pragma("unroll") for (int _i = 0; _i < 2; ++_i) \
;         __builtin_amdgcn_global_load_lds((const unsigned*)((const char*)(gbase) + (voff)[_i]), (LAS unsigned*)(lds + (bufoff) + ldsw + _i * 8192), 16, 0, 0); } while (0)
; #define PG8_LDA(dst, b, h) do { _Pragma("unroll") for (int m = 0; m < 4; ++m) _Pragma("unroll") for (int k = 0; k < 2; ++k) dst[m][k] = *(const LAS bf16x8*)(lds + PG8_SA(b, h) + aoff + m * 2048 + k * 1024); } while (0)
; #define PG8_MMA(ai, bj, At, Bt) do { __builtin_amdgcn_s_setprio(1); _Pragma("unroll") for (int m = 0; m < 4; ++m) _Pragma("unroll") for (int n = 0; n < 2; ++n) _Pragma("unroll") for (int k = 0; k < 2; ++k) \
;         acc[ai][bj][m][n] = __builtin_amdgcn_mfma_f32_16x16x32_bf16(Bt[n][k], At[m][k], acc[ai][bj][m][n], 0, 0, 0); __builtin_amdgcn_s_setprio(0); } while (0)
; #define PG8_WAIT_V(n) asm volatile("s_waitcnt vmcnt(" #n ")" ::: "memory")
; #define PG8_WAIT_L(n) asm volatile("s_waitcnt lgkmcnt(" #n ")" ::: "memory")
; #define PG8_BAR __builtin_amdgcn_s_barrier()
; #define PG8_SCHED __builtin_amdgcn_sched_barrier(0)
; template <class Epi>
; __device__ __forceinline__ void gemm_phase(LAS unsigned char* lds, const Gemm g, const Sched& S, const Epi& E) {
;     ...
;             PG8_LDA(At, 1, 1); PG8_STAGE(PG8_SB(1, 0), b3, voffB); PG8_STAGE(PG8_SB(1, 1), b3 + hstepB, voffB); PG8_STAGE(PG8_SA(1, 0), a3, voffA);
;             PG8_WAIT_V(8); PG8_WAIT_L(0); PG8_BAR; PG8_MMA(1, 0, At, B0); PG8_MMA(1, 1, At, B1); PG8_BAR; PG8_SCHED;
;         }
;         if (wr == 0) PG8_BAR;
;     __device__ __forceinline__ void operator()(AccRef acc, const Unit& u, int wr, int wc, int fr, int fq) const {
;         const int pn = u.pn, cw = wc * 32 + 8 * fq;
;         if (pn >= 17 && pn < 25) {
	s_add_i32 s52, s58, s86
	v_lshl_add_u64 v[200:201], v[200:201], 0, s[14:15]
	s_mov_b32 m0, s52
	ds_read_b128 v[184:187], v162 offset:49152
	ds_read_b128 v[188:191], v162 offset:50176
	ds_read_b128 v[192:195], v162 offset:51200
	ds_read_b128 v[196:199], v162 offset:52224
	ds_read_b128 v[204:207], v162 offset:53248
	ds_read_b128 v[208:211], v162 offset:54272
	ds_read_b128 v[212:215], v162 offset:55296
	ds_read_b128 v[216:219], v162 offset:56320
	global_load_lds_dwordx4 v[200:201], off
	s_add_i32 m0, s52, 0x2000
	s_add_u32 s4, s4, 0x40080
	v_lshl_add_u64 v[200:201], v[220:221], 0, s[14:15]
	s_addc_u32 s5, s5, 0
	s_add_i32 s52, s59, s86
	global_load_lds_dwordx4 v[200:201], off
	v_lshl_add_u64 v[200:201], s[4:5], 0, v[138:139]
	s_mov_b32 m0, s52
	s_nop 0
	global_load_lds_dwordx4 v[200:201], off
	v_lshl_add_u64 v[200:201], s[4:5], 0, v[142:143]
	s_add_i32 m0, s52, 0x2000
	s_nop 0
	global_load_lds_dwordx4 v[200:201], off
	v_lshl_add_u64 v[200:201], v[222:223], 0, s[14:15]
	s_mov_b32 m0, s87
	s_nop 0
	global_load_lds_dwordx4 v[200:201], off
	v_lshl_add_u64 v[200:201], v[224:225], 0, s[14:15]
	s_mov_b32 m0, s88
	s_nop 0
	global_load_lds_dwordx4 v[200:201], off
	s_waitcnt vmcnt(8)
	s_waitcnt lgkmcnt(0)
	s_barrier
	s_setprio 1
	v_mfma_f32_16x16x32_bf16 v[60:63], v[128:131], v[184:187], v[60:63]
	v_mfma_f32_16x16x32_bf16 v[52:55], v[152:155], v[184:187], v[52:55]
	v_mfma_f32_16x16x32_bf16 v[44:47], v[128:131], v[192:195], v[44:47]
	v_mfma_f32_16x16x32_bf16 v[36:39], v[152:155], v[192:195], v[36:39]
	v_mfma_f32_16x16x32_bf16 v[28:31], v[128:131], v[204:207], v[28:31]
	v_mfma_f32_16x16x32_bf16 v[20:23], v[152:155], v[204:207], v[20:23]
	v_mfma_f32_16x16x32_bf16 v[12:15], v[128:131], v[212:215], v[12:15]
	v_mfma_f32_16x16x32_bf16 v[4:7], v[152:155], v[212:215], v[4:7]
	v_mfma_f32_16x16x32_bf16 v[60:63], v[132:135], v[188:191], v[60:63]
	v_mfma_f32_16x16x32_bf16 v[52:55], v[164:167], v[188:191], v[52:55]
	v_mfma_f32_16x16x32_bf16 v[44:47], v[132:135], v[196:199], v[44:47]
	v_mfma_f32_16x16x32_bf16 v[36:39], v[164:167], v[196:199], v[36:39]
	v_mfma_f32_16x16x32_bf16 v[28:31], v[132:135], v[208:211], v[28:31]
	v_mfma_f32_16x16x32_bf16 v[20:23], v[164:167], v[208:211], v[20:23]
	v_mfma_f32_16x16x32_bf16 v[12:15], v[132:135], v[216:219], v[12:15]
	v_mfma_f32_16x16x32_bf16 v[4:7], v[164:167], v[216:219], v[4:7]
	v_mfma_f32_16x16x32_bf16 v[56:59], v[168:171], v[184:187], v[56:59]
	v_mfma_f32_16x16x32_bf16 v[48:51], v[176:179], v[184:187], v[48:51]
	v_mfma_f32_16x16x32_bf16 v[40:43], v[168:171], v[192:195], v[40:43]
	v_mfma_f32_16x16x32_bf16 v[32:35], v[176:179], v[192:195], v[32:35]
	v_mfma_f32_16x16x32_bf16 v[24:27], v[168:171], v[204:207], v[24:27]
	v_mfma_f32_16x16x32_bf16 v[16:19], v[176:179], v[204:207], v[16:19]
	v_mfma_f32_16x16x32_bf16 v[8:11], v[168:171], v[212:215], v[8:11]
	v_mfma_f32_16x16x32_bf16 v[0:3], v[176:179], v[212:215], v[0:3]
	v_mfma_f32_16x16x32_bf16 v[56:59], v[172:175], v[188:191], v[56:59]
	v_mfma_f32_16x16x32_bf16 v[48:51], v[180:183], v[188:191], v[48:51]
	v_mfma_f32_16x16x32_bf16 v[40:43], v[172:175], v[196:199], v[40:43]
	v_mfma_f32_16x16x32_bf16 v[32:35], v[180:183], v[196:199], v[32:35]
	v_mfma_f32_16x16x32_bf16 v[24:27], v[172:175], v[208:211], v[24:27]
	v_mfma_f32_16x16x32_bf16 v[16:19], v[180:183], v[208:211], v[16:19]
	v_mfma_f32_16x16x32_bf16 v[8:11], v[172:175], v[216:219], v[8:11]
	v_mfma_f32_16x16x32_bf16 v[0:3], v[180:183], v[216:219], v[0:3]
	s_setprio 0
	s_barrier
	s_add_i32 s57, s57, 2
	s_add_u32 s2, s2, 0x100
	s_addc_u32 s3, s3, 0
	s_add_u32 s55, s55, 0x100
	s_addc_u32 s56, s56, 0
	s_cmp_gt_u32 s57, 13
	s_cbranch_scc0 .LBB0_520
	s_and_b64 vcc, exec, s[20:21]
	s_cbranch_vccnz .LBB0_525
	s_sub_i32 s0, s44, 17
	s_cmp_gt_u32 s0, 7
	s_mov_b64 s[2:3], -1
	s_cbranch_scc1 .LBB0_526

; #define PG8_STAGE(bufoff, gbase, voff) do { _Pragma("unroll") for (int _i = 0; _i < 2; ++_i) \
;         __builtin_amdgcn_global_load_lds((const unsigned*)((const char*)(gbase) + (voff)[_i]), (LAS unsigned*)(lds + (bufoff) + ldsw + _i * 8192), 16, 0, 0); } while (0)
; #define PG8_LDA(dst, b, h) do { _Pragma("unroll") for (int m = 0; m < 4; ++m) _Pragma("unroll") for (int k = 0; k < 2; ++k) dst[m][k] = *(const LAS bf16x8*)(lds + PG8_SA(b, h) + aoff + m * 2048 + k * 1024); } while (0)
; #define PG8_LDB(dst, b, h) do { _Pragma("unroll") for (int n = 0; n < 2; ++n) _Pragma("unroll") for (int k = 0; k < 2; ++k) dst[n][k] = *(const LAS bf16x8*)(lds + PG8_SB(b, h) + boff + n * 2048 + k * 1024); } while (0)
; #define PG8_MMA(ai, bj, At, Bt) do { __builtin_amdgcn_s_setprio(1); _Pragma("unroll") for (int m = 0; m < 4; ++m) _Pragma("unroll") for (int n = 0; n < 2; ++n) _Pragma("unroll") for (int k = 0; k < 2; ++k) \
;         acc[ai][bj][m][n] = __builtin_amdgcn_mfma_f32_16x16x32_bf16(Bt[n][k], At[m][k], acc[ai][bj][m][n], 0, 0, 0); __builtin_amdgcn_s_setprio(0); } while (0)
; #define PG8_BAR __builtin_amdgcn_s_barrier()
; template <class Epi>
; __device__ __forceinline__ void gemm_phase(LAS unsigned char* lds, const Gemm g, const Sched& S, const Epi& E) {
;     ...
;         const bool has_next = S.next(ui + 1, nxt);
;         const char* nA = has_next ? (const char*)g.A + (size_t)S.aoff(nxt) * 2 : cA; const char* nB = has_next ? (const char*)g.Bt + (size_t)S.boff(nxt) * 2 : cB;
;         _Pragma("nounroll")
;         for (int t = 0; t < nt; t += 2) {
;             const bool last = (t == nt - 2);
;             const char* a1 = cA + (size_t)(t + 1) * kstep;
;             const char* a2 = last ? nA : cA + (size_t)(t + 2) * kstep; const char* b2 = last ? nB : cB + (size_t)(t + 2) * kstep;
;             const char* a3 = a2 + kstep; const char* b3 = b2 + kstep;
;             PG8_LDB(B0, 0, 0); PG8_LDB(B1, 0, 1); PG8_SCHED; PG8_LDA(At, 0, 0); PG8_STAGE(PG8_SA(1, 1), a1 + hstepA, voffA);
;             PG8_WAIT_V(8); PG8_WAIT_L(0); PG8_BAR; PG8_MMA(0, 0, At, B0); PG8_MMA(0, 1, At, B1); PG8_BAR; PG8_SCHED;
;             PG8_LDA(At, 0, 1); PG8_STAGE(PG8_SB(0, 0), b2, voffB); PG8_STAGE(PG8_SB(0, 1), b2 + hstepB, voffB); PG8_STAGE(PG8_SA(0, 0), a2, voffA);
;             PG8_WAIT_V(8); PG8_WAIT_L(0); PG8_BAR; PG8_MMA(1, 0, At, B0); PG8_MMA(1, 1, At, B1); PG8_BAR; PG8_SCHED;
.LBB0_773:
	s_add_u32 s60, s46, s74
	s_addc_u32 s61, s47, s75
	s_add_u32 s62, s60, 0x100
	s_addc_u32 s63, s61, 0
	s_and_b64 s[58:59], s[56:57], exec
	s_cselect_b32 s77, s3, s63
	s_cselect_b32 s76, s5, s62
	s_add_u32 s58, s52, s74
	s_addc_u32 s59, s53, s75
	s_add_u32 s58, s58, 0x100
	s_addc_u32 s59, s59, 0
	s_and_b64 s[56:57], s[56:57], exec
	s_cselect_b32 s79, s25, s59
	s_cselect_b32 s78, s27, s58
	s_add_u32 s86, s60, 0x10080
	ds_read_b128 v[80:83], v162
	ds_read_b128 v[84:87], v162 offset:1024
	ds_read_b128 v[136:139], v162 offset:2048
	ds_read_b128 v[140:143], v162 offset:3072
	ds_read_b128 v[154:157], v163
	ds_read_b128 v[166:169], v163 offset:1024
	ds_read_b128 v[170:173], v163 offset:2048
	ds_read_b128 v[174:177], v163 offset:3072
	s_addc_u32 s87, s61, 0
	s_add_i32 s67, s96, s15
	s_add_i32 s64, s67, 0x2000
	s_add_u32 s82, s78, 0x10000
	s_addc_u32 s83, s79, 0
	s_add_i32 s66, s97, s15
	s_add_i32 s65, s66, 0x2000
	s_add_i32 s63, 0, 0x18000
	s_add_i32 s62, 0, 0x1c000
	s_add_u32 s74, s76, 0x10000
	s_addc_u32 s75, s77, 0
	s_add_i32 s61, s63, s15
	s_add_i32 s59, s61, 0x2000
	s_add_u32 s56, s78, 0x10080
	s_addc_u32 s57, s79, 0
	s_add_i32 s60, s62, s15
	s_add_i32 s58, s60, 0x2000
	s_mov_b32 m0, s88
	v_lshl_add_u64 v[212:213], s[86:87], 0, v[144:145]
	ds_read_b128 v[178:181], v164
	ds_read_b128 v[182:185], v164 offset:1024
	ds_read_b128 v[186:189], v164 offset:2048
	ds_read_b128 v[190:193], v164 offset:3072
	ds_read_b128 v[194:197], v164 offset:4096
	ds_read_b128 v[198:201], v164 offset:5120
	ds_read_b128 v[204:207], v164 offset:6144
	ds_read_b128 v[208:211], v164 offset:7168
	global_load_lds_dwordx4 v[212:213], off
	v_lshl_add_u64 v[212:213], s[86:87], 0, v[148:149]
	s_mov_b32 m0, s11
	s_nop 0
	global_load_lds_dwordx4 v[212:213], off
	s_waitcnt vmcnt(8)
	s_waitcnt lgkmcnt(0)
	s_barrier
	s_setprio 1
	v_mfma_f32_16x16x32_bf16 v[132:135], v[80:83], v[178:181], v[132:135]
	v_mfma_f32_16x16x32_bf16 v[128:131], v[136:139], v[178:181], v[128:131]
	v_mfma_f32_16x16x32_bf16 v[124:127], v[80:83], v[186:189], v[124:127]
	v_mfma_f32_16x16x32_bf16 v[120:123], v[136:139], v[186:189], v[120:123]
	v_mfma_f32_16x16x32_bf16 v[116:119], v[80:83], v[194:197], v[116:119]
	v_mfma_f32_16x16x32_bf16 v[112:115], v[136:139], v[194:197], v[112:115]
	v_mfma_f32_16x16x32_bf16 v[108:111], v[80:83], v[204:207], v[108:111]
	v_mfma_f32_16x16x32_bf16 v[104:107], v[136:139], v[204:207], v[104:107]
	v_mfma_f32_16x16x32_bf16 v[132:135], v[84:87], v[182:185], v[132:135]
	v_mfma_f32_16x16x32_bf16 v[128:131], v[140:143], v[182:185], v[128:131]
	v_mfma_f32_16x16x32_bf16 v[124:127], v[84:87], v[190:193], v[124:127]
	v_mfma_f32_16x16x32_bf16 v[120:123], v[140:143], v[190:193], v[120:123]
	v_mfma_f32_16x16x32_bf16 v[116:119], v[84:87], v[198:201], v[116:119]
	v_mfma_f32_16x16x32_bf16 v[112:115], v[140:143], v[198:201], v[112:115]
	v_mfma_f32_16x16x32_bf16 v[108:111], v[84:87], v[208:211], v[108:111]
	v_mfma_f32_16x16x32_bf16 v[104:107], v[140:143], v[208:211], v[104:107]
	v_mfma_f32_16x16x32_bf16 v[60:63], v[154:157], v[178:181], v[60:63]
	v_mfma_f32_16x16x32_bf16 v[56:59], v[170:173], v[178:181], v[56:59]
	v_mfma_f32_16x16x32_bf16 v[52:55], v[154:157], v[186:189], v[52:55]
	v_mfma_f32_16x16x32_bf16 v[48:51], v[170:173], v[186:189], v[48:51]
	v_mfma_f32_16x16x32_bf16 v[44:47], v[154:157], v[194:197], v[44:47]
	v_mfma_f32_16x16x32_bf16 v[40:43], v[170:173], v[194:197], v[40:43]
	v_mfma_f32_16x16x32_bf16 v[36:39], v[154:157], v[204:207], v[36:39]
	v_mfma_f32_16x16x32_bf16 v[32:35], v[170:173], v[204:207], v[32:35]
	v_mfma_f32_16x16x32_bf16 v[60:63], v[166:169], v[182:185], v[60:63]
	v_mfma_f32_16x16x32_bf16 v[56:59], v[174:177], v[182:185], v[56:59]
	v_mfma_f32_16x16x32_bf16 v[52:55], v[166:169], v[190:193], v[52:55]
	v_mfma_f32_16x16x32_bf16 v[48:51], v[174:177], v[190:193], v[48:51]
	v_mfma_f32_16x16x32_bf16 v[44:47], v[166:169], v[198:201], v[44:47]
	v_mfma_f32_16x16x32_bf16 v[40:43], v[174:177], v[198:201], v[40:43]
	v_mfma_f32_16x16x32_bf16 v[36:39], v[166:169], v[208:211], v[36:39]
	v_mfma_f32_16x16x32_bf16 v[32:35], v[174:177], v[208:211], v[32:35]
	s_setprio 0
	s_barrier
	s_mov_b32 m0, s67
	v_lshl_add_u64 v[212:213], s[78:79], 0, v[146:147]
	ds_read_b128 v[178:181], v164 offset:16384
	ds_read_b128 v[182:185], v164 offset:17408
	ds_read_b128 v[186:189], v164 offset:18432
	ds_read_b128 v[190:193], v164 offset:19456
	ds_read_b128 v[194:197], v164 offset:20480
	ds_read_b128 v[198:201], v164 offset:21504
	ds_read_b128 v[204:207], v164 offset:22528
	ds_read_b128 v[208:211], v164 offset:23552
	global_load_lds_dwordx4 v[212:213], off
	v_lshl_add_u64 v[214:215], s[78:79], 0, v[150:151]
	s_mov_b32 m0, s64
	v_lshl_add_u64 v[216:217], s[82:83], 0, v[146:147]
	global_load_lds_dwordx4 v[214:215], off
	s_mov_b32 m0, s66
	v_lshl_add_u64 v[218:219], s[76:77], 0, v[148:149]
	global_load_lds_dwordx4 v[216:217], off
	v_lshl_add_u64 v[216:217], s[82:83], 0, v[150:151]
	s_mov_b32 m0, s65
	s_nop 0
	global_load_lds_dwordx4 v[216:217], off
	v_lshl_add_u64 v[216:217], s[76:77], 0, v[144:145]
	s_mov_b32 m0, s10
	s_nop 0
	global_load_lds_dwordx4 v[216:217], off
	s_mov_b32 m0, s89
	s_nop 0
	global_load_lds_dwordx4 v[218:219], off
	s_waitcnt vmcnt(8)
	s_waitcnt lgkmcnt(0)
	s_barrier
; #define PG8_STAGE(bufoff, gbase, voff) do { _Pragma("unroll") for (int _i = 0; _i < 2; ++_i) \
;         __builtin_amdgcn_global_load_lds((const unsigned*)((const char*)(gbase) + (voff)[_i]), (LAS unsigned*)(lds + (bufoff) + ldsw + _i * 8192), 16, 0, 0); } while (0)
; #define PG8_LDA(dst, b, h) do { _Pragma("unroll") for (int m = 0; m < 4; ++m) _Pragma("unroll") for (int k = 0; k < 2; ++k) dst[m][k] = *(const LAS bf16x8*)(lds + PG8_SA(b, h) + aoff + m * 2048 + k * 1024); } while (0)
; #define PG8_LDB(dst, b, h) do { _Pragma("unroll") for (int n = 0; n < 2; ++n) _Pragma("unroll") for (int k = 0; k < 2; ++k) dst[n][k] = *(const LAS bf16x8*)(lds + PG8_SB(b, h) + boff + n * 2048 + k * 1024); } while (0)
; #define PG8_MMA(ai, bj, At, Bt) do { __builtin_amdgcn_s_setprio(1); _Pragma("unroll") for (int m = 0; m < 4; ++m) _Pragma("unroll") for (int n = 0; n < 2; ++n) _Pragma("unroll") for (int k = 0; k < 2; ++k) \
;         acc[ai][bj][m][n] = __builtin_amdgcn_mfma_f32_16x16x32_bf16(Bt[n][k], At[m][k], acc[ai][bj][m][n], 0, 0, 0); __builtin_amdgcn_s_setprio(0); } while (0)
; #define PG8_WAIT_V(n) asm volatile("s_waitcnt vmcnt(" #n ")" ::: "memory")
; #define PG8_WAIT_L(n) asm volatile("s_waitcnt lgkmcnt(" #n ")" ::: "memory")
; #define PG8_BAR __builtin_amdgcn_s_barrier()
; #define PG8_SCHED __builtin_amdgcn_sched_barrier(0)
; template <class Epi>
; __device__ __forceinline__ void gemm_phase(LAS unsigned char* lds, const Gemm g, const Sched& S, const Epi& E) {
;     ...
;             PG8_WAIT_V(8); PG8_WAIT_L(0); PG8_BAR; PG8_MMA(1, 0, At, B0); PG8_MMA(1, 1, At, B1); PG8_BAR; PG8_SCHED;
;             PG8_LDB(B0, 1, 0); PG8_LDB(B1, 1, 1); PG8_SCHED; PG8_LDA(At, 1, 0); PG8_STAGE(PG8_SA(0, 1), a2 + hstepA, voffA);
;             PG8_WAIT_V(8); PG8_WAIT_L(0); PG8_BAR; PG8_MMA(0, 0, At, B0); PG8_MMA(0, 1, At, B1); PG8_BAR; PG8_SCHED;
	s_setprio 1
	v_mfma_f32_16x16x32_bf16 v[100:103], v[80:83], v[178:181], v[100:103]
	v_mfma_f32_16x16x32_bf16 v[96:99], v[136:139], v[178:181], v[96:99]
	v_mfma_f32_16x16x32_bf16 v[92:95], v[80:83], v[186:189], v[92:95]
	v_mfma_f32_16x16x32_bf16 v[88:91], v[136:139], v[186:189], v[88:91]
	v_mfma_f32_16x16x32_bf16 v[76:79], v[80:83], v[194:197], v[76:79]
	v_mfma_f32_16x16x32_bf16 v[72:75], v[136:139], v[194:197], v[72:75]
	v_mfma_f32_16x16x32_bf16 v[68:71], v[80:83], v[204:207], v[68:71]
	v_mfma_f32_16x16x32_bf16 v[64:67], v[136:139], v[204:207], v[64:67]
	v_mfma_f32_16x16x32_bf16 v[100:103], v[84:87], v[182:185], v[100:103]
	v_mfma_f32_16x16x32_bf16 v[96:99], v[140:143], v[182:185], v[96:99]
	v_mfma_f32_16x16x32_bf16 v[92:95], v[84:87], v[190:193], v[92:95]
	v_mfma_f32_16x16x32_bf16 v[88:91], v[140:143], v[190:193], v[88:91]
	v_mfma_f32_16x16x32_bf16 v[76:79], v[84:87], v[198:201], v[76:79]
	v_mfma_f32_16x16x32_bf16 v[72:75], v[140:143], v[198:201], v[72:75]
	v_mfma_f32_16x16x32_bf16 v[68:71], v[84:87], v[208:211], v[68:71]
	v_mfma_f32_16x16x32_bf16 v[64:67], v[140:143], v[208:211], v[64:67]
	v_mfma_f32_16x16x32_bf16 v[28:31], v[154:157], v[178:181], v[28:31]
	v_mfma_f32_16x16x32_bf16 v[24:27], v[170:173], v[178:181], v[24:27]
	v_mfma_f32_16x16x32_bf16 v[20:23], v[154:157], v[186:189], v[20:23]
	v_mfma_f32_16x16x32_bf16 v[16:19], v[170:173], v[186:189], v[16:19]
	v_mfma_f32_16x16x32_bf16 v[12:15], v[154:157], v[194:197], v[12:15]
	v_mfma_f32_16x16x32_bf16 v[8:11], v[170:173], v[194:197], v[8:11]
	v_mfma_f32_16x16x32_bf16 v[4:7], v[154:157], v[204:207], v[4:7]
	v_mfma_f32_16x16x32_bf16 v[0:3], v[170:173], v[204:207], v[0:3]
	v_mfma_f32_16x16x32_bf16 v[28:31], v[166:169], v[182:185], v[28:31]
	v_mfma_f32_16x16x32_bf16 v[24:27], v[174:177], v[182:185], v[24:27]
	v_mfma_f32_16x16x32_bf16 v[20:23], v[166:169], v[190:193], v[20:23]
	v_mfma_f32_16x16x32_bf16 v[16:19], v[174:177], v[190:193], v[16:19]
	v_mfma_f32_16x16x32_bf16 v[12:15], v[166:169], v[198:201], v[12:15]
	v_mfma_f32_16x16x32_bf16 v[8:11], v[174:177], v[198:201], v[8:11]
	v_mfma_f32_16x16x32_bf16 v[4:7], v[166:169], v[208:211], v[4:7]
	v_mfma_f32_16x16x32_bf16 v[0:3], v[174:177], v[208:211], v[0:3]
	s_setprio 0
	s_barrier
	v_add_u32_e32 v140, s63, v160
	v_add_u32_e32 v152, s62, v160
	ds_read_b128 v[80:83], v140
	ds_read_b128 v[84:87], v140 offset:1024
	ds_read_b128 v[136:139], v140 offset:2048
	ds_read_b128 v[140:143], v140 offset:3072
	ds_read_b128 v[154:157], v152
	ds_read_b128 v[166:169], v152 offset:1024
	ds_read_b128 v[170:173], v152 offset:2048
	ds_read_b128 v[174:177], v152 offset:3072
	s_mov_b32 m0, s90
	v_lshl_add_u64 v[220:221], s[74:75], 0, v[144:145]
	ds_read_b128 v[178:181], v164 offset:32768
	ds_read_b128 v[182:185], v164 offset:33792
	ds_read_b128 v[186:189], v164 offset:34816
	ds_read_b128 v[190:193], v164 offset:35840
	ds_read_b128 v[194:197], v164 offset:36864
	ds_read_b128 v[198:201], v164 offset:37888
	ds_read_b128 v[204:207], v164 offset:38912
	ds_read_b128 v[208:211], v164 offset:39936
	global_load_lds_dwordx4 v[220:221], off
	v_lshl_add_u64 v[220:221], s[74:75], 0, v[148:149]
	s_mov_b32 m0, s91
	s_nop 0
	global_load_lds_dwordx4 v[220:221], off
	s_waitcnt vmcnt(8)
	s_waitcnt lgkmcnt(0)
	s_barrier
	s_setprio 1
	v_mfma_f32_16x16x32_bf16 v[132:135], v[80:83], v[178:181], v[132:135]
	v_mfma_f32_16x16x32_bf16 v[128:131], v[136:139], v[178:181], v[128:131]
	v_mfma_f32_16x16x32_bf16 v[124:127], v[80:83], v[186:189], v[124:127]
	v_mfma_f32_16x16x32_bf16 v[120:123], v[136:139], v[186:189], v[120:123]
	v_mfma_f32_16x16x32_bf16 v[116:119], v[80:83], v[194:197], v[116:119]
	v_mfma_f32_16x16x32_bf16 v[112:115], v[136:139], v[194:197], v[112:115]
	v_mfma_f32_16x16x32_bf16 v[108:111], v[80:83], v[204:207], v[108:111]
	v_mfma_f32_16x16x32_bf16 v[104:107], v[136:139], v[204:207], v[104:107]
	v_mfma_f32_16x16x32_bf16 v[132:135], v[84:87], v[182:185], v[132:135]
	v_mfma_f32_16x16x32_bf16 v[128:131], v[140:143], v[182:185], v[128:131]
	v_mfma_f32_16x16x32_bf16 v[124:127], v[84:87], v[190:193], v[124:127]
	v_mfma_f32_16x16x32_bf16 v[120:123], v[140:143], v[190:193], v[120:123]
	v_mfma_f32_16x16x32_bf16 v[116:119], v[84:87], v[198:201], v[116:119]
	v_mfma_f32_16x16x32_bf16 v[112:115], v[140:143], v[198:201], v[112:115]
	v_mfma_f32_16x16x32_bf16 v[108:111], v[84:87], v[208:211], v[108:111]
	v_mfma_f32_16x16x32_bf16 v[104:107], v[140:143], v[208:211], v[104:107]
	v_mfma_f32_16x16x32_bf16 v[60:63], v[154:157], v[178:181], v[60:63]
	v_mfma_f32_16x16x32_bf16 v[56:59], v[170:173], v[178:181], v[56:59]
	v_mfma_f32_16x16x32_bf16 v[52:55], v[154:157], v[186:189], v[52:55]
	v_mfma_f32_16x16x32_bf16 v[48:51], v[170:173], v[186:189], v[48:51]
	v_mfma_f32_16x16x32_bf16 v[44:47], v[154:157], v[194:197], v[44:47]
	v_mfma_f32_16x16x32_bf16 v[40:43], v[170:173], v[194:197], v[40:43]
	v_mfma_f32_16x16x32_bf16 v[36:39], v[154:157], v[204:207], v[36:39]
	v_mfma_f32_16x16x32_bf16 v[32:35], v[170:173], v[204:207], v[32:35]
	v_mfma_f32_16x16x32_bf16 v[60:63], v[166:169], v[182:185], v[60:63]
	v_mfma_f32_16x16x32_bf16 v[56:59], v[174:177], v[182:185], v[56:59]
	v_mfma_f32_16x16x32_bf16 v[52:55], v[166:169], v[190:193], v[52:55]
	v_mfma_f32_16x16x32_bf16 v[48:51], v[174:177], v[190:193], v[48:51]
	v_mfma_f32_16x16x32_bf16 v[44:47], v[166:169], v[198:201], v[44:47]
	v_mfma_f32_16x16x32_bf16 v[40:43], v[174:177], v[198:201], v[40:43]
	v_mfma_f32_16x16x32_bf16 v[36:39], v[166:169], v[208:211], v[36:39]
	v_mfma_f32_16x16x32_bf16 v[32:35], v[174:177], v[208:211], v[32:35]
	s_setprio 0
	s_barrier
; #define PG8_STAGE(bufoff, gbase, voff) do { _Pragma("unroll") for (int _i = 0; _i < 2; ++_i) \
;         __builtin_amdgcn_global_load_lds((const unsigned*)((const char*)(gbase) + (voff)[_i]), (LAS unsigned*)(lds + (bufoff) + ldsw + _i * 8192), 16, 0, 0); } while (0)
; #define PG8_LDA(dst, b, h) do { _Pragma("unroll") for (int m = 0; m < 4; ++m) _Pragma("unroll") for (int k = 0; k < 2; ++k) dst[m][k] = *(const LAS bf16x8*)(lds + PG8_SA(b, h) + aoff + m * 2048 + k * 1024); } while (0)
; #define PG8_MMA(ai, bj, At, Bt) do { __builtin_amdgcn_s_setprio(1); _Pragma("unroll") for (int m = 0; m < 4; ++m) _Pragma("unroll") for (int n = 0; n < 2; ++n) _Pragma("unroll") for (int k = 0; k < 2; ++k) \
;         acc[ai][bj][m][n] = __builtin_amdgcn_mfma_f32_16x16x32_bf16(Bt[n][k], At[m][k], acc[ai][bj][m][n], 0, 0, 0); __builtin_amdgcn_s_setprio(0); } while (0)
; #define PG8_WAIT_V(n) asm volatile("s_waitcnt vmcnt(" #n ")" ::: "memory")
; #define PG8_WAIT_L(n) asm volatile("s_waitcnt lgkmcnt(" #n ")" ::: "memory")
; #define PG8_BAR __builtin_amdgcn_s_barrier()
; #define PG8_SCHED __builtin_amdgcn_sched_barrier(0)
; template <class Epi>
; __device__ __forceinline__ void gemm_phase(LAS unsigned char* lds, const Gemm g, const Sched& S, const Epi& E) {
;     ...
;             PG8_LDA(At, 1, 1); PG8_STAGE(PG8_SB(1, 0), b3, voffB); PG8_STAGE(PG8_SB(1, 1), b3 + hstepB, voffB); PG8_STAGE(PG8_SA(1, 0), a3, voffA);
;             PG8_WAIT_V(8); PG8_WAIT_L(0); PG8_BAR; PG8_MMA(1, 0, At, B0); PG8_MMA(1, 1, At, B1); PG8_BAR; PG8_SCHED;
;         }
;         if (wr == 0) PG8_BAR;
	s_mov_b32 m0, s61
	v_lshl_add_u64 v[212:213], v[212:213], 0, s[6:7]
	ds_read_b128 v[178:181], v164 offset:49152
	ds_read_b128 v[182:185], v164 offset:50176
	ds_read_b128 v[186:189], v164 offset:51200
	ds_read_b128 v[190:193], v164 offset:52224
	ds_read_b128 v[194:197], v164 offset:53248
	ds_read_b128 v[198:201], v164 offset:54272
	ds_read_b128 v[204:207], v164 offset:55296
	ds_read_b128 v[208:211], v164 offset:56320
	global_load_lds_dwordx4 v[212:213], off
	v_lshl_add_u64 v[212:213], v[214:215], 0, s[6:7]
	s_mov_b32 m0, s59
	s_nop 0
	global_load_lds_dwordx4 v[212:213], off
	v_lshl_add_u64 v[212:213], s[56:57], 0, v[146:147]
	s_mov_b32 m0, s60
	s_nop 0
	global_load_lds_dwordx4 v[212:213], off
	v_lshl_add_u64 v[212:213], s[56:57], 0, v[150:151]
	s_mov_b32 m0, s58
	s_nop 0
	global_load_lds_dwordx4 v[212:213], off
	v_lshl_add_u64 v[212:213], v[216:217], 0, s[6:7]
	s_mov_b32 m0, s94
	s_nop 0
	global_load_lds_dwordx4 v[212:213], off
	v_lshl_add_u64 v[212:213], v[218:219], 0, s[6:7]
	s_mov_b32 m0, s95
	s_nop 0
	global_load_lds_dwordx4 v[212:213], off
	s_waitcnt vmcnt(8)
	s_waitcnt lgkmcnt(0)
	s_barrier
	s_setprio 1
	v_mfma_f32_16x16x32_bf16 v[100:103], v[80:83], v[178:181], v[100:103]
	v_mfma_f32_16x16x32_bf16 v[96:99], v[136:139], v[178:181], v[96:99]
	v_mfma_f32_16x16x32_bf16 v[92:95], v[80:83], v[186:189], v[92:95]
	v_mfma_f32_16x16x32_bf16 v[88:91], v[136:139], v[186:189], v[88:91]
	v_mfma_f32_16x16x32_bf16 v[76:79], v[80:83], v[194:197], v[76:79]
	v_mfma_f32_16x16x32_bf16 v[72:75], v[136:139], v[194:197], v[72:75]
	v_mfma_f32_16x16x32_bf16 v[68:71], v[80:83], v[204:207], v[68:71]
	v_mfma_f32_16x16x32_bf16 v[64:67], v[136:139], v[204:207], v[64:67]
	v_mfma_f32_16x16x32_bf16 v[100:103], v[84:87], v[182:185], v[100:103]
	v_mfma_f32_16x16x32_bf16 v[96:99], v[140:143], v[182:185], v[96:99]
	v_mfma_f32_16x16x32_bf16 v[92:95], v[84:87], v[190:193], v[92:95]
	v_mfma_f32_16x16x32_bf16 v[88:91], v[140:143], v[190:193], v[88:91]
	v_mfma_f32_16x16x32_bf16 v[76:79], v[84:87], v[198:201], v[76:79]
	v_mfma_f32_16x16x32_bf16 v[72:75], v[140:143], v[198:201], v[72:75]
	v_mfma_f32_16x16x32_bf16 v[68:71], v[84:87], v[208:211], v[68:71]
	v_mfma_f32_16x16x32_bf16 v[64:67], v[140:143], v[208:211], v[64:67]
	v_mfma_f32_16x16x32_bf16 v[28:31], v[154:157], v[178:181], v[28:31]
	v_mfma_f32_16x16x32_bf16 v[24:27], v[170:173], v[178:181], v[24:27]
	v_mfma_f32_16x16x32_bf16 v[20:23], v[154:157], v[186:189], v[20:23]
	v_mfma_f32_16x16x32_bf16 v[16:19], v[170:173], v[186:189], v[16:19]
	v_mfma_f32_16x16x32_bf16 v[12:15], v[154:157], v[194:197], v[12:15]
	v_mfma_f32_16x16x32_bf16 v[8:11], v[170:173], v[194:197], v[8:11]
	v_mfma_f32_16x16x32_bf16 v[4:7], v[154:157], v[204:207], v[4:7]
	v_mfma_f32_16x16x32_bf16 v[0:3], v[170:173], v[204:207], v[0:3]
	v_mfma_f32_16x16x32_bf16 v[28:31], v[166:169], v[182:185], v[28:31]
	v_mfma_f32_16x16x32_bf16 v[24:27], v[174:177], v[182:185], v[24:27]
	v_mfma_f32_16x16x32_bf16 v[20:23], v[166:169], v[190:193], v[20:23]
	v_mfma_f32_16x16x32_bf16 v[16:19], v[174:177], v[190:193], v[16:19]
	v_mfma_f32_16x16x32_bf16 v[12:15], v[166:169], v[198:201], v[12:15]
	v_mfma_f32_16x16x32_bf16 v[8:11], v[174:177], v[198:201], v[8:11]
	v_mfma_f32_16x16x32_bf16 v[4:7], v[166:169], v[208:211], v[4:7]
	v_mfma_f32_16x16x32_bf16 v[0:3], v[174:177], v[208:211], v[0:3]
	s_setprio 0
	s_barrier
	s_andn2_b64 vcc, exec, s[54:55]
	s_mov_b64 s[56:57], -1
	s_mov_b64 s[54:55], 0
	s_mov_b64 s[74:75], 0x100
	s_cbranch_vccz .LBB0_773
	s_and_b64 vcc, exec, s[8:9]
	s_cbranch_vccz .LBB0_776
	s_barrier

; #define PG8_STAGE(bufoff, gbase, voff) do { _Pragma("unroll") for (int _i = 0; _i < 2; ++_i) \
;         __builtin_amdgcn_global_load_lds((const unsigned*)((const char*)(gbase) + (voff)[_i]), (LAS unsigned*)(lds + (bufoff) + ldsw + _i * 8192), 16, 0, 0); } while (0)
; #define PG8_LDA(dst, b, h) do { _Pragma("unroll") for (int m = 0; m < 4; ++m) _Pragma("unroll") for (int k = 0; k < 2; ++k) dst[m][k] = *(const LAS bf16x8*)(lds + PG8_SA(b, h) + aoff + m * 2048 + k * 1024); } while (0)
; #define PG8_LDB(dst, b, h) do { _Pragma("unroll") for (int n = 0; n < 2; ++n) _Pragma("unroll") for (int k = 0; k < 2; ++k) dst[n][k] = *(const LAS bf16x8*)(lds + PG8_SB(b, h) + boff + n * 2048 + k * 1024); } while (0)
; #define PG8_MMA(ai, bj, At, Bt) do { __builtin_amdgcn_s_setprio(1); _Pragma("unroll") for (int m = 0; m < 4; ++m) _Pragma("unroll") for (int n = 0; n < 2; ++n) _Pragma("unroll") for (int k = 0; k < 2; ++k) \
;         acc[ai][bj][m][n] = __builtin_amdgcn_mfma_f32_16x16x32_bf16(Bt[n][k], At[m][k], acc[ai][bj][m][n], 0, 0, 0); __builtin_amdgcn_s_setprio(0); } while (0)
; #define PG8_BAR __builtin_amdgcn_s_barrier()
; template <class Epi>
; __device__ __forceinline__ void gemm_phase(LAS unsigned char* lds, const Gemm g, const Sched& S, const Epi& E) {
;     ...
;         const bool has_next = S.next(ui + 1, nxt);
;         const char* nA = has_next ? (const char*)g.A + (size_t)S.aoff(nxt) * 2 : cA; const char* nB = has_next ? (const char*)g.Bt + (size_t)S.boff(nxt) * 2 : cB;
;         _Pragma("nounroll")
;         for (int t = 0; t < nt; t += 2) {
;             const bool last = (t == nt - 2);
;             const char* a1 = cA + (size_t)(t + 1) * kstep;
;             const char* a2 = last ? nA : cA + (size_t)(t + 2) * kstep; const char* b2 = last ? nB : cB + (size_t)(t + 2) * kstep;
;             const char* a3 = a2 + kstep; const char* b3 = b2 + kstep;
;             PG8_LDB(B0, 0, 0); PG8_LDB(B1, 0, 1); PG8_SCHED; PG8_LDA(At, 0, 0); PG8_STAGE(PG8_SA(1, 1), a1 + hstepA, voffA);
;             PG8_WAIT_V(8); PG8_WAIT_L(0); PG8_BAR; PG8_MMA(0, 0, At, B0); PG8_MMA(0, 1, At, B1); PG8_BAR; PG8_SCHED;
;             PG8_LDA(At, 0, 1); PG8_STAGE(PG8_SB(0, 0), b2, voffB); PG8_STAGE(PG8_SB(0, 1), b2 + hstepB, voffB); PG8_STAGE(PG8_SA(0, 0), a2, voffA);
;             PG8_WAIT_V(8); PG8_WAIT_L(0); PG8_BAR; PG8_MMA(1, 0, At, B0); PG8_MMA(1, 1, At, B1); PG8_BAR; PG8_SCHED;
.LBB0_900:
	s_add_u32 s57, s4, s78
	s_addc_u32 s64, s5, s79
	s_add_u32 s65, s57, 0x100
	s_addc_u32 s66, s64, 0
	s_and_b64 s[62:63], s[14:15], exec
	s_cselect_b32 s83, s75, s66
	s_cselect_b32 s82, s74, s65
	s_add_u32 s62, s6, s78
	s_addc_u32 s63, s7, s79
	s_add_u32 s62, s62, 0x100
	s_addc_u32 s63, s63, 0
	s_and_b64 s[14:15], s[14:15], exec
	s_cselect_b32 s87, s1, s63
	s_cselect_b32 s86, s55, s62
	s_add_u32 s90, s57, 0x40080
	ds_read_b128 v[96:99], v155
	ds_read_b128 v[100:103], v155 offset:1024
	ds_read_b128 v[144:147], v155 offset:2048
	ds_read_b128 v[148:151], v155 offset:3072
	ds_read_b128 v[160:163], v156
	ds_read_b128 v[164:167], v156 offset:1024
	ds_read_b128 v[168:171], v156 offset:2048
	ds_read_b128 v[172:175], v156 offset:3072
	s_addc_u32 s91, s64, 0
	s_add_i32 s67, s59, s10
	s_add_i32 m0, s11, 0xc000
	s_add_i32 s85, s11, 0xe000
	s_add_i32 s84, s67, 0x2000
	s_add_u32 s88, s86, 0x10000
	s_addc_u32 s89, s87, 0
	s_add_i32 vcc_hi, s60, s10
	s_add_i32 vcc_lo, vcc_hi, 0x2000
	s_add_i32 s66, 0, 0x18000
	s_add_i32 s65, 0, 0x1c000
	s_add_u32 s78, s82, 0x40000
	s_addc_u32 s79, s83, 0
	s_add_i32 s64, s66, s10
	s_add_i32 s62, s64, 0x2000
	s_add_u32 s14, s86, 0x10080
	s_addc_u32 s15, s87, 0
	s_add_i32 s63, s65, s10
	s_add_i32 s57, s63, 0x2000
	v_lshl_add_u64 v[200:201], s[90:91], 0, v[136:137]
	ds_read_b128 v[176:179], v157
	ds_read_b128 v[180:183], v157 offset:1024
	ds_read_b128 v[184:187], v157 offset:2048
	ds_read_b128 v[188:191], v157 offset:3072
	ds_read_b128 v[192:195], v157 offset:4096
	ds_read_b128 v[196:199], v157 offset:5120
	ds_read_b128 v[204:207], v157 offset:6144
	ds_read_b128 v[208:211], v157 offset:7168
	global_load_lds_dwordx4 v[200:201], off
	v_lshl_add_u64 v[200:201], s[90:91], 0, v[140:141]
	s_mov_b32 m0, s85
	s_nop 0
	global_load_lds_dwordx4 v[200:201], off
	s_waitcnt vmcnt(8)
	s_waitcnt lgkmcnt(0)
	s_barrier
	s_setprio 1
	v_mfma_f32_16x16x32_bf16 v[132:135], v[96:99], v[176:179], v[132:135]
	v_mfma_f32_16x16x32_bf16 v[128:131], v[144:147], v[176:179], v[128:131]
	v_mfma_f32_16x16x32_bf16 v[124:127], v[96:99], v[184:187], v[124:127]
	v_mfma_f32_16x16x32_bf16 v[120:123], v[144:147], v[184:187], v[120:123]
	v_mfma_f32_16x16x32_bf16 v[116:119], v[96:99], v[192:195], v[116:119]
	v_mfma_f32_16x16x32_bf16 v[112:115], v[144:147], v[192:195], v[112:115]
	v_mfma_f32_16x16x32_bf16 v[108:111], v[96:99], v[204:207], v[108:111]
	v_mfma_f32_16x16x32_bf16 v[104:107], v[144:147], v[204:207], v[104:107]
	v_mfma_f32_16x16x32_bf16 v[132:135], v[100:103], v[180:183], v[132:135]
	v_mfma_f32_16x16x32_bf16 v[128:131], v[148:151], v[180:183], v[128:131]
	v_mfma_f32_16x16x32_bf16 v[124:127], v[100:103], v[188:191], v[124:127]
	v_mfma_f32_16x16x32_bf16 v[120:123], v[148:151], v[188:191], v[120:123]
	v_mfma_f32_16x16x32_bf16 v[116:119], v[100:103], v[196:199], v[116:119]
	v_mfma_f32_16x16x32_bf16 v[112:115], v[148:151], v[196:199], v[112:115]
	v_mfma_f32_16x16x32_bf16 v[108:111], v[100:103], v[208:211], v[108:111]
	v_mfma_f32_16x16x32_bf16 v[104:107], v[148:151], v[208:211], v[104:107]
	v_mfma_f32_16x16x32_bf16 v[60:63], v[160:163], v[176:179], v[60:63]
	v_mfma_f32_16x16x32_bf16 v[56:59], v[168:171], v[176:179], v[56:59]
	v_mfma_f32_16x16x32_bf16 v[52:55], v[160:163], v[184:187], v[52:55]
	v_mfma_f32_16x16x32_bf16 v[48:51], v[168:171], v[184:187], v[48:51]
	v_mfma_f32_16x16x32_bf16 v[44:47], v[160:163], v[192:195], v[44:47]
	v_mfma_f32_16x16x32_bf16 v[40:43], v[168:171], v[192:195], v[40:43]
	v_mfma_f32_16x16x32_bf16 v[36:39], v[160:163], v[204:207], v[36:39]
	v_mfma_f32_16x16x32_bf16 v[32:35], v[168:171], v[204:207], v[32:35]
	v_mfma_f32_16x16x32_bf16 v[60:63], v[164:167], v[180:183], v[60:63]
	v_mfma_f32_16x16x32_bf16 v[56:59], v[172:175], v[180:183], v[56:59]
	v_mfma_f32_16x16x32_bf16 v[52:55], v[164:167], v[188:191], v[52:55]
	v_mfma_f32_16x16x32_bf16 v[48:51], v[172:175], v[188:191], v[48:51]
	v_mfma_f32_16x16x32_bf16 v[44:47], v[164:167], v[196:199], v[44:47]
	v_mfma_f32_16x16x32_bf16 v[40:43], v[172:175], v[196:199], v[40:43]
	v_mfma_f32_16x16x32_bf16 v[36:39], v[164:167], v[208:211], v[36:39]
	v_mfma_f32_16x16x32_bf16 v[32:35], v[172:175], v[208:211], v[32:35]
	s_setprio 0
	s_barrier
	s_mov_b32 m0, s67
	v_lshl_add_u64 v[200:201], s[86:87], 0, v[138:139]
	ds_read_b128 v[176:179], v157 offset:16384
	ds_read_b128 v[180:183], v157 offset:17408
	ds_read_b128 v[184:187], v157 offset:18432
	ds_read_b128 v[188:191], v157 offset:19456
	ds_read_b128 v[192:195], v157 offset:20480
	ds_read_b128 v[196:199], v157 offset:21504
	ds_read_b128 v[204:207], v157 offset:22528
	ds_read_b128 v[208:211], v157 offset:23552
	global_load_lds_dwordx4 v[200:201], off
	v_lshl_add_u64 v[212:213], s[86:87], 0, v[142:143]
	s_mov_b32 m0, s84
	v_lshl_add_u64 v[214:215], s[88:89], 0, v[138:139]
	global_load_lds_dwordx4 v[212:213], off
	s_mov_b32 m0, vcc_hi
	v_lshl_add_u64 v[216:217], s[82:83], 0, v[140:141]
	global_load_lds_dwordx4 v[214:215], off
	v_lshl_add_u64 v[214:215], s[88:89], 0, v[142:143]
	s_mov_b32 m0, vcc_lo
	s_nop 0
	global_load_lds_dwordx4 v[214:215], off
	v_lshl_add_u64 v[214:215], s[82:83], 0, v[136:137]
	s_mov_b32 m0, s11
	s_nop 0
	global_load_lds_dwordx4 v[214:215], off
	s_mov_b32 m0, s93
	s_nop 0
	global_load_lds_dwordx4 v[216:217], off
	s_waitcnt vmcnt(8)
	s_waitcnt lgkmcnt(0)
	s_barrier
; #define PG8_STAGE(bufoff, gbase, voff) do { _Pragma("unroll") for (int _i = 0; _i < 2; ++_i) \
;         __builtin_amdgcn_global_load_lds((const unsigned*)((const char*)(gbase) + (voff)[_i]), (LAS unsigned*)(lds + (bufoff) + ldsw + _i * 8192), 16, 0, 0); } while (0)
; #define PG8_LDA(dst, b, h) do { _Pragma("unroll") for (int m = 0; m < 4; ++m) _Pragma("unroll") for (int k = 0; k < 2; ++k) dst[m][k] = *(const LAS bf16x8*)(lds + PG8_SA(b, h) + aoff + m * 2048 + k * 1024); } while (0)
; #define PG8_LDB(dst, b, h) do { _Pragma("unroll") for (int n = 0; n < 2; ++n) _Pragma("unroll") for (int k = 0; k < 2; ++k) dst[n][k] = *(const LAS bf16x8*)(lds + PG8_SB(b, h) + boff + n * 2048 + k * 1024); } while (0)
; #define PG8_MMA(ai, bj, At, Bt) do { __builtin_amdgcn_s_setprio(1); _Pragma("unroll") for (int m = 0; m < 4; ++m) _Pragma("unroll") for (int n = 0; n < 2; ++n) _Pragma("unroll") for (int k = 0; k < 2; ++k) \
;         acc[ai][bj][m][n] = __builtin_amdgcn_mfma_f32_16x16x32_bf16(Bt[n][k], At[m][k], acc[ai][bj][m][n], 0, 0, 0); __builtin_amdgcn_s_setprio(0); } while (0)
; #define PG8_WAIT_V(n) asm volatile("s_waitcnt vmcnt(" #n ")" ::: "memory")
; #define PG8_WAIT_L(n) asm volatile("s_waitcnt lgkmcnt(" #n ")" ::: "memory")
; #define PG8_BAR __builtin_amdgcn_s_barrier()
; #define PG8_SCHED __builtin_amdgcn_sched_barrier(0)
; template <class Epi>
; __device__ __forceinline__ void gemm_phase(LAS unsigned char* lds, const Gemm g, const Sched& S, const Epi& E) {
;     ...
;             PG8_WAIT_V(8); PG8_WAIT_L(0); PG8_BAR; PG8_MMA(1, 0, At, B0); PG8_MMA(1, 1, At, B1); PG8_BAR; PG8_SCHED;
;             PG8_LDB(B0, 1, 0); PG8_LDB(B1, 1, 1); PG8_SCHED; PG8_LDA(At, 1, 0); PG8_STAGE(PG8_SA(0, 1), a2 + hstepA, voffA);
;             PG8_WAIT_V(8); PG8_WAIT_L(0); PG8_BAR; PG8_MMA(0, 0, At, B0); PG8_MMA(0, 1, At, B1); PG8_BAR; PG8_SCHED;
	s_setprio 1
	v_mfma_f32_16x16x32_bf16 v[92:95], v[96:99], v[176:179], v[92:95]
	v_mfma_f32_16x16x32_bf16 v[88:91], v[144:147], v[176:179], v[88:91]
	v_mfma_f32_16x16x32_bf16 v[84:87], v[96:99], v[184:187], v[84:87]
	v_mfma_f32_16x16x32_bf16 v[80:83], v[144:147], v[184:187], v[80:83]
	v_mfma_f32_16x16x32_bf16 v[76:79], v[96:99], v[192:195], v[76:79]
	v_mfma_f32_16x16x32_bf16 v[72:75], v[144:147], v[192:195], v[72:75]
	v_mfma_f32_16x16x32_bf16 v[68:71], v[96:99], v[204:207], v[68:71]
	v_mfma_f32_16x16x32_bf16 v[64:67], v[144:147], v[204:207], v[64:67]
	v_mfma_f32_16x16x32_bf16 v[92:95], v[100:103], v[180:183], v[92:95]
	v_mfma_f32_16x16x32_bf16 v[88:91], v[148:151], v[180:183], v[88:91]
	v_mfma_f32_16x16x32_bf16 v[84:87], v[100:103], v[188:191], v[84:87]
	v_mfma_f32_16x16x32_bf16 v[80:83], v[148:151], v[188:191], v[80:83]
	v_mfma_f32_16x16x32_bf16 v[76:79], v[100:103], v[196:199], v[76:79]
	v_mfma_f32_16x16x32_bf16 v[72:75], v[148:151], v[196:199], v[72:75]
	v_mfma_f32_16x16x32_bf16 v[68:71], v[100:103], v[208:211], v[68:71]
	v_mfma_f32_16x16x32_bf16 v[64:67], v[148:151], v[208:211], v[64:67]
	v_mfma_f32_16x16x32_bf16 v[28:31], v[160:163], v[176:179], v[28:31]
	v_mfma_f32_16x16x32_bf16 v[24:27], v[168:171], v[176:179], v[24:27]
	v_mfma_f32_16x16x32_bf16 v[20:23], v[160:163], v[184:187], v[20:23]
	v_mfma_f32_16x16x32_bf16 v[16:19], v[168:171], v[184:187], v[16:19]
	v_mfma_f32_16x16x32_bf16 v[12:15], v[160:163], v[192:195], v[12:15]
	v_mfma_f32_16x16x32_bf16 v[8:11], v[168:171], v[192:195], v[8:11]
	v_mfma_f32_16x16x32_bf16 v[4:7], v[160:163], v[204:207], v[4:7]
	v_mfma_f32_16x16x32_bf16 v[0:3], v[168:171], v[204:207], v[0:3]
	v_mfma_f32_16x16x32_bf16 v[28:31], v[164:167], v[180:183], v[28:31]
	v_mfma_f32_16x16x32_bf16 v[24:27], v[172:175], v[180:183], v[24:27]
	v_mfma_f32_16x16x32_bf16 v[20:23], v[164:167], v[188:191], v[20:23]
	v_mfma_f32_16x16x32_bf16 v[16:19], v[172:175], v[188:191], v[16:19]
	v_mfma_f32_16x16x32_bf16 v[12:15], v[164:167], v[196:199], v[12:15]
	v_mfma_f32_16x16x32_bf16 v[8:11], v[172:175], v[196:199], v[8:11]
	v_mfma_f32_16x16x32_bf16 v[4:7], v[164:167], v[208:211], v[4:7]
	v_mfma_f32_16x16x32_bf16 v[0:3], v[172:175], v[208:211], v[0:3]
	s_setprio 0
	s_barrier
	v_add_u32_e32 v148, s66, v153
	v_add_u32_e32 v159, s65, v153
	ds_read_b128 v[96:99], v148
	ds_read_b128 v[100:103], v148 offset:1024
	ds_read_b128 v[144:147], v148 offset:2048
	ds_read_b128 v[148:151], v148 offset:3072
	ds_read_b128 v[160:163], v159
	ds_read_b128 v[164:167], v159 offset:1024
	ds_read_b128 v[168:171], v159 offset:2048
	ds_read_b128 v[172:175], v159 offset:3072
	s_mov_b32 m0, s94
	v_lshl_add_u64 v[218:219], s[78:79], 0, v[136:137]
	ds_read_b128 v[176:179], v157 offset:32768
	ds_read_b128 v[180:183], v157 offset:33792
	ds_read_b128 v[184:187], v157 offset:34816
	ds_read_b128 v[188:191], v157 offset:35840
	ds_read_b128 v[192:195], v157 offset:36864
	ds_read_b128 v[196:199], v157 offset:37888
	ds_read_b128 v[204:207], v157 offset:38912
	ds_read_b128 v[208:211], v157 offset:39936
	global_load_lds_dwordx4 v[218:219], off
	v_lshl_add_u64 v[218:219], s[78:79], 0, v[140:141]
	s_mov_b32 m0, s95
	s_nop 0
	global_load_lds_dwordx4 v[218:219], off
	s_waitcnt vmcnt(8)
	s_waitcnt lgkmcnt(0)
	s_barrier
	s_setprio 1
	v_mfma_f32_16x16x32_bf16 v[132:135], v[96:99], v[176:179], v[132:135]
	v_mfma_f32_16x16x32_bf16 v[128:131], v[144:147], v[176:179], v[128:131]
	v_mfma_f32_16x16x32_bf16 v[124:127], v[96:99], v[184:187], v[124:127]
	v_mfma_f32_16x16x32_bf16 v[120:123], v[144:147], v[184:187], v[120:123]
	v_mfma_f32_16x16x32_bf16 v[116:119], v[96:99], v[192:195], v[116:119]
	v_mfma_f32_16x16x32_bf16 v[112:115], v[144:147], v[192:195], v[112:115]
	v_mfma_f32_16x16x32_bf16 v[108:111], v[96:99], v[204:207], v[108:111]
	v_mfma_f32_16x16x32_bf16 v[104:107], v[144:147], v[204:207], v[104:107]
	v_mfma_f32_16x16x32_bf16 v[132:135], v[100:103], v[180:183], v[132:135]
	v_mfma_f32_16x16x32_bf16 v[128:131], v[148:151], v[180:183], v[128:131]
	v_mfma_f32_16x16x32_bf16 v[124:127], v[100:103], v[188:191], v[124:127]
	v_mfma_f32_16x16x32_bf16 v[120:123], v[148:151], v[188:191], v[120:123]
	v_mfma_f32_16x16x32_bf16 v[116:119], v[100:103], v[196:199], v[116:119]
	v_mfma_f32_16x16x32_bf16 v[112:115], v[148:151], v[196:199], v[112:115]
	v_mfma_f32_16x16x32_bf16 v[108:111], v[100:103], v[208:211], v[108:111]
	v_mfma_f32_16x16x32_bf16 v[104:107], v[148:151], v[208:211], v[104:107]
	v_mfma_f32_16x16x32_bf16 v[60:63], v[160:163], v[176:179], v[60:63]
	v_mfma_f32_16x16x32_bf16 v[56:59], v[168:171], v[176:179], v[56:59]
	v_mfma_f32_16x16x32_bf16 v[52:55], v[160:163], v[184:187], v[52:55]
	v_mfma_f32_16x16x32_bf16 v[48:51], v[168:171], v[184:187], v[48:51]
	v_mfma_f32_16x16x32_bf16 v[44:47], v[160:163], v[192:195], v[44:47]
	v_mfma_f32_16x16x32_bf16 v[40:43], v[168:171], v[192:195], v[40:43]
	v_mfma_f32_16x16x32_bf16 v[36:39], v[160:163], v[204:207], v[36:39]
	v_mfma_f32_16x16x32_bf16 v[32:35], v[168:171], v[204:207], v[32:35]
	v_mfma_f32_16x16x32_bf16 v[60:63], v[164:167], v[180:183], v[60:63]
	v_mfma_f32_16x16x32_bf16 v[56:59], v[172:175], v[180:183], v[56:59]
	v_mfma_f32_16x16x32_bf16 v[52:55], v[164:167], v[188:191], v[52:55]
	v_mfma_f32_16x16x32_bf16 v[48:51], v[172:175], v[188:191], v[48:51]
	v_mfma_f32_16x16x32_bf16 v[44:47], v[164:167], v[196:199], v[44:47]
	v_mfma_f32_16x16x32_bf16 v[40:43], v[172:175], v[196:199], v[40:43]
	v_mfma_f32_16x16x32_bf16 v[36:39], v[164:167], v[208:211], v[36:39]
	v_mfma_f32_16x16x32_bf16 v[32:35], v[172:175], v[208:211], v[32:35]
	s_setprio 0
	s_barrier
; #define PG8_STAGE(bufoff, gbase, voff) do { _Pragma("unroll") for (int _i = 0; _i < 2; ++_i) \
;         __builtin_amdgcn_global_load_lds((const unsigned*)((const char*)(gbase) + (voff)[_i]), (LAS unsigned*)(lds + (bufoff) + ldsw + _i * 8192), 16, 0, 0); } while (0)
; #define PG8_LDA(dst, b, h) do { _Pragma("unroll") for (int m = 0; m < 4; ++m) _Pragma("unroll") for (int k = 0; k < 2; ++k) dst[m][k] = *(const LAS bf16x8*)(lds + PG8_SA(b, h) + aoff + m * 2048 + k * 1024); } while (0)
; #define PG8_MMA(ai, bj, At, Bt) do { __builtin_amdgcn_s_setprio(1); _Pragma("unroll") for (int m = 0; m < 4; ++m) _Pragma("unroll") for (int n = 0; n < 2; ++n) _Pragma("unroll") for (int k = 0; k < 2; ++k) \
;         acc[ai][bj][m][n] = __builtin_amdgcn_mfma_f32_16x16x32_bf16(Bt[n][k], At[m][k], acc[ai][bj][m][n], 0, 0, 0); __builtin_amdgcn_s_setprio(0); } while (0)
; #define PG8_WAIT_V(n) asm volatile("s_waitcnt vmcnt(" #n ")" ::: "memory")
; #define PG8_WAIT_L(n) asm volatile("s_waitcnt lgkmcnt(" #n ")" ::: "memory")
; #define PG8_BAR __builtin_amdgcn_s_barrier()
; #define PG8_SCHED __builtin_amdgcn_sched_barrier(0)
; template <class Epi>
; __device__ __forceinline__ void gemm_phase(LAS unsigned char* lds, const Gemm g, const Sched& S, const Epi& E) {
;     ...
;             PG8_LDA(At, 1, 1); PG8_STAGE(PG8_SB(1, 0), b3, voffB); PG8_STAGE(PG8_SB(1, 1), b3 + hstepB, voffB); PG8_STAGE(PG8_SA(1, 0), a3, voffA);
;             PG8_WAIT_V(8); PG8_WAIT_L(0); PG8_BAR; PG8_MMA(1, 0, At, B0); PG8_MMA(1, 1, At, B1); PG8_BAR; PG8_SCHED;
;         }
;         if (wr == 0) PG8_BAR;
	s_mov_b32 m0, s64
	v_lshl_add_u64 v[200:201], v[200:201], 0, s[46:47]
	ds_read_b128 v[176:179], v157 offset:49152
	ds_read_b128 v[180:183], v157 offset:50176
	ds_read_b128 v[184:187], v157 offset:51200
	ds_read_b128 v[188:191], v157 offset:52224
	ds_read_b128 v[192:195], v157 offset:53248
	ds_read_b128 v[196:199], v157 offset:54272
	ds_read_b128 v[204:207], v157 offset:55296
	ds_read_b128 v[208:211], v157 offset:56320
	global_load_lds_dwordx4 v[200:201], off
	v_lshl_add_u64 v[200:201], v[212:213], 0, s[46:47]
	s_mov_b32 m0, s62
	s_nop 0
	global_load_lds_dwordx4 v[200:201], off
	v_lshl_add_u64 v[200:201], s[14:15], 0, v[138:139]
	s_mov_b32 m0, s63
	s_nop 0
	global_load_lds_dwordx4 v[200:201], off
	v_lshl_add_u64 v[200:201], s[14:15], 0, v[142:143]
	s_mov_b32 m0, s57
	s_nop 0
	global_load_lds_dwordx4 v[200:201], off
	v_lshl_add_u64 v[200:201], v[214:215], 0, s[46:47]
	s_mov_b32 m0, s97
	s_nop 0
	global_load_lds_dwordx4 v[200:201], off
	v_lshl_add_u64 v[200:201], v[216:217], 0, s[46:47]
	s_mov_b32 m0, s58
	s_nop 0
	global_load_lds_dwordx4 v[200:201], off
	s_waitcnt vmcnt(8)
	s_waitcnt lgkmcnt(0)
	s_barrier
	s_setprio 1
	v_mfma_f32_16x16x32_bf16 v[92:95], v[96:99], v[176:179], v[92:95]
	v_mfma_f32_16x16x32_bf16 v[88:91], v[144:147], v[176:179], v[88:91]
	v_mfma_f32_16x16x32_bf16 v[84:87], v[96:99], v[184:187], v[84:87]
	v_mfma_f32_16x16x32_bf16 v[80:83], v[144:147], v[184:187], v[80:83]
	v_mfma_f32_16x16x32_bf16 v[76:79], v[96:99], v[192:195], v[76:79]
	v_mfma_f32_16x16x32_bf16 v[72:75], v[144:147], v[192:195], v[72:75]
	v_mfma_f32_16x16x32_bf16 v[68:71], v[96:99], v[204:207], v[68:71]
	v_mfma_f32_16x16x32_bf16 v[64:67], v[144:147], v[204:207], v[64:67]
	v_mfma_f32_16x16x32_bf16 v[92:95], v[100:103], v[180:183], v[92:95]
	v_mfma_f32_16x16x32_bf16 v[88:91], v[148:151], v[180:183], v[88:91]
	v_mfma_f32_16x16x32_bf16 v[84:87], v[100:103], v[188:191], v[84:87]
	v_mfma_f32_16x16x32_bf16 v[80:83], v[148:151], v[188:191], v[80:83]
	v_mfma_f32_16x16x32_bf16 v[76:79], v[100:103], v[196:199], v[76:79]
	v_mfma_f32_16x16x32_bf16 v[72:75], v[148:151], v[196:199], v[72:75]
	v_mfma_f32_16x16x32_bf16 v[68:71], v[100:103], v[208:211], v[68:71]
	v_mfma_f32_16x16x32_bf16 v[64:67], v[148:151], v[208:211], v[64:67]
	v_mfma_f32_16x16x32_bf16 v[28:31], v[160:163], v[176:179], v[28:31]
	v_mfma_f32_16x16x32_bf16 v[24:27], v[168:171], v[176:179], v[24:27]
	v_mfma_f32_16x16x32_bf16 v[20:23], v[160:163], v[184:187], v[20:23]
	v_mfma_f32_16x16x32_bf16 v[16:19], v[168:171], v[184:187], v[16:19]
	v_mfma_f32_16x16x32_bf16 v[12:15], v[160:163], v[192:195], v[12:15]
	v_mfma_f32_16x16x32_bf16 v[8:11], v[168:171], v[192:195], v[8:11]
	v_mfma_f32_16x16x32_bf16 v[4:7], v[160:163], v[204:207], v[4:7]
	v_mfma_f32_16x16x32_bf16 v[0:3], v[168:171], v[204:207], v[0:3]
	v_mfma_f32_16x16x32_bf16 v[28:31], v[164:167], v[180:183], v[28:31]
	v_mfma_f32_16x16x32_bf16 v[24:27], v[172:175], v[180:183], v[24:27]
	v_mfma_f32_16x16x32_bf16 v[20:23], v[164:167], v[188:191], v[20:23]
	v_mfma_f32_16x16x32_bf16 v[16:19], v[172:175], v[188:191], v[16:19]
	v_mfma_f32_16x16x32_bf16 v[12:15], v[164:167], v[196:199], v[12:15]
	v_mfma_f32_16x16x32_bf16 v[8:11], v[172:175], v[196:199], v[8:11]
	v_mfma_f32_16x16x32_bf16 v[4:7], v[164:167], v[208:211], v[4:7]
	v_mfma_f32_16x16x32_bf16 v[0:3], v[172:175], v[208:211], v[0:3]
	s_setprio 0
	s_barrier
	s_andn2_b64 vcc, exec, s[8:9]
	s_mov_b64 s[14:15], -1
	s_mov_b64 s[8:9], 0
	s_mov_b64 s[78:79], 0x100
	s_cbranch_vccz .LBB0_900
	s_and_b64 vcc, exec, s[52:53]
	s_cbranch_vccz .LBB0_903
	s_barrier

; #define PG8_STAGE(bufoff, gbase, voff) do { _Pragma("unroll") for (int _i = 0; _i < 2; ++_i) \
;         __builtin_amdgcn_global_load_lds((const unsigned*)((const char*)(gbase) + (voff)[_i]), (LAS unsigned*)(lds + (bufoff) + ldsw + _i * 8192), 16, 0, 0); } while (0)
; #define PG8_LDA(dst, b, h) do { _Pragma("unroll") for (int m = 0; m < 4; ++m) _Pragma("unroll") for (int k = 0; k < 2; ++k) dst[m][k] = *(const LAS bf16x8*)(lds + PG8_SA(b, h) + aoff + m * 2048 + k * 1024); } while (0)
; #define PG8_LDB(dst, b, h) do { _Pragma("unroll") for (int n = 0; n < 2; ++n) _Pragma("unroll") for (int k = 0; k < 2; ++k) dst[n][k] = *(const LAS bf16x8*)(lds + PG8_SB(b, h) + boff + n * 2048 + k * 1024); } while (0)
; #define PG8_MMA(ai, bj, At, Bt) do { __builtin_amdgcn_s_setprio(1); _Pragma("unroll") for (int m = 0; m < 4; ++m) _Pragma("unroll") for (int n = 0; n < 2; ++n) _Pragma("unroll") for (int k = 0; k < 2; ++k) \
;         acc[ai][bj][m][n] = __builtin_amdgcn_mfma_f32_16x16x32_bf16(Bt[n][k], At[m][k], acc[ai][bj][m][n], 0, 0, 0); __builtin_amdgcn_s_setprio(0); } while (0)
; #define PG8_WAIT_V(n) asm volatile("s_waitcnt vmcnt(" #n ")" ::: "memory")
; #define PG8_WAIT_L(n) asm volatile("s_waitcnt lgkmcnt(" #n ")" ::: "memory")
; #define PG8_BAR __builtin_amdgcn_s_barrier()
; #define PG8_SCHED __builtin_amdgcn_sched_barrier(0)
; template <class Epi>
; __device__ __forceinline__ void gemm_phase(LAS unsigned char* lds, const Gemm g, const Sched& S, const Epi& E) {
;     ...
;             const char* a1 = cA + (size_t)(t + 1) * kstep;
;             const char* a2 = last ? nA : cA + (size_t)(t + 2) * kstep; const char* b2 = last ? nB : cB + (size_t)(t + 2) * kstep;
;             const char* a3 = a2 + kstep; const char* b3 = b2 + kstep;
;             PG8_LDB(B0, 0, 0); PG8_LDB(B1, 0, 1); PG8_SCHED; PG8_LDA(At, 0, 0); PG8_STAGE(PG8_SA(1, 1), a1 + hstepA, voffA);
;             PG8_WAIT_V(8); PG8_WAIT_L(0); PG8_BAR; PG8_MMA(0, 0, At, B0); PG8_MMA(0, 1, At, B1); PG8_BAR; PG8_SCHED;
;             PG8_LDA(At, 0, 1); PG8_STAGE(PG8_SB(0, 0), b2, voffB); PG8_STAGE(PG8_SB(0, 1), b2 + hstepB, voffB); PG8_STAGE(PG8_SA(0, 0), a2, voffA);
;             PG8_WAIT_V(8); PG8_WAIT_L(0); PG8_BAR; PG8_MMA(1, 0, At, B0); PG8_MMA(1, 1, At, B1); PG8_BAR; PG8_SCHED;
.LBB0_1214:
	v_add_u32_e32 v158, s58, v144
	v_add_u32_e32 v174, s59, v144
	s_add_u32 s46, s40, s44
	ds_read_b128 v[146:149], v158
	ds_read_b128 v[150:153], v158 offset:1024
	ds_read_b128 v[154:157], v158 offset:2048
	ds_read_b128 v[158:161], v158 offset:3072
	ds_read_b128 v[162:165], v174
	ds_read_b128 v[166:169], v174 offset:1024
	ds_read_b128 v[170:173], v174 offset:2048
	ds_read_b128 v[174:177], v174 offset:3072
	s_addc_u32 s47, s41, s45
	s_add_u32 s46, s46, 0x100
	s_addc_u32 s47, s47, 0
	s_add_u32 s67, s62, s44
	s_addc_u32 s68, s63, s45
	s_cmpk_eq_i32 s44, 0x700
	s_cselect_b32 s49, s25, s47
	s_cselect_b32 s48, s64, s46
	s_cselect_b32 s47, s27, s68
	s_cselect_b32 s46, s65, s67
	v_lshl_add_u64 v[186:187], v[140:141], 0, s[44:45]
	s_add_i32 m0, s51, 0xc000
	ds_read_b128 v[178:181], v145
	ds_read_b128 v[182:185], v145 offset:1024
	ds_read_b128 v[192:195], v145 offset:2048
	ds_read_b128 v[196:199], v145 offset:3072
	ds_read_b128 v[204:207], v145 offset:4096
	ds_read_b128 v[208:211], v145 offset:5120
	ds_read_b128 v[212:215], v145 offset:6144
	ds_read_b128 v[216:219], v145 offset:7168
	global_load_lds_dwordx4 v[186:187], off
	v_lshl_add_u64 v[186:187], v[142:143], 0, s[44:45]
	s_add_i32 m0, s51, 0xe000
	s_nop 0
	global_load_lds_dwordx4 v[186:187], off
	s_waitcnt vmcnt(8)
	s_waitcnt lgkmcnt(0)
	s_barrier
	s_setprio 1
	v_mfma_f32_16x16x32_bf16 v[124:127], v[146:149], v[178:181], v[124:127]
	v_mfma_f32_16x16x32_bf16 v[120:123], v[154:157], v[178:181], v[120:123]
	v_mfma_f32_16x16x32_bf16 v[108:111], v[146:149], v[192:195], v[108:111]
	v_mfma_f32_16x16x32_bf16 v[104:107], v[154:157], v[192:195], v[104:107]
	v_mfma_f32_16x16x32_bf16 v[92:95], v[146:149], v[204:207], v[92:95]
	v_mfma_f32_16x16x32_bf16 v[88:91], v[154:157], v[204:207], v[88:91]
	v_mfma_f32_16x16x32_bf16 v[76:79], v[146:149], v[212:215], v[76:79]
	v_mfma_f32_16x16x32_bf16 v[72:75], v[154:157], v[212:215], v[72:75]
	v_mfma_f32_16x16x32_bf16 v[124:127], v[150:153], v[182:185], v[124:127]
	v_mfma_f32_16x16x32_bf16 v[120:123], v[158:161], v[182:185], v[120:123]
	v_mfma_f32_16x16x32_bf16 v[108:111], v[150:153], v[196:199], v[108:111]
	v_mfma_f32_16x16x32_bf16 v[104:107], v[158:161], v[196:199], v[104:107]
	v_mfma_f32_16x16x32_bf16 v[92:95], v[150:153], v[208:211], v[92:95]
	v_mfma_f32_16x16x32_bf16 v[88:91], v[158:161], v[208:211], v[88:91]
	v_mfma_f32_16x16x32_bf16 v[76:79], v[150:153], v[216:219], v[76:79]
	v_mfma_f32_16x16x32_bf16 v[72:75], v[158:161], v[216:219], v[72:75]
	v_mfma_f32_16x16x32_bf16 v[116:119], v[162:165], v[178:181], v[116:119]
	v_mfma_f32_16x16x32_bf16 v[112:115], v[170:173], v[178:181], v[112:115]
	v_mfma_f32_16x16x32_bf16 v[100:103], v[162:165], v[192:195], v[100:103]
	v_mfma_f32_16x16x32_bf16 v[96:99], v[170:173], v[192:195], v[96:99]
	v_mfma_f32_16x16x32_bf16 v[84:87], v[162:165], v[204:207], v[84:87]
	v_mfma_f32_16x16x32_bf16 v[80:83], v[170:173], v[204:207], v[80:83]
	v_mfma_f32_16x16x32_bf16 v[68:71], v[162:165], v[212:215], v[68:71]
	v_mfma_f32_16x16x32_bf16 v[64:67], v[170:173], v[212:215], v[64:67]
	v_mfma_f32_16x16x32_bf16 v[116:119], v[166:169], v[182:185], v[116:119]
	v_mfma_f32_16x16x32_bf16 v[112:115], v[174:177], v[182:185], v[112:115]
	v_mfma_f32_16x16x32_bf16 v[100:103], v[166:169], v[196:199], v[100:103]
	v_mfma_f32_16x16x32_bf16 v[96:99], v[174:177], v[196:199], v[96:99]
	v_mfma_f32_16x16x32_bf16 v[84:87], v[166:169], v[208:211], v[84:87]
	v_mfma_f32_16x16x32_bf16 v[80:83], v[174:177], v[208:211], v[80:83]
	v_mfma_f32_16x16x32_bf16 v[68:71], v[166:169], v[216:219], v[68:71]
	v_mfma_f32_16x16x32_bf16 v[64:67], v[174:177], v[216:219], v[64:67]
	s_setprio 0
	s_barrier
	s_add_i32 s67, s58, s50
	v_lshl_add_u64 v[186:187], s[46:47], 0, v[130:131]
	s_mov_b32 m0, s67
	ds_read_b128 v[178:181], v145 offset:16384
	ds_read_b128 v[182:185], v145 offset:17408
	ds_read_b128 v[192:195], v145 offset:18432
	ds_read_b128 v[196:199], v145 offset:19456
	ds_read_b128 v[204:207], v145 offset:20480
	ds_read_b128 v[208:211], v145 offset:21504
	ds_read_b128 v[212:215], v145 offset:22528
	ds_read_b128 v[216:219], v145 offset:23552
	global_load_lds_dwordx4 v[186:187], off
	s_add_i32 m0, s67, 0x2000
	s_add_u32 s68, s46, 0x40000
	v_lshl_add_u64 v[200:201], s[46:47], 0, v[134:135]
	s_addc_u32 s69, s47, 0
	s_add_i32 s67, s59, s50
	global_load_lds_dwordx4 v[200:201], off
	v_lshl_add_u64 v[220:221], s[68:69], 0, v[130:131]
	s_mov_b32 m0, s67
	v_lshl_add_u64 v[222:223], s[48:49], 0, v[132:133]
	global_load_lds_dwordx4 v[220:221], off
	v_lshl_add_u64 v[220:221], s[68:69], 0, v[134:135]
	s_add_i32 m0, s67, 0x2000
	s_nop 0
	global_load_lds_dwordx4 v[220:221], off
	v_lshl_add_u64 v[220:221], s[48:49], 0, v[128:129]
	s_mov_b32 m0, s51
	s_nop 0
	global_load_lds_dwordx4 v[220:221], off
	s_mov_b32 m0, s52
	s_nop 0
	global_load_lds_dwordx4 v[222:223], off
	s_waitcnt vmcnt(8)
	s_waitcnt lgkmcnt(0)
	s_barrier
; #define PG8_STAGE(bufoff, gbase, voff) do { _Pragma("unroll") for (int _i = 0; _i < 2; ++_i) \
;         __builtin_amdgcn_global_load_lds((const unsigned*)((const char*)(gbase) + (voff)[_i]), (LAS unsigned*)(lds + (bufoff) + ldsw + _i * 8192), 16, 0, 0); } while (0)
; #define PG8_LDA(dst, b, h) do { _Pragma("unroll") for (int m = 0; m < 4; ++m) _Pragma("unroll") for (int k = 0; k < 2; ++k) dst[m][k] = *(const LAS bf16x8*)(lds + PG8_SA(b, h) + aoff + m * 2048 + k * 1024); } while (0)
; #define PG8_LDB(dst, b, h) do { _Pragma("unroll") for (int n = 0; n < 2; ++n) _Pragma("unroll") for (int k = 0; k < 2; ++k) dst[n][k] = *(const LAS bf16x8*)(lds + PG8_SB(b, h) + boff + n * 2048 + k * 1024); } while (0)
; #define PG8_MMA(ai, bj, At, Bt) do { __builtin_amdgcn_s_setprio(1); _Pragma("unroll") for (int m = 0; m < 4; ++m) _Pragma("unroll") for (int n = 0; n < 2; ++n) _Pragma("unroll") for (int k = 0; k < 2; ++k) \
;         acc[ai][bj][m][n] = __builtin_amdgcn_mfma_f32_16x16x32_bf16(Bt[n][k], At[m][k], acc[ai][bj][m][n], 0, 0, 0); __builtin_amdgcn_s_setprio(0); } while (0)
; #define PG8_WAIT_V(n) asm volatile("s_waitcnt vmcnt(" #n ")" ::: "memory")
; #define PG8_WAIT_L(n) asm volatile("s_waitcnt lgkmcnt(" #n ")" ::: "memory")
; #define PG8_BAR __builtin_amdgcn_s_barrier()
; #define PG8_SCHED __builtin_amdgcn_sched_barrier(0)
; template <class Epi>
; __device__ __forceinline__ void gemm_phase(LAS unsigned char* lds, const Gemm g, const Sched& S, const Epi& E) {
;     ...
;             PG8_WAIT_V(8); PG8_WAIT_L(0); PG8_BAR; PG8_MMA(1, 0, At, B0); PG8_MMA(1, 1, At, B1); PG8_BAR; PG8_SCHED;
;             PG8_LDB(B0, 1, 0); PG8_LDB(B1, 1, 1); PG8_SCHED; PG8_LDA(At, 1, 0); PG8_STAGE(PG8_SA(0, 1), a2 + hstepA, voffA);
;             PG8_WAIT_V(8); PG8_WAIT_L(0); PG8_BAR; PG8_MMA(0, 0, At, B0); PG8_MMA(0, 1, At, B1); PG8_BAR; PG8_SCHED;
	s_setprio 1
	v_mfma_f32_16x16x32_bf16 v[60:63], v[146:149], v[178:181], v[60:63]
	v_mfma_f32_16x16x32_bf16 v[56:59], v[154:157], v[178:181], v[56:59]
	v_mfma_f32_16x16x32_bf16 v[44:47], v[146:149], v[192:195], v[44:47]
	v_mfma_f32_16x16x32_bf16 v[40:43], v[154:157], v[192:195], v[40:43]
	v_mfma_f32_16x16x32_bf16 v[28:31], v[146:149], v[204:207], v[28:31]
	v_mfma_f32_16x16x32_bf16 v[24:27], v[154:157], v[204:207], v[24:27]
	v_mfma_f32_16x16x32_bf16 v[12:15], v[146:149], v[212:215], v[12:15]
	v_mfma_f32_16x16x32_bf16 v[8:11], v[154:157], v[212:215], v[8:11]
	v_mfma_f32_16x16x32_bf16 v[60:63], v[150:153], v[182:185], v[60:63]
	v_mfma_f32_16x16x32_bf16 v[56:59], v[158:161], v[182:185], v[56:59]
	v_mfma_f32_16x16x32_bf16 v[44:47], v[150:153], v[196:199], v[44:47]
	v_mfma_f32_16x16x32_bf16 v[40:43], v[158:161], v[196:199], v[40:43]
	v_mfma_f32_16x16x32_bf16 v[28:31], v[150:153], v[208:211], v[28:31]
	v_mfma_f32_16x16x32_bf16 v[24:27], v[158:161], v[208:211], v[24:27]
	v_mfma_f32_16x16x32_bf16 v[12:15], v[150:153], v[216:219], v[12:15]
	v_mfma_f32_16x16x32_bf16 v[8:11], v[158:161], v[216:219], v[8:11]
	v_mfma_f32_16x16x32_bf16 v[52:55], v[162:165], v[178:181], v[52:55]
	v_mfma_f32_16x16x32_bf16 v[48:51], v[170:173], v[178:181], v[48:51]
	v_mfma_f32_16x16x32_bf16 v[36:39], v[162:165], v[192:195], v[36:39]
	v_mfma_f32_16x16x32_bf16 v[32:35], v[170:173], v[192:195], v[32:35]
	v_mfma_f32_16x16x32_bf16 v[20:23], v[162:165], v[204:207], v[20:23]
	v_mfma_f32_16x16x32_bf16 v[16:19], v[170:173], v[204:207], v[16:19]
	v_mfma_f32_16x16x32_bf16 v[4:7], v[162:165], v[212:215], v[4:7]
	v_mfma_f32_16x16x32_bf16 v[0:3], v[170:173], v[212:215], v[0:3]
	v_mfma_f32_16x16x32_bf16 v[52:55], v[166:169], v[182:185], v[52:55]
	v_mfma_f32_16x16x32_bf16 v[48:51], v[174:177], v[182:185], v[48:51]
	v_mfma_f32_16x16x32_bf16 v[36:39], v[166:169], v[196:199], v[36:39]
	v_mfma_f32_16x16x32_bf16 v[32:35], v[174:177], v[196:199], v[32:35]
	v_mfma_f32_16x16x32_bf16 v[20:23], v[166:169], v[208:211], v[20:23]
	v_mfma_f32_16x16x32_bf16 v[16:19], v[174:177], v[208:211], v[16:19]
	v_mfma_f32_16x16x32_bf16 v[4:7], v[166:169], v[216:219], v[4:7]
	v_mfma_f32_16x16x32_bf16 v[0:3], v[174:177], v[216:219], v[0:3]
	s_setprio 0
	s_barrier
	s_add_i32 s67, 0, 0x18000
	s_add_i32 s68, 0, 0x1c000
	v_add_u32_e32 v158, s67, v144
	v_add_u32_e32 v174, s68, v144
	ds_read_b128 v[146:149], v158
	ds_read_b128 v[150:153], v158 offset:1024
	ds_read_b128 v[154:157], v158 offset:2048
	ds_read_b128 v[158:161], v158 offset:3072
	ds_read_b128 v[162:165], v174
	ds_read_b128 v[166:169], v174 offset:1024
	ds_read_b128 v[170:173], v174 offset:2048
	ds_read_b128 v[174:177], v174 offset:3072
	s_add_u32 s48, s48, 0x40000
	s_addc_u32 s49, s49, 0
	s_mov_b32 m0, s53
	v_lshl_add_u64 v[224:225], s[48:49], 0, v[128:129]
	ds_read_b128 v[178:181], v145 offset:32768
	ds_read_b128 v[182:185], v145 offset:33792
	ds_read_b128 v[192:195], v145 offset:34816
	ds_read_b128 v[196:199], v145 offset:35840
	ds_read_b128 v[204:207], v145 offset:36864
	ds_read_b128 v[208:211], v145 offset:37888
	ds_read_b128 v[212:215], v145 offset:38912
	ds_read_b128 v[216:219], v145 offset:39936
	global_load_lds_dwordx4 v[224:225], off
	v_lshl_add_u64 v[224:225], s[48:49], 0, v[132:133]
	s_mov_b32 m0, s54
	s_nop 0
	global_load_lds_dwordx4 v[224:225], off
	s_waitcnt vmcnt(8)
	s_waitcnt lgkmcnt(0)
	s_barrier
	s_setprio 1
	v_mfma_f32_16x16x32_bf16 v[124:127], v[146:149], v[178:181], v[124:127]
	v_mfma_f32_16x16x32_bf16 v[120:123], v[154:157], v[178:181], v[120:123]
	v_mfma_f32_16x16x32_bf16 v[108:111], v[146:149], v[192:195], v[108:111]
	v_mfma_f32_16x16x32_bf16 v[104:107], v[154:157], v[192:195], v[104:107]
	v_mfma_f32_16x16x32_bf16 v[92:95], v[146:149], v[204:207], v[92:95]
	v_mfma_f32_16x16x32_bf16 v[88:91], v[154:157], v[204:207], v[88:91]
	v_mfma_f32_16x16x32_bf16 v[76:79], v[146:149], v[212:215], v[76:79]
	v_mfma_f32_16x16x32_bf16 v[72:75], v[154:157], v[212:215], v[72:75]
	v_mfma_f32_16x16x32_bf16 v[124:127], v[150:153], v[182:185], v[124:127]
	v_mfma_f32_16x16x32_bf16 v[120:123], v[158:161], v[182:185], v[120:123]
	v_mfma_f32_16x16x32_bf16 v[108:111], v[150:153], v[196:199], v[108:111]
	v_mfma_f32_16x16x32_bf16 v[104:107], v[158:161], v[196:199], v[104:107]
	v_mfma_f32_16x16x32_bf16 v[92:95], v[150:153], v[208:211], v[92:95]
	v_mfma_f32_16x16x32_bf16 v[88:91], v[158:161], v[208:211], v[88:91]
	v_mfma_f32_16x16x32_bf16 v[76:79], v[150:153], v[216:219], v[76:79]
	v_mfma_f32_16x16x32_bf16 v[72:75], v[158:161], v[216:219], v[72:75]
	v_mfma_f32_16x16x32_bf16 v[116:119], v[162:165], v[178:181], v[116:119]
	v_mfma_f32_16x16x32_bf16 v[112:115], v[170:173], v[178:181], v[112:115]
	v_mfma_f32_16x16x32_bf16 v[100:103], v[162:165], v[192:195], v[100:103]
	v_mfma_f32_16x16x32_bf16 v[96:99], v[170:173], v[192:195], v[96:99]
	v_mfma_f32_16x16x32_bf16 v[84:87], v[162:165], v[204:207], v[84:87]
	v_mfma_f32_16x16x32_bf16 v[80:83], v[170:173], v[204:207], v[80:83]
	v_mfma_f32_16x16x32_bf16 v[68:71], v[162:165], v[212:215], v[68:71]
	v_mfma_f32_16x16x32_bf16 v[64:67], v[170:173], v[212:215], v[64:67]
	v_mfma_f32_16x16x32_bf16 v[116:119], v[166:169], v[182:185], v[116:119]
	v_mfma_f32_16x16x32_bf16 v[112:115], v[174:177], v[182:185], v[112:115]
	v_mfma_f32_16x16x32_bf16 v[100:103], v[166:169], v[196:199], v[100:103]
	v_mfma_f32_16x16x32_bf16 v[96:99], v[174:177], v[196:199], v[96:99]
	v_mfma_f32_16x16x32_bf16 v[84:87], v[166:169], v[208:211], v[84:87]
	v_mfma_f32_16x16x32_bf16 v[80:83], v[174:177], v[208:211], v[80:83]
	v_mfma_f32_16x16x32_bf16 v[68:71], v[166:169], v[216:219], v[68:71]
	v_mfma_f32_16x16x32_bf16 v[64:67], v[174:177], v[216:219], v[64:67]
	s_setprio 0
	s_barrier
; #define PG8_STAGE(bufoff, gbase, voff) do { _Pragma("unroll") for (int _i = 0; _i < 2; ++_i) \
;         __builtin_amdgcn_global_load_lds((const unsigned*)((const char*)(gbase) + (voff)[_i]), (LAS unsigned*)(lds + (bufoff) + ldsw + _i * 8192), 16, 0, 0); } while (0)
; #define PG8_LDA(dst, b, h) do { _Pragma("unroll") for (int m = 0; m < 4; ++m) _Pragma("unroll") for (int k = 0; k < 2; ++k) dst[m][k] = *(const LAS bf16x8*)(lds + PG8_SA(b, h) + aoff + m * 2048 + k * 1024); } while (0)
; #define PG8_MMA(ai, bj, At, Bt) do { __builtin_amdgcn_s_setprio(1); _Pragma("unroll") for (int m = 0; m < 4; ++m) _Pragma("unroll") for (int n = 0; n < 2; ++n) _Pragma("unroll") for (int k = 0; k < 2; ++k) \
;         acc[ai][bj][m][n] = __builtin_amdgcn_mfma_f32_16x16x32_bf16(Bt[n][k], At[m][k], acc[ai][bj][m][n], 0, 0, 0); __builtin_amdgcn_s_setprio(0); } while (0)
; #define PG8_WAIT_V(n) asm volatile("s_waitcnt vmcnt(" #n ")" ::: "memory")
; #define PG8_WAIT_L(n) asm volatile("s_waitcnt lgkmcnt(" #n ")" ::: "memory")
; #define PG8_BAR __builtin_amdgcn_s_barrier()
; #define PG8_SCHED __builtin_amdgcn_sched_barrier(0)
; template <class Epi>
; __device__ __forceinline__ void gemm_phase(LAS unsigned char* lds, const Gemm g, const Sched& S, const Epi& E) {
;     ...
;             PG8_LDA(At, 1, 1); PG8_STAGE(PG8_SB(1, 0), b3, voffB); PG8_STAGE(PG8_SB(1, 1), b3 + hstepB, voffB); PG8_STAGE(PG8_SA(1, 0), a3, voffA);
;             PG8_WAIT_V(8); PG8_WAIT_L(0); PG8_BAR; PG8_MMA(1, 0, At, B0); PG8_MMA(1, 1, At, B1); PG8_BAR; PG8_SCHED;
;         }
;         if (wr == 0) PG8_BAR;
	s_add_i32 s48, s67, s50
	v_lshl_add_u64 v[186:187], v[186:187], 0, s[4:5]
	s_mov_b32 m0, s48
	ds_read_b128 v[178:181], v145 offset:49152
	ds_read_b128 v[182:185], v145 offset:50176
	ds_read_b128 v[192:195], v145 offset:51200
	ds_read_b128 v[196:199], v145 offset:52224
	ds_read_b128 v[204:207], v145 offset:53248
	ds_read_b128 v[208:211], v145 offset:54272
	ds_read_b128 v[212:215], v145 offset:55296
	ds_read_b128 v[216:219], v145 offset:56320
	global_load_lds_dwordx4 v[186:187], off
	s_add_i32 m0, s48, 0x2000
	s_add_u32 s46, s46, 0x40080
	v_lshl_add_u64 v[186:187], v[200:201], 0, s[4:5]
	s_addc_u32 s47, s47, 0
	s_add_i32 s48, s68, s50
	global_load_lds_dwordx4 v[186:187], off
	v_lshl_add_u64 v[186:187], s[46:47], 0, v[130:131]
	s_mov_b32 m0, s48
	s_nop 0
	global_load_lds_dwordx4 v[186:187], off
	v_lshl_add_u64 v[186:187], s[46:47], 0, v[134:135]
	s_add_i32 m0, s48, 0x2000
	s_nop 0
	global_load_lds_dwordx4 v[186:187], off
	v_lshl_add_u64 v[186:187], v[220:221], 0, s[4:5]
	s_mov_b32 m0, s56
	s_nop 0
	global_load_lds_dwordx4 v[186:187], off
	v_lshl_add_u64 v[186:187], v[222:223], 0, s[4:5]
	s_mov_b32 m0, s57
	s_nop 0
	global_load_lds_dwordx4 v[186:187], off
	s_waitcnt vmcnt(8)
	s_waitcnt lgkmcnt(0)
	s_barrier
	s_setprio 1
	v_mfma_f32_16x16x32_bf16 v[60:63], v[146:149], v[178:181], v[60:63]
	v_mfma_f32_16x16x32_bf16 v[56:59], v[154:157], v[178:181], v[56:59]
	v_mfma_f32_16x16x32_bf16 v[44:47], v[146:149], v[192:195], v[44:47]
	v_mfma_f32_16x16x32_bf16 v[40:43], v[154:157], v[192:195], v[40:43]
	v_mfma_f32_16x16x32_bf16 v[28:31], v[146:149], v[204:207], v[28:31]
	v_mfma_f32_16x16x32_bf16 v[24:27], v[154:157], v[204:207], v[24:27]
	v_mfma_f32_16x16x32_bf16 v[12:15], v[146:149], v[212:215], v[12:15]
	v_mfma_f32_16x16x32_bf16 v[8:11], v[154:157], v[212:215], v[8:11]
	v_mfma_f32_16x16x32_bf16 v[60:63], v[150:153], v[182:185], v[60:63]
	v_mfma_f32_16x16x32_bf16 v[56:59], v[158:161], v[182:185], v[56:59]
	v_mfma_f32_16x16x32_bf16 v[44:47], v[150:153], v[196:199], v[44:47]
	v_mfma_f32_16x16x32_bf16 v[40:43], v[158:161], v[196:199], v[40:43]
	v_mfma_f32_16x16x32_bf16 v[28:31], v[150:153], v[208:211], v[28:31]
	v_mfma_f32_16x16x32_bf16 v[24:27], v[158:161], v[208:211], v[24:27]
	v_mfma_f32_16x16x32_bf16 v[12:15], v[150:153], v[216:219], v[12:15]
	v_mfma_f32_16x16x32_bf16 v[8:11], v[158:161], v[216:219], v[8:11]
	v_mfma_f32_16x16x32_bf16 v[52:55], v[162:165], v[178:181], v[52:55]
	v_mfma_f32_16x16x32_bf16 v[48:51], v[170:173], v[178:181], v[48:51]
	v_mfma_f32_16x16x32_bf16 v[36:39], v[162:165], v[192:195], v[36:39]
	v_mfma_f32_16x16x32_bf16 v[32:35], v[170:173], v[192:195], v[32:35]
	v_mfma_f32_16x16x32_bf16 v[20:23], v[162:165], v[204:207], v[20:23]
	v_mfma_f32_16x16x32_bf16 v[16:19], v[170:173], v[204:207], v[16:19]
	v_mfma_f32_16x16x32_bf16 v[4:7], v[162:165], v[212:215], v[4:7]
	v_mfma_f32_16x16x32_bf16 v[0:3], v[170:173], v[212:215], v[0:3]
	v_mfma_f32_16x16x32_bf16 v[52:55], v[166:169], v[182:185], v[52:55]
	v_mfma_f32_16x16x32_bf16 v[48:51], v[174:177], v[182:185], v[48:51]
	v_mfma_f32_16x16x32_bf16 v[36:39], v[166:169], v[196:199], v[36:39]
	v_mfma_f32_16x16x32_bf16 v[32:35], v[174:177], v[196:199], v[32:35]
	v_mfma_f32_16x16x32_bf16 v[20:23], v[166:169], v[208:211], v[20:23]
	v_mfma_f32_16x16x32_bf16 v[16:19], v[174:177], v[208:211], v[16:19]
	v_mfma_f32_16x16x32_bf16 v[4:7], v[166:169], v[216:219], v[4:7]
	v_mfma_f32_16x16x32_bf16 v[0:3], v[174:177], v[216:219], v[0:3]
	s_setprio 0
	s_barrier
	s_add_i32 s66, s66, 2
	s_add_u32 s44, s44, 0x100
	s_addc_u32 s45, s45, 0
	s_cmp_gt_u32 s66, 13
	s_cbranch_scc0 .LBB0_1214
	s_and_b64 vcc, exec, s[22:23]
	s_cbranch_vccz .LBB0_1217
	s_barrier

; #define PG8_STAGE(bufoff, gbase, voff) do { _Pragma("unroll") for (int _i = 0; _i < 2; ++_i) \
;         __builtin_amdgcn_global_load_lds((const unsigned*)((const char*)(gbase) + (voff)[_i]), (LAS unsigned*)(lds + (bufoff) + ldsw + _i * 8192), 16, 0, 0); } while (0)
; #define PG8_LDA(dst, b, h) do { _Pragma("unroll") for (int m = 0; m < 4; ++m) _Pragma("unroll") for (int k = 0; k < 2; ++k) dst[m][k] = *(const LAS bf16x8*)(lds + PG8_SA(b, h) + aoff + m * 2048 + k * 1024); } while (0)
; #define PG8_LDB(dst, b, h) do { _Pragma("unroll") for (int n = 0; n < 2; ++n) _Pragma("unroll") for (int k = 0; k < 2; ++k) dst[n][k] = *(const LAS bf16x8*)(lds + PG8_SB(b, h) + boff + n * 2048 + k * 1024); } while (0)
; #define PG8_MMA(ai, bj, At, Bt) do { __builtin_amdgcn_s_setprio(1); _Pragma("unroll") for (int m = 0; m < 4; ++m) _Pragma("unroll") for (int n = 0; n < 2; ++n) _Pragma("unroll") for (int k = 0; k < 2; ++k) \
;         acc[ai][bj][m][n] = __builtin_amdgcn_mfma_f32_16x16x32_bf16(Bt[n][k], At[m][k], acc[ai][bj][m][n], 0, 0, 0); __builtin_amdgcn_s_setprio(0); } while (0)
; #define PG8_WAIT_V(n) asm volatile("s_waitcnt vmcnt(" #n ")" ::: "memory")
; #define PG8_WAIT_L(n) asm volatile("s_waitcnt lgkmcnt(" #n ")" ::: "memory")
; #define PG8_BAR __builtin_amdgcn_s_barrier()
; #define PG8_SCHED __builtin_amdgcn_sched_barrier(0)
; template <class Epi>
; __device__ __forceinline__ void gemm_phase(LAS unsigned char* lds, const Gemm g, const Sched& S, const Epi& E) {
;     ...
;             const char* a1 = cA + (size_t)(t + 1) * kstep;
;             const char* a2 = last ? nA : cA + (size_t)(t + 2) * kstep; const char* b2 = last ? nB : cB + (size_t)(t + 2) * kstep;
;             const char* a3 = a2 + kstep; const char* b3 = b2 + kstep;
;             PG8_LDB(B0, 0, 0); PG8_LDB(B1, 0, 1); PG8_SCHED; PG8_LDA(At, 0, 0); PG8_STAGE(PG8_SA(1, 1), a1 + hstepA, voffA);
;             PG8_WAIT_V(8); PG8_WAIT_L(0); PG8_BAR; PG8_MMA(0, 0, At, B0); PG8_MMA(0, 1, At, B1); PG8_BAR; PG8_SCHED;
;             PG8_LDA(At, 0, 1); PG8_STAGE(PG8_SB(0, 0), b2, voffB); PG8_STAGE(PG8_SB(0, 1), b2 + hstepB, voffB); PG8_STAGE(PG8_SA(0, 0), a2, voffA);
;             PG8_WAIT_V(8); PG8_WAIT_L(0); PG8_BAR; PG8_MMA(1, 0, At, B0); PG8_MMA(1, 1, At, B1); PG8_BAR; PG8_SCHED;
.LBB0_1355:
	ds_read_b128 v[140:143], v148
	ds_read_b128 v[152:155], v148 offset:1024
	ds_read_b128 v[156:159], v148 offset:2048
	ds_read_b128 v[160:163], v148 offset:3072
	ds_read_b128 v[164:167], v149
	ds_read_b128 v[168:171], v149 offset:1024
	ds_read_b128 v[172:175], v149 offset:2048
	ds_read_b128 v[176:179], v149 offset:3072
	s_add_u32 s40, s38, 0xfffc0080
	s_addc_u32 s41, s39, -1
	s_cmp_eq_u32 s54, 12
	s_cselect_b32 s43, s23, s41
	s_cselect_b32 s42, s50, s40
	s_cselect_b32 s41, s25, s53
	s_cselect_b32 s40, s51, s52
	v_lshl_add_u64 v[200:201], s[38:39], 0, v[136:137]
	s_add_i32 m0, s11, 0xc000
	ds_read_b128 v[180:183], v150
	ds_read_b128 v[184:187], v150 offset:1024
	ds_read_b128 v[188:191], v150 offset:2048
	ds_read_b128 v[192:195], v150 offset:3072
	ds_read_b128 v[196:199], v150 offset:4096
	ds_read_b128 v[204:207], v150 offset:5120
	ds_read_b128 v[208:211], v150 offset:6144
	ds_read_b128 v[212:215], v150 offset:7168
	global_load_lds_dwordx4 v[200:201], off
	v_lshl_add_u64 v[200:201], s[38:39], 0, v[138:139]
	s_add_i32 m0, s11, 0xe000
	s_nop 0
	global_load_lds_dwordx4 v[200:201], off
	s_waitcnt vmcnt(8)
	s_waitcnt lgkmcnt(0)
	s_barrier
	s_setprio 1
	v_mfma_f32_16x16x32_bf16 v[124:127], v[140:143], v[180:183], v[124:127]
	v_mfma_f32_16x16x32_bf16 v[120:123], v[156:159], v[180:183], v[120:123]
	v_mfma_f32_16x16x32_bf16 v[116:119], v[140:143], v[188:191], v[116:119]
	v_mfma_f32_16x16x32_bf16 v[108:111], v[156:159], v[188:191], v[108:111]
	v_mfma_f32_16x16x32_bf16 v[100:103], v[140:143], v[196:199], v[100:103]
	v_mfma_f32_16x16x32_bf16 v[92:95], v[156:159], v[196:199], v[92:95]
	v_mfma_f32_16x16x32_bf16 v[84:87], v[140:143], v[208:211], v[84:87]
	v_mfma_f32_16x16x32_bf16 v[76:79], v[156:159], v[208:211], v[76:79]
	v_mfma_f32_16x16x32_bf16 v[124:127], v[152:155], v[184:187], v[124:127]
	v_mfma_f32_16x16x32_bf16 v[120:123], v[160:163], v[184:187], v[120:123]
	v_mfma_f32_16x16x32_bf16 v[116:119], v[152:155], v[192:195], v[116:119]
	v_mfma_f32_16x16x32_bf16 v[108:111], v[160:163], v[192:195], v[108:111]
	v_mfma_f32_16x16x32_bf16 v[100:103], v[152:155], v[204:207], v[100:103]
	v_mfma_f32_16x16x32_bf16 v[92:95], v[160:163], v[204:207], v[92:95]
	v_mfma_f32_16x16x32_bf16 v[84:87], v[152:155], v[212:215], v[84:87]
	v_mfma_f32_16x16x32_bf16 v[76:79], v[160:163], v[212:215], v[76:79]
	v_mfma_f32_16x16x32_bf16 v[112:115], v[164:167], v[180:183], v[112:115]
	v_mfma_f32_16x16x32_bf16 v[104:107], v[172:175], v[180:183], v[104:107]
	v_mfma_f32_16x16x32_bf16 v[96:99], v[164:167], v[188:191], v[96:99]
	v_mfma_f32_16x16x32_bf16 v[88:91], v[172:175], v[188:191], v[88:91]
	v_mfma_f32_16x16x32_bf16 v[80:83], v[164:167], v[196:199], v[80:83]
	v_mfma_f32_16x16x32_bf16 v[72:75], v[172:175], v[196:199], v[72:75]
	v_mfma_f32_16x16x32_bf16 v[68:71], v[164:167], v[208:211], v[68:71]
	v_mfma_f32_16x16x32_bf16 v[64:67], v[172:175], v[208:211], v[64:67]
	v_mfma_f32_16x16x32_bf16 v[112:115], v[168:171], v[184:187], v[112:115]
	v_mfma_f32_16x16x32_bf16 v[104:107], v[176:179], v[184:187], v[104:107]
	v_mfma_f32_16x16x32_bf16 v[96:99], v[168:171], v[192:195], v[96:99]
	v_mfma_f32_16x16x32_bf16 v[88:91], v[176:179], v[192:195], v[88:91]
	v_mfma_f32_16x16x32_bf16 v[80:83], v[168:171], v[204:207], v[80:83]
	v_mfma_f32_16x16x32_bf16 v[72:75], v[176:179], v[204:207], v[72:75]
	v_mfma_f32_16x16x32_bf16 v[68:71], v[168:171], v[212:215], v[68:71]
	v_mfma_f32_16x16x32_bf16 v[64:67], v[176:179], v[212:215], v[64:67]
	s_setprio 0
	s_barrier
	s_add_i32 s55, s47, s10
	v_lshl_add_u64 v[200:201], s[40:41], 0, v[130:131]
	s_mov_b32 m0, s55
	ds_read_b128 v[180:183], v150 offset:16384
	ds_read_b128 v[184:187], v150 offset:17408
	ds_read_b128 v[188:191], v150 offset:18432
	ds_read_b128 v[192:195], v150 offset:19456
	ds_read_b128 v[196:199], v150 offset:20480
	ds_read_b128 v[204:207], v150 offset:21504
	ds_read_b128 v[208:211], v150 offset:22528
	ds_read_b128 v[212:215], v150 offset:23552
	global_load_lds_dwordx4 v[200:201], off
	s_add_i32 m0, s55, 0x2000
	s_add_u32 s56, s40, 0x40000
	v_lshl_add_u64 v[216:217], s[40:41], 0, v[134:135]
	s_addc_u32 s57, s41, 0
	s_add_i32 s55, s48, s10
	global_load_lds_dwordx4 v[216:217], off
	v_lshl_add_u64 v[218:219], s[56:57], 0, v[130:131]
	s_mov_b32 m0, s55
	v_lshl_add_u64 v[220:221], s[42:43], 0, v[132:133]
	global_load_lds_dwordx4 v[218:219], off
	v_lshl_add_u64 v[218:219], s[56:57], 0, v[134:135]
	s_add_i32 m0, s55, 0x2000
	s_nop 0
	global_load_lds_dwordx4 v[218:219], off
	v_lshl_add_u64 v[218:219], s[42:43], 0, v[128:129]
	s_mov_b32 m0, s11
	s_nop 0
	global_load_lds_dwordx4 v[218:219], off
	s_mov_b32 m0, s13
	s_nop 0
	global_load_lds_dwordx4 v[220:221], off
	s_waitcnt vmcnt(8)
	s_waitcnt lgkmcnt(0)
	s_barrier
; #define PG8_STAGE(bufoff, gbase, voff) do { _Pragma("unroll") for (int _i = 0; _i < 2; ++_i) \
;         __builtin_amdgcn_global_load_lds((const unsigned*)((const char*)(gbase) + (voff)[_i]), (LAS unsigned*)(lds + (bufoff) + ldsw + _i * 8192), 16, 0, 0); } while (0)
; #define PG8_LDA(dst, b, h) do { _Pragma("unroll") for (int m = 0; m < 4; ++m) _Pragma("unroll") for (int k = 0; k < 2; ++k) dst[m][k] = *(const LAS bf16x8*)(lds + PG8_SA(b, h) + aoff + m * 2048 + k * 1024); } while (0)
; #define PG8_LDB(dst, b, h) do { _Pragma("unroll") for (int n = 0; n < 2; ++n) _Pragma("unroll") for (int k = 0; k < 2; ++k) dst[n][k] = *(const LAS bf16x8*)(lds + PG8_SB(b, h) + boff + n * 2048 + k * 1024); } while (0)
; #define PG8_MMA(ai, bj, At, Bt) do { __builtin_amdgcn_s_setprio(1); _Pragma("unroll") for (int m = 0; m < 4; ++m) _Pragma("unroll") for (int n = 0; n < 2; ++n) _Pragma("unroll") for (int k = 0; k < 2; ++k) \
;         acc[ai][bj][m][n] = __builtin_amdgcn_mfma_f32_16x16x32_bf16(Bt[n][k], At[m][k], acc[ai][bj][m][n], 0, 0, 0); __builtin_amdgcn_s_setprio(0); } while (0)
; #define PG8_WAIT_V(n) asm volatile("s_waitcnt vmcnt(" #n ")" ::: "memory")
; #define PG8_WAIT_L(n) asm volatile("s_waitcnt lgkmcnt(" #n ")" ::: "memory")
; #define PG8_BAR __builtin_amdgcn_s_barrier()
; #define PG8_SCHED __builtin_amdgcn_sched_barrier(0)
; template <class Epi>
; __device__ __forceinline__ void gemm_phase(LAS unsigned char* lds, const Gemm g, const Sched& S, const Epi& E) {
;     ...
;             PG8_WAIT_V(8); PG8_WAIT_L(0); PG8_BAR; PG8_MMA(1, 0, At, B0); PG8_MMA(1, 1, At, B1); PG8_BAR; PG8_SCHED;
;             PG8_LDB(B0, 1, 0); PG8_LDB(B1, 1, 1); PG8_SCHED; PG8_LDA(At, 1, 0); PG8_STAGE(PG8_SA(0, 1), a2 + hstepA, voffA);
;             PG8_WAIT_V(8); PG8_WAIT_L(0); PG8_BAR; PG8_MMA(0, 0, At, B0); PG8_MMA(0, 1, At, B1); PG8_BAR; PG8_SCHED;
	s_setprio 1
	v_mfma_f32_16x16x32_bf16 v[60:63], v[140:143], v[180:183], v[60:63]
	v_mfma_f32_16x16x32_bf16 v[56:59], v[156:159], v[180:183], v[56:59]
	v_mfma_f32_16x16x32_bf16 v[52:55], v[140:143], v[188:191], v[52:55]
	v_mfma_f32_16x16x32_bf16 v[44:47], v[156:159], v[188:191], v[44:47]
	v_mfma_f32_16x16x32_bf16 v[36:39], v[140:143], v[196:199], v[36:39]
	v_mfma_f32_16x16x32_bf16 v[28:31], v[156:159], v[196:199], v[28:31]
	v_mfma_f32_16x16x32_bf16 v[20:23], v[140:143], v[208:211], v[20:23]
	v_mfma_f32_16x16x32_bf16 v[12:15], v[156:159], v[208:211], v[12:15]
	v_mfma_f32_16x16x32_bf16 v[60:63], v[152:155], v[184:187], v[60:63]
	v_mfma_f32_16x16x32_bf16 v[56:59], v[160:163], v[184:187], v[56:59]
	v_mfma_f32_16x16x32_bf16 v[52:55], v[152:155], v[192:195], v[52:55]
	v_mfma_f32_16x16x32_bf16 v[44:47], v[160:163], v[192:195], v[44:47]
	v_mfma_f32_16x16x32_bf16 v[36:39], v[152:155], v[204:207], v[36:39]
	v_mfma_f32_16x16x32_bf16 v[28:31], v[160:163], v[204:207], v[28:31]
	v_mfma_f32_16x16x32_bf16 v[20:23], v[152:155], v[212:215], v[20:23]
	v_mfma_f32_16x16x32_bf16 v[12:15], v[160:163], v[212:215], v[12:15]
	v_mfma_f32_16x16x32_bf16 v[48:51], v[164:167], v[180:183], v[48:51]
	v_mfma_f32_16x16x32_bf16 v[40:43], v[172:175], v[180:183], v[40:43]
	v_mfma_f32_16x16x32_bf16 v[32:35], v[164:167], v[188:191], v[32:35]
	v_mfma_f32_16x16x32_bf16 v[24:27], v[172:175], v[188:191], v[24:27]
	v_mfma_f32_16x16x32_bf16 v[16:19], v[164:167], v[196:199], v[16:19]
	v_mfma_f32_16x16x32_bf16 v[8:11], v[172:175], v[196:199], v[8:11]
	v_mfma_f32_16x16x32_bf16 v[4:7], v[164:167], v[208:211], v[4:7]
	v_mfma_f32_16x16x32_bf16 v[0:3], v[172:175], v[208:211], v[0:3]
	v_mfma_f32_16x16x32_bf16 v[48:51], v[168:171], v[184:187], v[48:51]
	v_mfma_f32_16x16x32_bf16 v[40:43], v[176:179], v[184:187], v[40:43]
	v_mfma_f32_16x16x32_bf16 v[32:35], v[168:171], v[192:195], v[32:35]
	v_mfma_f32_16x16x32_bf16 v[24:27], v[176:179], v[192:195], v[24:27]
	v_mfma_f32_16x16x32_bf16 v[16:19], v[168:171], v[204:207], v[16:19]
	v_mfma_f32_16x16x32_bf16 v[8:11], v[176:179], v[204:207], v[8:11]
	v_mfma_f32_16x16x32_bf16 v[4:7], v[168:171], v[212:215], v[4:7]
	v_mfma_f32_16x16x32_bf16 v[0:3], v[176:179], v[212:215], v[0:3]
	s_setprio 0
	s_barrier
	s_add_i32 s55, 0, 0x18000
	v_add_u32_e32 v151, s55, v146
	s_add_i32 s56, 0, 0x1c000
	ds_read_b128 v[140:143], v151
	ds_read_b128 v[152:155], v151 offset:1024
	ds_read_b128 v[156:159], v151 offset:2048
	ds_read_b128 v[160:163], v151 offset:3072
	v_add_u32_e32 v151, s56, v146
	ds_read_b128 v[164:167], v151
	ds_read_b128 v[168:171], v151 offset:1024
	ds_read_b128 v[172:175], v151 offset:2048
	ds_read_b128 v[176:179], v151 offset:3072
	s_add_u32 s42, s42, 0x40000
	s_addc_u32 s43, s43, 0
	s_mov_b32 m0, s19
	v_lshl_add_u64 v[222:223], s[42:43], 0, v[128:129]
	ds_read_b128 v[180:183], v150 offset:32768
	ds_read_b128 v[184:187], v150 offset:33792
	ds_read_b128 v[188:191], v150 offset:34816
	ds_read_b128 v[192:195], v150 offset:35840
	ds_read_b128 v[196:199], v150 offset:36864
	ds_read_b128 v[204:207], v150 offset:37888
	ds_read_b128 v[208:211], v150 offset:38912
	ds_read_b128 v[212:215], v150 offset:39936
	global_load_lds_dwordx4 v[222:223], off
	v_lshl_add_u64 v[222:223], s[42:43], 0, v[132:133]
	s_mov_b32 m0, s37
	s_nop 0
	global_load_lds_dwordx4 v[222:223], off
	s_waitcnt vmcnt(8)
	s_waitcnt lgkmcnt(0)
	s_barrier
	s_setprio 1
	v_mfma_f32_16x16x32_bf16 v[124:127], v[140:143], v[180:183], v[124:127]
	v_mfma_f32_16x16x32_bf16 v[120:123], v[156:159], v[180:183], v[120:123]
	v_mfma_f32_16x16x32_bf16 v[116:119], v[140:143], v[188:191], v[116:119]
	v_mfma_f32_16x16x32_bf16 v[108:111], v[156:159], v[188:191], v[108:111]
	v_mfma_f32_16x16x32_bf16 v[100:103], v[140:143], v[196:199], v[100:103]
	v_mfma_f32_16x16x32_bf16 v[92:95], v[156:159], v[196:199], v[92:95]
	v_mfma_f32_16x16x32_bf16 v[84:87], v[140:143], v[208:211], v[84:87]
	v_mfma_f32_16x16x32_bf16 v[76:79], v[156:159], v[208:211], v[76:79]
	v_mfma_f32_16x16x32_bf16 v[124:127], v[152:155], v[184:187], v[124:127]
	v_mfma_f32_16x16x32_bf16 v[120:123], v[160:163], v[184:187], v[120:123]
	v_mfma_f32_16x16x32_bf16 v[116:119], v[152:155], v[192:195], v[116:119]
	v_mfma_f32_16x16x32_bf16 v[108:111], v[160:163], v[192:195], v[108:111]
	v_mfma_f32_16x16x32_bf16 v[100:103], v[152:155], v[204:207], v[100:103]
	v_mfma_f32_16x16x32_bf16 v[92:95], v[160:163], v[204:207], v[92:95]
	v_mfma_f32_16x16x32_bf16 v[84:87], v[152:155], v[212:215], v[84:87]
	v_mfma_f32_16x16x32_bf16 v[76:79], v[160:163], v[212:215], v[76:79]
	v_mfma_f32_16x16x32_bf16 v[112:115], v[164:167], v[180:183], v[112:115]
	v_mfma_f32_16x16x32_bf16 v[104:107], v[172:175], v[180:183], v[104:107]
	v_mfma_f32_16x16x32_bf16 v[96:99], v[164:167], v[188:191], v[96:99]
	v_mfma_f32_16x16x32_bf16 v[88:91], v[172:175], v[188:191], v[88:91]
	v_mfma_f32_16x16x32_bf16 v[80:83], v[164:167], v[196:199], v[80:83]
	v_mfma_f32_16x16x32_bf16 v[72:75], v[172:175], v[196:199], v[72:75]
	v_mfma_f32_16x16x32_bf16 v[68:71], v[164:167], v[208:211], v[68:71]
	v_mfma_f32_16x16x32_bf16 v[64:67], v[172:175], v[208:211], v[64:67]
	v_mfma_f32_16x16x32_bf16 v[112:115], v[168:171], v[184:187], v[112:115]
	v_mfma_f32_16x16x32_bf16 v[104:107], v[176:179], v[184:187], v[104:107]
	v_mfma_f32_16x16x32_bf16 v[96:99], v[168:171], v[192:195], v[96:99]
	v_mfma_f32_16x16x32_bf16 v[88:91], v[176:179], v[192:195], v[88:91]
	v_mfma_f32_16x16x32_bf16 v[80:83], v[168:171], v[204:207], v[80:83]
	v_mfma_f32_16x16x32_bf16 v[72:75], v[176:179], v[204:207], v[72:75]
	v_mfma_f32_16x16x32_bf16 v[68:71], v[168:171], v[212:215], v[68:71]
	v_mfma_f32_16x16x32_bf16 v[64:67], v[176:179], v[212:215], v[64:67]
	s_setprio 0
	s_barrier
; #define PG8_STAGE(bufoff, gbase, voff) do { _Pragma("unroll") for (int _i = 0; _i < 2; ++_i) \
;         __builtin_amdgcn_global_load_lds((const unsigned*)((const char*)(gbase) + (voff)[_i]), (LAS unsigned*)(lds + (bufoff) + ldsw + _i * 8192), 16, 0, 0); } while (0)
; #define PG8_LDA(dst, b, h) do { _Pragma("unroll") for (int m = 0; m < 4; ++m) _Pragma("unroll") for (int k = 0; k < 2; ++k) dst[m][k] = *(const LAS bf16x8*)(lds + PG8_SA(b, h) + aoff + m * 2048 + k * 1024); } while (0)
; #define PG8_MMA(ai, bj, At, Bt) do { __builtin_amdgcn_s_setprio(1); _Pragma("unroll") for (int m = 0; m < 4; ++m) _Pragma("unroll") for (int n = 0; n < 2; ++n) _Pragma("unroll") for (int k = 0; k < 2; ++k) \
;         acc[ai][bj][m][n] = __builtin_amdgcn_mfma_f32_16x16x32_bf16(Bt[n][k], At[m][k], acc[ai][bj][m][n], 0, 0, 0); __builtin_amdgcn_s_setprio(0); } while (0)
; #define PG8_WAIT_V(n) asm volatile("s_waitcnt vmcnt(" #n ")" ::: "memory")
; #define PG8_WAIT_L(n) asm volatile("s_waitcnt lgkmcnt(" #n ")" ::: "memory")
; #define PG8_BAR __builtin_amdgcn_s_barrier()
; #define PG8_SCHED __builtin_amdgcn_sched_barrier(0)
; template <class Epi>
; __device__ __forceinline__ void gemm_phase(LAS unsigned char* lds, const Gemm g, const Sched& S, const Epi& E) {
;     ...
;             PG8_LDA(At, 1, 1); PG8_STAGE(PG8_SB(1, 0), b3, voffB); PG8_STAGE(PG8_SB(1, 1), b3 + hstepB, voffB); PG8_STAGE(PG8_SA(1, 0), a3, voffA);
;             PG8_WAIT_V(8); PG8_WAIT_L(0); PG8_BAR; PG8_MMA(1, 0, At, B0); PG8_MMA(1, 1, At, B1); PG8_BAR; PG8_SCHED;
;         }
;         if (wr == 0) PG8_BAR;
	s_add_i32 s42, s55, s10
	v_lshl_add_u64 v[200:201], v[200:201], 0, s[14:15]
	s_mov_b32 m0, s42
	ds_read_b128 v[180:183], v150 offset:49152
	ds_read_b128 v[184:187], v150 offset:50176
	ds_read_b128 v[188:191], v150 offset:51200
	ds_read_b128 v[192:195], v150 offset:52224
	ds_read_b128 v[196:199], v150 offset:53248
	ds_read_b128 v[204:207], v150 offset:54272
	ds_read_b128 v[208:211], v150 offset:55296
	ds_read_b128 v[212:215], v150 offset:56320
	global_load_lds_dwordx4 v[200:201], off
	s_add_i32 m0, s42, 0x2000
	s_add_u32 s40, s40, 0x40080
	v_lshl_add_u64 v[200:201], v[216:217], 0, s[14:15]
	s_addc_u32 s41, s41, 0
	s_add_i32 s42, s56, s10
	global_load_lds_dwordx4 v[200:201], off
	v_lshl_add_u64 v[200:201], s[40:41], 0, v[130:131]
	s_mov_b32 m0, s42
	s_nop 0
	global_load_lds_dwordx4 v[200:201], off
	v_lshl_add_u64 v[200:201], s[40:41], 0, v[134:135]
	s_add_i32 m0, s42, 0x2000
	s_nop 0
	global_load_lds_dwordx4 v[200:201], off
	v_lshl_add_u64 v[200:201], v[218:219], 0, s[14:15]
	s_mov_b32 m0, s45
	s_nop 0
	global_load_lds_dwordx4 v[200:201], off
	v_lshl_add_u64 v[200:201], v[220:221], 0, s[14:15]
	s_mov_b32 m0, s46
	s_nop 0
	global_load_lds_dwordx4 v[200:201], off
	s_waitcnt vmcnt(8)
	s_waitcnt lgkmcnt(0)
	s_barrier
	s_setprio 1
	v_mfma_f32_16x16x32_bf16 v[60:63], v[140:143], v[180:183], v[60:63]
	v_mfma_f32_16x16x32_bf16 v[56:59], v[156:159], v[180:183], v[56:59]
	v_mfma_f32_16x16x32_bf16 v[52:55], v[140:143], v[188:191], v[52:55]
	v_mfma_f32_16x16x32_bf16 v[44:47], v[156:159], v[188:191], v[44:47]
	v_mfma_f32_16x16x32_bf16 v[36:39], v[140:143], v[196:199], v[36:39]
	v_mfma_f32_16x16x32_bf16 v[28:31], v[156:159], v[196:199], v[28:31]
	v_mfma_f32_16x16x32_bf16 v[20:23], v[140:143], v[208:211], v[20:23]
	v_mfma_f32_16x16x32_bf16 v[12:15], v[156:159], v[208:211], v[12:15]
	v_mfma_f32_16x16x32_bf16 v[60:63], v[152:155], v[184:187], v[60:63]
	v_mfma_f32_16x16x32_bf16 v[56:59], v[160:163], v[184:187], v[56:59]
	v_mfma_f32_16x16x32_bf16 v[52:55], v[152:155], v[192:195], v[52:55]
	v_mfma_f32_16x16x32_bf16 v[44:47], v[160:163], v[192:195], v[44:47]
	v_mfma_f32_16x16x32_bf16 v[36:39], v[152:155], v[204:207], v[36:39]
	v_mfma_f32_16x16x32_bf16 v[28:31], v[160:163], v[204:207], v[28:31]
	v_mfma_f32_16x16x32_bf16 v[20:23], v[152:155], v[212:215], v[20:23]
	v_mfma_f32_16x16x32_bf16 v[12:15], v[160:163], v[212:215], v[12:15]
	v_mfma_f32_16x16x32_bf16 v[48:51], v[164:167], v[180:183], v[48:51]
	v_mfma_f32_16x16x32_bf16 v[40:43], v[172:175], v[180:183], v[40:43]
	v_mfma_f32_16x16x32_bf16 v[32:35], v[164:167], v[188:191], v[32:35]
	v_mfma_f32_16x16x32_bf16 v[24:27], v[172:175], v[188:191], v[24:27]
	v_mfma_f32_16x16x32_bf16 v[16:19], v[164:167], v[196:199], v[16:19]
	v_mfma_f32_16x16x32_bf16 v[8:11], v[172:175], v[196:199], v[8:11]
	v_mfma_f32_16x16x32_bf16 v[4:7], v[164:167], v[208:211], v[4:7]
	v_mfma_f32_16x16x32_bf16 v[0:3], v[172:175], v[208:211], v[0:3]
	v_mfma_f32_16x16x32_bf16 v[48:51], v[168:171], v[184:187], v[48:51]
	v_mfma_f32_16x16x32_bf16 v[40:43], v[176:179], v[184:187], v[40:43]
	v_mfma_f32_16x16x32_bf16 v[32:35], v[168:171], v[192:195], v[32:35]
	v_mfma_f32_16x16x32_bf16 v[24:27], v[176:179], v[192:195], v[24:27]
	v_mfma_f32_16x16x32_bf16 v[16:19], v[168:171], v[204:207], v[16:19]
	v_mfma_f32_16x16x32_bf16 v[8:11], v[176:179], v[204:207], v[8:11]
	v_mfma_f32_16x16x32_bf16 v[4:7], v[168:171], v[212:215], v[4:7]
	v_mfma_f32_16x16x32_bf16 v[0:3], v[176:179], v[212:215], v[0:3]
	s_setprio 0
	s_barrier
	s_add_i32 s54, s54, 2
	s_add_u32 s38, s38, 0x100
	s_addc_u32 s39, s39, 0
	s_add_u32 s52, s52, 0x100
	s_addc_u32 s53, s53, 0
	s_cmp_gt_u32 s54, 13
	s_cbranch_scc0 .LBB0_1355
	s_and_b64 vcc, exec, s[16:17]
	s_cbranch_vccz .LBB0_1358
	s_barrier

; #define PG8_STAGE(bufoff, gbase, voff) do { _Pragma("unroll") for (int _i = 0; _i < 2; ++_i) \
;         __builtin_amdgcn_global_load_lds((const unsigned*)((const char*)(gbase) + (voff)[_i]), (LAS unsigned*)(lds + (bufoff) + ldsw + _i * 8192), 16, 0, 0); } while (0)
; #define PG8_LDA(dst, b, h) do { _Pragma("unroll") for (int m = 0; m < 4; ++m) _Pragma("unroll") for (int k = 0; k < 2; ++k) dst[m][k] = *(const LAS bf16x8*)(lds + PG8_SA(b, h) + aoff + m * 2048 + k * 1024); } while (0)
; #define PG8_LDB(dst, b, h) do { _Pragma("unroll") for (int n = 0; n < 2; ++n) _Pragma("unroll") for (int k = 0; k < 2; ++k) dst[n][k] = *(const LAS bf16x8*)(lds + PG8_SB(b, h) + boff + n * 2048 + k * 1024); } while (0)
; #define PG8_MMA(ai, bj, At, Bt) do { __builtin_amdgcn_s_setprio(1); _Pragma("unroll") for (int m = 0; m < 4; ++m) _Pragma("unroll") for (int n = 0; n < 2; ++n) _Pragma("unroll") for (int k = 0; k < 2; ++k) \
;         acc[ai][bj][m][n] = __builtin_amdgcn_mfma_f32_16x16x32_bf16(Bt[n][k], At[m][k], acc[ai][bj][m][n], 0, 0, 0); __builtin_amdgcn_s_setprio(0); } while (0)
; #define PG8_BAR __builtin_amdgcn_s_barrier()
; template <class Epi>
; __device__ __forceinline__ void gemm_phase(LAS unsigned char* lds, const Gemm g, const Sched& S, const Epi& E) {
;     ...
;         const bool has_next = S.next(ui + 1, nxt);
;         const char* nA = has_next ? (const char*)g.A + (size_t)S.aoff(nxt) * 2 : cA; const char* nB = has_next ? (const char*)g.Bt + (size_t)S.boff(nxt) * 2 : cB;
;         _Pragma("nounroll")
;         for (int t = 0; t < nt; t += 2) {
;             const bool last = (t == nt - 2);
;             const char* a1 = cA + (size_t)(t + 1) * kstep;
;             const char* a2 = last ? nA : cA + (size_t)(t + 2) * kstep; const char* b2 = last ? nB : cB + (size_t)(t + 2) * kstep;
;             const char* a3 = a2 + kstep; const char* b3 = b2 + kstep;
;             PG8_LDB(B0, 0, 0); PG8_LDB(B1, 0, 1); PG8_SCHED; PG8_LDA(At, 0, 0); PG8_STAGE(PG8_SA(1, 1), a1 + hstepA, voffA);
;             PG8_WAIT_V(8); PG8_WAIT_L(0); PG8_BAR; PG8_MMA(0, 0, At, B0); PG8_MMA(0, 1, At, B1); PG8_BAR; PG8_SCHED;
;             PG8_LDA(At, 0, 1); PG8_STAGE(PG8_SB(0, 0), b2, voffB); PG8_STAGE(PG8_SB(0, 1), b2 + hstepB, voffB); PG8_STAGE(PG8_SA(0, 0), a2, voffA);
;             PG8_WAIT_V(8); PG8_WAIT_L(0); PG8_BAR; PG8_MMA(1, 0, At, B0); PG8_MMA(1, 1, At, B1); PG8_BAR; PG8_SCHED;
.LBB0_1381:
	s_add_u32 s52, s18, s46
	s_addc_u32 s53, s19, s47
	s_add_u32 s50, s52, 0x100
	s_addc_u32 s51, s53, 0
	s_and_b64 s[48:49], s[44:45], exec
	s_cselect_b32 s49, s29, s51
	s_cselect_b32 s48, s70, s50
	s_add_u32 s46, s20, s46
	s_addc_u32 s47, s21, s47
	s_add_u32 s46, s46, 0x100
	s_addc_u32 s47, s47, 0
	s_and_b64 s[44:45], s[44:45], exec
	s_cselect_b32 s51, s39, s47
	s_cselect_b32 s50, s38, s46
	s_add_u32 s54, s52, 0x40080
	s_addc_u32 s55, s53, 0
	s_add_i32 s78, s66, s57
	s_add_i32 m0, s17, 0xc000
	s_add_i32 s81, s17, 0xe000
	s_add_i32 s75, s78, 0x2000
	v_add_u32_e32 v142, s66, v140
	s_add_u32 s52, s50, 0x40000
	ds_read_b128 v[146:149], v142
	ds_read_b128 v[150:153], v142 offset:1024
	ds_read_b128 v[154:157], v142 offset:2048
	ds_read_b128 v[158:161], v142 offset:3072
	v_add_u32_e32 v142, s67, v140
	s_addc_u32 s53, s51, 0
	s_add_i32 s77, s67, s57
	ds_read_b128 v[162:165], v142
	ds_read_b128 v[166:169], v142 offset:1024
	ds_read_b128 v[170:173], v142 offset:2048
	ds_read_b128 v[174:177], v142 offset:3072
	s_add_i32 s76, s77, 0x2000
	s_add_i32 s74, 0, 0x18000
	s_add_i32 s73, 0, 0x1c000
	s_add_u32 s46, s48, 0x40000
	s_addc_u32 s47, s49, 0
	s_add_i32 s72, s74, s57
	s_add_i32 s71, s72, 0x2000
	s_add_u32 s44, s50, 0x40080
	s_addc_u32 s45, s51, 0
	s_add_i32 s80, s73, s57
	s_add_i32 s79, s80, 0x2000
	v_lshl_add_u64 v[142:143], s[54:55], 0, v[128:129]
	ds_read_b128 v[178:181], v141
	ds_read_b128 v[182:185], v141 offset:1024
	ds_read_b128 v[186:189], v141 offset:2048
	ds_read_b128 v[190:193], v141 offset:3072
	ds_read_b128 v[194:197], v141 offset:4096
	ds_read_b128 v[198:201], v141 offset:5120
	ds_read_b128 v[204:207], v141 offset:6144
	ds_read_b128 v[208:211], v141 offset:7168
	global_load_lds_dwordx4 v[142:143], off
	v_lshl_add_u64 v[142:143], s[54:55], 0, v[132:133]
	s_mov_b32 m0, s81
	s_nop 0
	global_load_lds_dwordx4 v[142:143], off
	s_waitcnt vmcnt(8)
	s_waitcnt lgkmcnt(0)
	s_barrier
	s_setprio 1
	v_mfma_f32_16x16x32_bf16 v[124:127], v[146:149], v[178:181], v[124:127]
	v_mfma_f32_16x16x32_bf16 v[120:123], v[154:157], v[178:181], v[120:123]
	v_mfma_f32_16x16x32_bf16 v[112:115], v[146:149], v[186:189], v[112:115]
	v_mfma_f32_16x16x32_bf16 v[108:111], v[154:157], v[186:189], v[108:111]
	v_mfma_f32_16x16x32_bf16 v[100:103], v[146:149], v[194:197], v[100:103]
	v_mfma_f32_16x16x32_bf16 v[92:95], v[154:157], v[194:197], v[92:95]
	v_mfma_f32_16x16x32_bf16 v[84:87], v[146:149], v[204:207], v[84:87]
	v_mfma_f32_16x16x32_bf16 v[76:79], v[154:157], v[204:207], v[76:79]
	v_mfma_f32_16x16x32_bf16 v[124:127], v[150:153], v[182:185], v[124:127]
	v_mfma_f32_16x16x32_bf16 v[120:123], v[158:161], v[182:185], v[120:123]
	v_mfma_f32_16x16x32_bf16 v[112:115], v[150:153], v[190:193], v[112:115]
	v_mfma_f32_16x16x32_bf16 v[108:111], v[158:161], v[190:193], v[108:111]
	v_mfma_f32_16x16x32_bf16 v[100:103], v[150:153], v[198:201], v[100:103]
	v_mfma_f32_16x16x32_bf16 v[92:95], v[158:161], v[198:201], v[92:95]
	v_mfma_f32_16x16x32_bf16 v[84:87], v[150:153], v[208:211], v[84:87]
	v_mfma_f32_16x16x32_bf16 v[76:79], v[158:161], v[208:211], v[76:79]
	v_mfma_f32_16x16x32_bf16 v[116:119], v[162:165], v[178:181], v[116:119]
	v_mfma_f32_16x16x32_bf16 v[104:107], v[170:173], v[178:181], v[104:107]
	v_mfma_f32_16x16x32_bf16 v[96:99], v[162:165], v[186:189], v[96:99]
	v_mfma_f32_16x16x32_bf16 v[88:91], v[170:173], v[186:189], v[88:91]
	v_mfma_f32_16x16x32_bf16 v[80:83], v[162:165], v[194:197], v[80:83]
	v_mfma_f32_16x16x32_bf16 v[72:75], v[170:173], v[194:197], v[72:75]
	v_mfma_f32_16x16x32_bf16 v[68:71], v[162:165], v[204:207], v[68:71]
	v_mfma_f32_16x16x32_bf16 v[64:67], v[170:173], v[204:207], v[64:67]
	v_mfma_f32_16x16x32_bf16 v[116:119], v[166:169], v[182:185], v[116:119]
	v_mfma_f32_16x16x32_bf16 v[104:107], v[174:177], v[182:185], v[104:107]
	v_mfma_f32_16x16x32_bf16 v[96:99], v[166:169], v[190:193], v[96:99]
	v_mfma_f32_16x16x32_bf16 v[88:91], v[174:177], v[190:193], v[88:91]
	v_mfma_f32_16x16x32_bf16 v[80:83], v[166:169], v[198:201], v[80:83]
	v_mfma_f32_16x16x32_bf16 v[72:75], v[174:177], v[198:201], v[72:75]
	v_mfma_f32_16x16x32_bf16 v[68:71], v[166:169], v[208:211], v[68:71]
	v_mfma_f32_16x16x32_bf16 v[64:67], v[174:177], v[208:211], v[64:67]
	s_setprio 0
	s_barrier
	s_mov_b32 m0, s78
	v_lshl_add_u64 v[142:143], s[50:51], 0, v[130:131]
	ds_read_b128 v[178:181], v141 offset:16384
	ds_read_b128 v[182:185], v141 offset:17408
	ds_read_b128 v[186:189], v141 offset:18432
	ds_read_b128 v[190:193], v141 offset:19456
	ds_read_b128 v[194:197], v141 offset:20480
	ds_read_b128 v[198:201], v141 offset:21504
	ds_read_b128 v[204:207], v141 offset:22528
	ds_read_b128 v[208:211], v141 offset:23552
	global_load_lds_dwordx4 v[142:143], off
	v_lshl_add_u64 v[212:213], s[50:51], 0, v[134:135]
	s_mov_b32 m0, s75
	v_lshl_add_u64 v[214:215], s[52:53], 0, v[130:131]
	global_load_lds_dwordx4 v[212:213], off
	s_mov_b32 m0, s77
	v_lshl_add_u64 v[216:217], s[48:49], 0, v[132:133]
	global_load_lds_dwordx4 v[214:215], off
	v_lshl_add_u64 v[214:215], s[52:53], 0, v[134:135]
	s_mov_b32 m0, s76
	s_nop 0
	global_load_lds_dwordx4 v[214:215], off
	v_lshl_add_u64 v[214:215], s[48:49], 0, v[128:129]
	s_mov_b32 m0, s17
	s_nop 0
	global_load_lds_dwordx4 v[214:215], off
	s_mov_b32 m0, s60
	s_nop 0
	global_load_lds_dwordx4 v[216:217], off
	s_waitcnt vmcnt(8)
	s_waitcnt lgkmcnt(0)
	s_barrier
; #define PG8_STAGE(bufoff, gbase, voff) do { _Pragma("unroll") for (int _i = 0; _i < 2; ++_i) \
;         __builtin_amdgcn_global_load_lds((const unsigned*)((const char*)(gbase) + (voff)[_i]), (LAS unsigned*)(lds + (bufoff) + ldsw + _i * 8192), 16, 0, 0); } while (0)
; #define PG8_LDA(dst, b, h) do { _Pragma("unroll") for (int m = 0; m < 4; ++m) _Pragma("unroll") for (int k = 0; k < 2; ++k) dst[m][k] = *(const LAS bf16x8*)(lds + PG8_SA(b, h) + aoff + m * 2048 + k * 1024); } while (0)
; #define PG8_LDB(dst, b, h) do { _Pragma("unroll") for (int n = 0; n < 2; ++n) _Pragma("unroll") for (int k = 0; k < 2; ++k) dst[n][k] = *(const LAS bf16x8*)(lds + PG8_SB(b, h) + boff + n * 2048 + k * 1024); } while (0)
; #define PG8_MMA(ai, bj, At, Bt) do { __builtin_amdgcn_s_setprio(1); _Pragma("unroll") for (int m = 0; m < 4; ++m) _Pragma("unroll") for (int n = 0; n < 2; ++n) _Pragma("unroll") for (int k = 0; k < 2; ++k) \
;         acc[ai][bj][m][n] = __builtin_amdgcn_mfma_f32_16x16x32_bf16(Bt[n][k], At[m][k], acc[ai][bj][m][n], 0, 0, 0); __builtin_amdgcn_s_setprio(0); } while (0)
; #define PG8_WAIT_V(n) asm volatile("s_waitcnt vmcnt(" #n ")" ::: "memory")
; #define PG8_WAIT_L(n) asm volatile("s_waitcnt lgkmcnt(" #n ")" ::: "memory")
; #define PG8_BAR __builtin_amdgcn_s_barrier()
; #define PG8_SCHED __builtin_amdgcn_sched_barrier(0)
; template <class Epi>
; __device__ __forceinline__ void gemm_phase(LAS unsigned char* lds, const Gemm g, const Sched& S, const Epi& E) {
;     ...
;             PG8_WAIT_V(8); PG8_WAIT_L(0); PG8_BAR; PG8_MMA(1, 0, At, B0); PG8_MMA(1, 1, At, B1); PG8_BAR; PG8_SCHED;
;             PG8_LDB(B0, 1, 0); PG8_LDB(B1, 1, 1); PG8_SCHED; PG8_LDA(At, 1, 0); PG8_STAGE(PG8_SA(0, 1), a2 + hstepA, voffA);
;             PG8_WAIT_V(8); PG8_WAIT_L(0); PG8_BAR; PG8_MMA(0, 0, At, B0); PG8_MMA(0, 1, At, B1); PG8_BAR; PG8_SCHED;
	s_setprio 1
	v_mfma_f32_16x16x32_bf16 v[60:63], v[146:149], v[178:181], v[60:63]
	v_mfma_f32_16x16x32_bf16 v[56:59], v[154:157], v[178:181], v[56:59]
	v_mfma_f32_16x16x32_bf16 v[52:55], v[146:149], v[186:189], v[52:55]
	v_mfma_f32_16x16x32_bf16 v[44:47], v[154:157], v[186:189], v[44:47]
	v_mfma_f32_16x16x32_bf16 v[36:39], v[146:149], v[194:197], v[36:39]
	v_mfma_f32_16x16x32_bf16 v[28:31], v[154:157], v[194:197], v[28:31]
	v_mfma_f32_16x16x32_bf16 v[20:23], v[146:149], v[204:207], v[20:23]
	v_mfma_f32_16x16x32_bf16 v[12:15], v[154:157], v[204:207], v[12:15]
	v_mfma_f32_16x16x32_bf16 v[60:63], v[150:153], v[182:185], v[60:63]
	v_mfma_f32_16x16x32_bf16 v[56:59], v[158:161], v[182:185], v[56:59]
	v_mfma_f32_16x16x32_bf16 v[52:55], v[150:153], v[190:193], v[52:55]
	v_mfma_f32_16x16x32_bf16 v[44:47], v[158:161], v[190:193], v[44:47]
	v_mfma_f32_16x16x32_bf16 v[36:39], v[150:153], v[198:201], v[36:39]
	v_mfma_f32_16x16x32_bf16 v[28:31], v[158:161], v[198:201], v[28:31]
	v_mfma_f32_16x16x32_bf16 v[20:23], v[150:153], v[208:211], v[20:23]
	v_mfma_f32_16x16x32_bf16 v[12:15], v[158:161], v[208:211], v[12:15]
	v_mfma_f32_16x16x32_bf16 v[48:51], v[162:165], v[178:181], v[48:51]
	v_mfma_f32_16x16x32_bf16 v[40:43], v[170:173], v[178:181], v[40:43]
	v_mfma_f32_16x16x32_bf16 v[32:35], v[162:165], v[186:189], v[32:35]
	v_mfma_f32_16x16x32_bf16 v[24:27], v[170:173], v[186:189], v[24:27]
	v_mfma_f32_16x16x32_bf16 v[16:19], v[162:165], v[194:197], v[16:19]
	v_mfma_f32_16x16x32_bf16 v[8:11], v[170:173], v[194:197], v[8:11]
	v_mfma_f32_16x16x32_bf16 v[4:7], v[162:165], v[204:207], v[4:7]
	v_mfma_f32_16x16x32_bf16 v[0:3], v[170:173], v[204:207], v[0:3]
	v_mfma_f32_16x16x32_bf16 v[48:51], v[166:169], v[182:185], v[48:51]
	v_mfma_f32_16x16x32_bf16 v[40:43], v[174:177], v[182:185], v[40:43]
	v_mfma_f32_16x16x32_bf16 v[32:35], v[166:169], v[190:193], v[32:35]
	v_mfma_f32_16x16x32_bf16 v[24:27], v[174:177], v[190:193], v[24:27]
	v_mfma_f32_16x16x32_bf16 v[16:19], v[166:169], v[198:201], v[16:19]
	v_mfma_f32_16x16x32_bf16 v[8:11], v[174:177], v[198:201], v[8:11]
	v_mfma_f32_16x16x32_bf16 v[4:7], v[166:169], v[208:211], v[4:7]
	v_mfma_f32_16x16x32_bf16 v[0:3], v[174:177], v[208:211], v[0:3]
	s_setprio 0
	s_barrier
	v_add_u32_e32 v145, s74, v140
	ds_read_b128 v[146:149], v145
	ds_read_b128 v[150:153], v145 offset:1024
	ds_read_b128 v[154:157], v145 offset:2048
	ds_read_b128 v[158:161], v145 offset:3072
	v_add_u32_e32 v145, s73, v140
	ds_read_b128 v[162:165], v145
	ds_read_b128 v[166:169], v145 offset:1024
	ds_read_b128 v[170:173], v145 offset:2048
	ds_read_b128 v[174:177], v145 offset:3072
	s_mov_b32 m0, s61
	v_lshl_add_u64 v[218:219], s[46:47], 0, v[128:129]
	ds_read_b128 v[178:181], v141 offset:32768
	ds_read_b128 v[182:185], v141 offset:33792
	ds_read_b128 v[186:189], v141 offset:34816
	ds_read_b128 v[190:193], v141 offset:35840
	ds_read_b128 v[194:197], v141 offset:36864
	ds_read_b128 v[198:201], v141 offset:37888
	ds_read_b128 v[204:207], v141 offset:38912
	ds_read_b128 v[208:211], v141 offset:39936
	global_load_lds_dwordx4 v[218:219], off
	v_lshl_add_u64 v[218:219], s[46:47], 0, v[132:133]
	s_mov_b32 m0, s62
	s_nop 0
	global_load_lds_dwordx4 v[218:219], off
	s_waitcnt vmcnt(8)
	s_waitcnt lgkmcnt(0)
	s_barrier
	s_setprio 1
	v_mfma_f32_16x16x32_bf16 v[124:127], v[146:149], v[178:181], v[124:127]
	v_mfma_f32_16x16x32_bf16 v[120:123], v[154:157], v[178:181], v[120:123]
	v_mfma_f32_16x16x32_bf16 v[112:115], v[146:149], v[186:189], v[112:115]
	v_mfma_f32_16x16x32_bf16 v[108:111], v[154:157], v[186:189], v[108:111]
	v_mfma_f32_16x16x32_bf16 v[100:103], v[146:149], v[194:197], v[100:103]
	v_mfma_f32_16x16x32_bf16 v[92:95], v[154:157], v[194:197], v[92:95]
	v_mfma_f32_16x16x32_bf16 v[84:87], v[146:149], v[204:207], v[84:87]
	v_mfma_f32_16x16x32_bf16 v[76:79], v[154:157], v[204:207], v[76:79]
	v_mfma_f32_16x16x32_bf16 v[124:127], v[150:153], v[182:185], v[124:127]
	v_mfma_f32_16x16x32_bf16 v[120:123], v[158:161], v[182:185], v[120:123]
	v_mfma_f32_16x16x32_bf16 v[112:115], v[150:153], v[190:193], v[112:115]
	v_mfma_f32_16x16x32_bf16 v[108:111], v[158:161], v[190:193], v[108:111]
	v_mfma_f32_16x16x32_bf16 v[100:103], v[150:153], v[198:201], v[100:103]
	v_mfma_f32_16x16x32_bf16 v[92:95], v[158:161], v[198:201], v[92:95]
	v_mfma_f32_16x16x32_bf16 v[84:87], v[150:153], v[208:211], v[84:87]
	v_mfma_f32_16x16x32_bf16 v[76:79], v[158:161], v[208:211], v[76:79]
	v_mfma_f32_16x16x32_bf16 v[116:119], v[162:165], v[178:181], v[116:119]
	v_mfma_f32_16x16x32_bf16 v[104:107], v[170:173], v[178:181], v[104:107]
	v_mfma_f32_16x16x32_bf16 v[96:99], v[162:165], v[186:189], v[96:99]
	v_mfma_f32_16x16x32_bf16 v[88:91], v[170:173], v[186:189], v[88:91]
	v_mfma_f32_16x16x32_bf16 v[80:83], v[162:165], v[194:197], v[80:83]
	v_mfma_f32_16x16x32_bf16 v[72:75], v[170:173], v[194:197], v[72:75]
	v_mfma_f32_16x16x32_bf16 v[68:71], v[162:165], v[204:207], v[68:71]
	v_mfma_f32_16x16x32_bf16 v[64:67], v[170:173], v[204:207], v[64:67]
	v_mfma_f32_16x16x32_bf16 v[116:119], v[166:169], v[182:185], v[116:119]
	v_mfma_f32_16x16x32_bf16 v[104:107], v[174:177], v[182:185], v[104:107]
	v_mfma_f32_16x16x32_bf16 v[96:99], v[166:169], v[190:193], v[96:99]
	v_mfma_f32_16x16x32_bf16 v[88:91], v[174:177], v[190:193], v[88:91]
	v_mfma_f32_16x16x32_bf16 v[80:83], v[166:169], v[198:201], v[80:83]
	v_mfma_f32_16x16x32_bf16 v[72:75], v[174:177], v[198:201], v[72:75]
	v_mfma_f32_16x16x32_bf16 v[68:71], v[166:169], v[208:211], v[68:71]
	v_mfma_f32_16x16x32_bf16 v[64:67], v[174:177], v[208:211], v[64:67]
	s_setprio 0
	s_barrier
; #define PG8_STAGE(bufoff, gbase, voff) do { _Pragma("unroll") for (int _i = 0; _i < 2; ++_i) \
;         __builtin_amdgcn_global_load_lds((const unsigned*)((const char*)(gbase) + (voff)[_i]), (LAS unsigned*)(lds + (bufoff) + ldsw + _i * 8192), 16, 0, 0); } while (0)
; #define PG8_LDA(dst, b, h) do { _Pragma("unroll") for (int m = 0; m < 4; ++m) _Pragma("unroll") for (int k = 0; k < 2; ++k) dst[m][k] = *(const LAS bf16x8*)(lds + PG8_SA(b, h) + aoff + m * 2048 + k * 1024); } while (0)
; #define PG8_MMA(ai, bj, At, Bt) do { __builtin_amdgcn_s_setprio(1); _Pragma("unroll") for (int m = 0; m < 4; ++m) _Pragma("unroll") for (int n = 0; n < 2; ++n) _Pragma("unroll") for (int k = 0; k < 2; ++k) \
;         acc[ai][bj][m][n] = __builtin_amdgcn_mfma_f32_16x16x32_bf16(Bt[n][k], At[m][k], acc[ai][bj][m][n], 0, 0, 0); __builtin_amdgcn_s_setprio(0); } while (0)
; #define PG8_WAIT_V(n) asm volatile("s_waitcnt vmcnt(" #n ")" ::: "memory")
; #define PG8_WAIT_L(n) asm volatile("s_waitcnt lgkmcnt(" #n ")" ::: "memory")
; #define PG8_BAR __builtin_amdgcn_s_barrier()
; #define PG8_SCHED __builtin_amdgcn_sched_barrier(0)
; template <class Epi>
; __device__ __forceinline__ void gemm_phase(LAS unsigned char* lds, const Gemm g, const Sched& S, const Epi& E) {
;     ...
;             PG8_LDA(At, 1, 1); PG8_STAGE(PG8_SB(1, 0), b3, voffB); PG8_STAGE(PG8_SB(1, 1), b3 + hstepB, voffB); PG8_STAGE(PG8_SA(1, 0), a3, voffA);
;             PG8_WAIT_V(8); PG8_WAIT_L(0); PG8_BAR; PG8_MMA(1, 0, At, B0); PG8_MMA(1, 1, At, B1); PG8_BAR; PG8_SCHED;
;         }
;         if (wr == 0) PG8_BAR;
;         if constexpr (!Epi::AFTER_DRAIN) { E(acc, cur, wr, wc, fr, fq); }
;         if (!has_next) break;
	s_mov_b32 m0, s72
	v_lshl_add_u64 v[142:143], v[142:143], 0, s[24:25]
	ds_read_b128 v[178:181], v141 offset:49152
	ds_read_b128 v[182:185], v141 offset:50176
	ds_read_b128 v[186:189], v141 offset:51200
	ds_read_b128 v[190:193], v141 offset:52224
	ds_read_b128 v[194:197], v141 offset:53248
	ds_read_b128 v[198:201], v141 offset:54272
	ds_read_b128 v[204:207], v141 offset:55296
	ds_read_b128 v[208:211], v141 offset:56320
	global_load_lds_dwordx4 v[142:143], off
	v_lshl_add_u64 v[142:143], v[212:213], 0, s[24:25]
	s_mov_b32 m0, s71
	s_nop 0
	global_load_lds_dwordx4 v[142:143], off
	v_lshl_add_u64 v[142:143], s[44:45], 0, v[130:131]
	s_mov_b32 m0, s80
	s_nop 0
	global_load_lds_dwordx4 v[142:143], off
	v_lshl_add_u64 v[142:143], s[44:45], 0, v[134:135]
	s_mov_b32 m0, s79
	s_nop 0
	global_load_lds_dwordx4 v[142:143], off
	v_lshl_add_u64 v[142:143], v[214:215], 0, s[24:25]
	s_mov_b32 m0, s64
	s_nop 0
	global_load_lds_dwordx4 v[142:143], off
	v_lshl_add_u64 v[142:143], v[216:217], 0, s[24:25]
	s_mov_b32 m0, s65
	s_nop 0
	global_load_lds_dwordx4 v[142:143], off
	s_waitcnt vmcnt(8)
	s_waitcnt lgkmcnt(0)
	s_barrier
	s_setprio 1
	v_mfma_f32_16x16x32_bf16 v[60:63], v[146:149], v[178:181], v[60:63]
	v_mfma_f32_16x16x32_bf16 v[56:59], v[154:157], v[178:181], v[56:59]
	v_mfma_f32_16x16x32_bf16 v[52:55], v[146:149], v[186:189], v[52:55]
	v_mfma_f32_16x16x32_bf16 v[44:47], v[154:157], v[186:189], v[44:47]
	v_mfma_f32_16x16x32_bf16 v[36:39], v[146:149], v[194:197], v[36:39]
	v_mfma_f32_16x16x32_bf16 v[28:31], v[154:157], v[194:197], v[28:31]
	v_mfma_f32_16x16x32_bf16 v[20:23], v[146:149], v[204:207], v[20:23]
	v_mfma_f32_16x16x32_bf16 v[12:15], v[154:157], v[204:207], v[12:15]
	v_mfma_f32_16x16x32_bf16 v[60:63], v[150:153], v[182:185], v[60:63]
	v_mfma_f32_16x16x32_bf16 v[56:59], v[158:161], v[182:185], v[56:59]
	v_mfma_f32_16x16x32_bf16 v[52:55], v[150:153], v[190:193], v[52:55]
	v_mfma_f32_16x16x32_bf16 v[44:47], v[158:161], v[190:193], v[44:47]
	v_mfma_f32_16x16x32_bf16 v[36:39], v[150:153], v[198:201], v[36:39]
	v_mfma_f32_16x16x32_bf16 v[28:31], v[158:161], v[198:201], v[28:31]
	v_mfma_f32_16x16x32_bf16 v[20:23], v[150:153], v[208:211], v[20:23]
	v_mfma_f32_16x16x32_bf16 v[12:15], v[158:161], v[208:211], v[12:15]
	v_mfma_f32_16x16x32_bf16 v[48:51], v[162:165], v[178:181], v[48:51]
	v_mfma_f32_16x16x32_bf16 v[40:43], v[170:173], v[178:181], v[40:43]
	v_mfma_f32_16x16x32_bf16 v[32:35], v[162:165], v[186:189], v[32:35]
	v_mfma_f32_16x16x32_bf16 v[24:27], v[170:173], v[186:189], v[24:27]
	v_mfma_f32_16x16x32_bf16 v[16:19], v[162:165], v[194:197], v[16:19]
	v_mfma_f32_16x16x32_bf16 v[8:11], v[170:173], v[194:197], v[8:11]
	v_mfma_f32_16x16x32_bf16 v[4:7], v[162:165], v[204:207], v[4:7]
	v_mfma_f32_16x16x32_bf16 v[0:3], v[170:173], v[204:207], v[0:3]
	v_mfma_f32_16x16x32_bf16 v[48:51], v[166:169], v[182:185], v[48:51]
	v_mfma_f32_16x16x32_bf16 v[40:43], v[174:177], v[182:185], v[40:43]
	v_mfma_f32_16x16x32_bf16 v[32:35], v[166:169], v[190:193], v[32:35]
	v_mfma_f32_16x16x32_bf16 v[24:27], v[174:177], v[190:193], v[24:27]
	v_mfma_f32_16x16x32_bf16 v[16:19], v[166:169], v[198:201], v[16:19]
	v_mfma_f32_16x16x32_bf16 v[8:11], v[174:177], v[198:201], v[8:11]
	v_mfma_f32_16x16x32_bf16 v[4:7], v[166:169], v[208:211], v[4:7]
	v_mfma_f32_16x16x32_bf16 v[0:3], v[174:177], v[208:211], v[0:3]
	s_setprio 0
	s_barrier
	s_andn2_b64 vcc, exec, s[42:43]
	s_mov_b64 s[44:45], -1
	s_mov_b64 s[42:43], 0
	s_mov_b64 s[46:47], 0x100
	s_cbranch_vccz .LBB0_1381
	s_and_b64 vcc, exec, s[26:27]
	s_cbranch_vccnz .LBB0_1384
	s_and_b64 vcc, exec, s[4:5]
	s_mov_b32 s81, s12
	s_cbranch_vccnz .LBB0_1371
	s_branch .LBB0_1385

; #define PG8_STAGE(bufoff, gbase, voff) do { _Pragma("unroll") for (int _i = 0; _i < 2; ++_i) \
;         __builtin_amdgcn_global_load_lds((const unsigned*)((const char*)(gbase) + (voff)[_i]), (LAS unsigned*)(lds + (bufoff) + ldsw + _i * 8192), 16, 0, 0); } while (0)
; #define PG8_LDA(dst, b, h) do { _Pragma("unroll") for (int m = 0; m < 4; ++m) _Pragma("unroll") for (int k = 0; k < 2; ++k) dst[m][k] = *(const LAS bf16x8*)(lds + PG8_SA(b, h) + aoff + m * 2048 + k * 1024); } while (0)
; #define PG8_LDB(dst, b, h) do { _Pragma("unroll") for (int n = 0; n < 2; ++n) _Pragma("unroll") for (int k = 0; k < 2; ++k) dst[n][k] = *(const LAS bf16x8*)(lds + PG8_SB(b, h) + boff + n * 2048 + k * 1024); } while (0)
; #define PG8_MMA(ai, bj, At, Bt) do { __builtin_amdgcn_s_setprio(1); _Pragma("unroll") for (int m = 0; m < 4; ++m) _Pragma("unroll") for (int n = 0; n < 2; ++n) _Pragma("unroll") for (int k = 0; k < 2; ++k) \
;         acc[ai][bj][m][n] = __builtin_amdgcn_mfma_f32_16x16x32_bf16(Bt[n][k], At[m][k], acc[ai][bj][m][n], 0, 0, 0); __builtin_amdgcn_s_setprio(0); } while (0)
; #define PG8_BAR __builtin_amdgcn_s_barrier()
; template <class Epi>
; __device__ __forceinline__ void gemm_phase(LAS unsigned char* lds, const Gemm g, const Sched& S, const Epi& E) {
;     ...
;         const bool has_next = S.next(ui + 1, nxt);
;         const char* nA = has_next ? (const char*)g.A + (size_t)S.aoff(nxt) * 2 : cA; const char* nB = has_next ? (const char*)g.Bt + (size_t)S.boff(nxt) * 2 : cB;
;         _Pragma("nounroll")
;         for (int t = 0; t < nt; t += 2) {
;             const bool last = (t == nt - 2);
;             const char* a1 = cA + (size_t)(t + 1) * kstep;
;             const char* a2 = last ? nA : cA + (size_t)(t + 2) * kstep; const char* b2 = last ? nB : cB + (size_t)(t + 2) * kstep;
;             const char* a3 = a2 + kstep; const char* b3 = b2 + kstep;
;             PG8_LDB(B0, 0, 0); PG8_LDB(B1, 0, 1); PG8_SCHED; PG8_LDA(At, 0, 0); PG8_STAGE(PG8_SA(1, 1), a1 + hstepA, voffA);
;             PG8_WAIT_V(8); PG8_WAIT_L(0); PG8_BAR; PG8_MMA(0, 0, At, B0); PG8_MMA(0, 1, At, B1); PG8_BAR; PG8_SCHED;
;             PG8_LDA(At, 0, 1); PG8_STAGE(PG8_SB(0, 0), b2, voffB); PG8_STAGE(PG8_SB(0, 1), b2 + hstepB, voffB); PG8_STAGE(PG8_SA(0, 0), a2, voffA);
;             PG8_WAIT_V(8); PG8_WAIT_L(0); PG8_BAR; PG8_MMA(1, 0, At, B0); PG8_MMA(1, 1, At, B1); PG8_BAR; PG8_SCHED;
.LBB0_1439:
	s_add_u32 s47, s28, s46
	s_addc_u32 s52, s29, 0
	s_add_u32 s50, s47, 0x100
	s_addc_u32 s51, s52, 0
	s_and_b64 s[48:49], s[44:45], exec
	s_cselect_b32 s49, s23, s51
	s_cselect_b32 s48, s25, s50
	s_add_u32 s46, s36, s46
	s_addc_u32 s50, s37, 0
	s_add_u32 s46, s46, 0x100
	s_addc_u32 s50, s50, 0
	s_and_b64 s[44:45], s[44:45], exec
	s_cselect_b32 s51, s39, s50
	s_cselect_b32 s50, s38, s46
	s_add_u32 s54, s47, 0x40080
	ds_read_b128 v[146:149], v139
	ds_read_b128 v[150:153], v139 offset:1024
	ds_read_b128 v[154:157], v139 offset:2048
	ds_read_b128 v[158:161], v139 offset:3072
	ds_read_b128 v[162:165], v140
	ds_read_b128 v[166:169], v140 offset:1024
	ds_read_b128 v[170:173], v140 offset:2048
	ds_read_b128 v[174:177], v140 offset:3072
	s_addc_u32 s55, s52, 0
	s_add_i32 s72, s62, s10
	s_add_i32 m0, s27, 0xc000
	s_add_i32 s75, s27, 0xe000
	s_add_i32 s69, s72, 0x2000
	s_add_u32 s52, s50, 0x80000
	s_addc_u32 s53, s51, 0
	s_add_i32 s71, s63, s10
	s_add_i32 s70, s71, 0x2000
	s_add_i32 s68, 0, 0x18000
	s_add_i32 s67, 0, 0x1c000
	s_add_u32 s46, s48, 0x40000
	s_addc_u32 s47, s49, 0
	s_add_i32 s66, s68, s10
	s_add_i32 s65, s66, 0x2000
	s_add_u32 s44, s50, 0x80080
	s_addc_u32 s45, s51, 0
	s_add_i32 s74, s67, s10
	s_add_i32 s73, s74, 0x2000
	v_lshl_add_u64 v[142:143], s[54:55], 0, v[128:129]
	ds_read_b128 v[178:181], v141
	ds_read_b128 v[182:185], v141 offset:1024
	ds_read_b128 v[186:189], v141 offset:2048
	ds_read_b128 v[190:193], v141 offset:3072
	ds_read_b128 v[194:197], v141 offset:4096
	ds_read_b128 v[198:201], v141 offset:5120
	ds_read_b128 v[204:207], v141 offset:6144
	ds_read_b128 v[208:211], v141 offset:7168
	global_load_lds_dwordx4 v[142:143], off
	v_lshl_add_u64 v[142:143], s[54:55], 0, v[132:133]
	s_mov_b32 m0, s75
	s_nop 0
	global_load_lds_dwordx4 v[142:143], off
	s_waitcnt vmcnt(8)
	s_waitcnt lgkmcnt(0)
	s_barrier
	s_setprio 1
	v_mfma_f32_16x16x32_bf16 v[124:127], v[146:149], v[178:181], v[124:127]
	v_mfma_f32_16x16x32_bf16 v[120:123], v[154:157], v[178:181], v[120:123]
	v_mfma_f32_16x16x32_bf16 v[116:119], v[146:149], v[186:189], v[116:119]
	v_mfma_f32_16x16x32_bf16 v[112:115], v[154:157], v[186:189], v[112:115]
	v_mfma_f32_16x16x32_bf16 v[100:103], v[146:149], v[194:197], v[100:103]
	v_mfma_f32_16x16x32_bf16 v[96:99], v[154:157], v[194:197], v[96:99]
	v_mfma_f32_16x16x32_bf16 v[84:87], v[146:149], v[204:207], v[84:87]
	v_mfma_f32_16x16x32_bf16 v[80:83], v[154:157], v[204:207], v[80:83]
	v_mfma_f32_16x16x32_bf16 v[124:127], v[150:153], v[182:185], v[124:127]
	v_mfma_f32_16x16x32_bf16 v[120:123], v[158:161], v[182:185], v[120:123]
	v_mfma_f32_16x16x32_bf16 v[116:119], v[150:153], v[190:193], v[116:119]
	v_mfma_f32_16x16x32_bf16 v[112:115], v[158:161], v[190:193], v[112:115]
	v_mfma_f32_16x16x32_bf16 v[100:103], v[150:153], v[198:201], v[100:103]
	v_mfma_f32_16x16x32_bf16 v[96:99], v[158:161], v[198:201], v[96:99]
	v_mfma_f32_16x16x32_bf16 v[84:87], v[150:153], v[208:211], v[84:87]
	v_mfma_f32_16x16x32_bf16 v[80:83], v[158:161], v[208:211], v[80:83]
	v_mfma_f32_16x16x32_bf16 v[108:111], v[162:165], v[178:181], v[108:111]
	v_mfma_f32_16x16x32_bf16 v[104:107], v[170:173], v[178:181], v[104:107]
	v_mfma_f32_16x16x32_bf16 v[92:95], v[162:165], v[186:189], v[92:95]
	v_mfma_f32_16x16x32_bf16 v[88:91], v[170:173], v[186:189], v[88:91]
	v_mfma_f32_16x16x32_bf16 v[76:79], v[162:165], v[194:197], v[76:79]
	v_mfma_f32_16x16x32_bf16 v[72:75], v[170:173], v[194:197], v[72:75]
	v_mfma_f32_16x16x32_bf16 v[68:71], v[162:165], v[204:207], v[68:71]
	v_mfma_f32_16x16x32_bf16 v[64:67], v[170:173], v[204:207], v[64:67]
	v_mfma_f32_16x16x32_bf16 v[108:111], v[166:169], v[182:185], v[108:111]
	v_mfma_f32_16x16x32_bf16 v[104:107], v[174:177], v[182:185], v[104:107]
	v_mfma_f32_16x16x32_bf16 v[92:95], v[166:169], v[190:193], v[92:95]
	v_mfma_f32_16x16x32_bf16 v[88:91], v[174:177], v[190:193], v[88:91]
	v_mfma_f32_16x16x32_bf16 v[76:79], v[166:169], v[198:201], v[76:79]
	v_mfma_f32_16x16x32_bf16 v[72:75], v[174:177], v[198:201], v[72:75]
	v_mfma_f32_16x16x32_bf16 v[68:71], v[166:169], v[208:211], v[68:71]
	v_mfma_f32_16x16x32_bf16 v[64:67], v[174:177], v[208:211], v[64:67]
	s_setprio 0
	s_barrier
	s_mov_b32 m0, s72
	v_lshl_add_u64 v[142:143], s[50:51], 0, v[130:131]
	ds_read_b128 v[178:181], v141 offset:16384
	ds_read_b128 v[182:185], v141 offset:17408
	ds_read_b128 v[186:189], v141 offset:18432
	ds_read_b128 v[190:193], v141 offset:19456
	ds_read_b128 v[194:197], v141 offset:20480
	ds_read_b128 v[198:201], v141 offset:21504
	ds_read_b128 v[204:207], v141 offset:22528
	ds_read_b128 v[208:211], v141 offset:23552
	global_load_lds_dwordx4 v[142:143], off
	v_lshl_add_u64 v[212:213], s[50:51], 0, v[134:135]
	s_mov_b32 m0, s69
	v_lshl_add_u64 v[214:215], s[52:53], 0, v[130:131]
	global_load_lds_dwordx4 v[212:213], off
	s_mov_b32 m0, s71
	v_lshl_add_u64 v[216:217], s[48:49], 0, v[132:133]
	global_load_lds_dwordx4 v[214:215], off
	v_lshl_add_u64 v[214:215], s[52:53], 0, v[134:135]
	s_mov_b32 m0, s70
	s_nop 0
	global_load_lds_dwordx4 v[214:215], off
	v_lshl_add_u64 v[214:215], s[48:49], 0, v[128:129]
	s_mov_b32 m0, s27
	s_nop 0
	global_load_lds_dwordx4 v[214:215], off
	s_mov_b32 m0, s56
	s_nop 0
	global_load_lds_dwordx4 v[216:217], off
	s_waitcnt vmcnt(8)
	s_waitcnt lgkmcnt(0)
	s_barrier
; #define PG8_STAGE(bufoff, gbase, voff) do { _Pragma("unroll") for (int _i = 0; _i < 2; ++_i) \
;         __builtin_amdgcn_global_load_lds((const unsigned*)((const char*)(gbase) + (voff)[_i]), (LAS unsigned*)(lds + (bufoff) + ldsw + _i * 8192), 16, 0, 0); } while (0)
; #define PG8_LDA(dst, b, h) do { _Pragma("unroll") for (int m = 0; m < 4; ++m) _Pragma("unroll") for (int k = 0; k < 2; ++k) dst[m][k] = *(const LAS bf16x8*)(lds + PG8_SA(b, h) + aoff + m * 2048 + k * 1024); } while (0)
; #define PG8_LDB(dst, b, h) do { _Pragma("unroll") for (int n = 0; n < 2; ++n) _Pragma("unroll") for (int k = 0; k < 2; ++k) dst[n][k] = *(const LAS bf16x8*)(lds + PG8_SB(b, h) + boff + n * 2048 + k * 1024); } while (0)
; #define PG8_MMA(ai, bj, At, Bt) do { __builtin_amdgcn_s_setprio(1); _Pragma("unroll") for (int m = 0; m < 4; ++m) _Pragma("unroll") for (int n = 0; n < 2; ++n) _Pragma("unroll") for (int k = 0; k < 2; ++k) \
;         acc[ai][bj][m][n] = __builtin_amdgcn_mfma_f32_16x16x32_bf16(Bt[n][k], At[m][k], acc[ai][bj][m][n], 0, 0, 0); __builtin_amdgcn_s_setprio(0); } while (0)
; #define PG8_WAIT_V(n) asm volatile("s_waitcnt vmcnt(" #n ")" ::: "memory")
; #define PG8_WAIT_L(n) asm volatile("s_waitcnt lgkmcnt(" #n ")" ::: "memory")
; #define PG8_BAR __builtin_amdgcn_s_barrier()
; #define PG8_SCHED __builtin_amdgcn_sched_barrier(0)
; template <class Epi>
; __device__ __forceinline__ void gemm_phase(LAS unsigned char* lds, const Gemm g, const Sched& S, const Epi& E) {
;     ...
;             PG8_WAIT_V(8); PG8_WAIT_L(0); PG8_BAR; PG8_MMA(1, 0, At, B0); PG8_MMA(1, 1, At, B1); PG8_BAR; PG8_SCHED;
;             PG8_LDB(B0, 1, 0); PG8_LDB(B1, 1, 1); PG8_SCHED; PG8_LDA(At, 1, 0); PG8_STAGE(PG8_SA(0, 1), a2 + hstepA, voffA);
;             PG8_WAIT_V(8); PG8_WAIT_L(0); PG8_BAR; PG8_MMA(0, 0, At, B0); PG8_MMA(0, 1, At, B1); PG8_BAR; PG8_SCHED;
	s_setprio 1
	v_mfma_f32_16x16x32_bf16 v[60:63], v[146:149], v[178:181], v[60:63]
	v_mfma_f32_16x16x32_bf16 v[56:59], v[154:157], v[178:181], v[56:59]
	v_mfma_f32_16x16x32_bf16 v[52:55], v[146:149], v[186:189], v[52:55]
	v_mfma_f32_16x16x32_bf16 v[48:51], v[154:157], v[186:189], v[48:51]
	v_mfma_f32_16x16x32_bf16 v[36:39], v[146:149], v[194:197], v[36:39]
	v_mfma_f32_16x16x32_bf16 v[32:35], v[154:157], v[194:197], v[32:35]
	v_mfma_f32_16x16x32_bf16 v[20:23], v[146:149], v[204:207], v[20:23]
	v_mfma_f32_16x16x32_bf16 v[16:19], v[154:157], v[204:207], v[16:19]
	v_mfma_f32_16x16x32_bf16 v[60:63], v[150:153], v[182:185], v[60:63]
	v_mfma_f32_16x16x32_bf16 v[56:59], v[158:161], v[182:185], v[56:59]
	v_mfma_f32_16x16x32_bf16 v[52:55], v[150:153], v[190:193], v[52:55]
	v_mfma_f32_16x16x32_bf16 v[48:51], v[158:161], v[190:193], v[48:51]
	v_mfma_f32_16x16x32_bf16 v[36:39], v[150:153], v[198:201], v[36:39]
	v_mfma_f32_16x16x32_bf16 v[32:35], v[158:161], v[198:201], v[32:35]
	v_mfma_f32_16x16x32_bf16 v[20:23], v[150:153], v[208:211], v[20:23]
	v_mfma_f32_16x16x32_bf16 v[16:19], v[158:161], v[208:211], v[16:19]
	v_mfma_f32_16x16x32_bf16 v[44:47], v[162:165], v[178:181], v[44:47]
	v_mfma_f32_16x16x32_bf16 v[40:43], v[170:173], v[178:181], v[40:43]
	v_mfma_f32_16x16x32_bf16 v[28:31], v[162:165], v[186:189], v[28:31]
	v_mfma_f32_16x16x32_bf16 v[24:27], v[170:173], v[186:189], v[24:27]
	v_mfma_f32_16x16x32_bf16 v[12:15], v[162:165], v[194:197], v[12:15]
	v_mfma_f32_16x16x32_bf16 v[8:11], v[170:173], v[194:197], v[8:11]
	v_mfma_f32_16x16x32_bf16 v[4:7], v[162:165], v[204:207], v[4:7]
	v_mfma_f32_16x16x32_bf16 v[0:3], v[170:173], v[204:207], v[0:3]
	v_mfma_f32_16x16x32_bf16 v[44:47], v[166:169], v[182:185], v[44:47]
	v_mfma_f32_16x16x32_bf16 v[40:43], v[174:177], v[182:185], v[40:43]
	v_mfma_f32_16x16x32_bf16 v[28:31], v[166:169], v[190:193], v[28:31]
	v_mfma_f32_16x16x32_bf16 v[24:27], v[174:177], v[190:193], v[24:27]
	v_mfma_f32_16x16x32_bf16 v[12:15], v[166:169], v[198:201], v[12:15]
	v_mfma_f32_16x16x32_bf16 v[8:11], v[174:177], v[198:201], v[8:11]
	v_mfma_f32_16x16x32_bf16 v[4:7], v[166:169], v[208:211], v[4:7]
	v_mfma_f32_16x16x32_bf16 v[0:3], v[174:177], v[208:211], v[0:3]
	s_setprio 0
	s_barrier
	v_add_u32_e32 v145, s68, v137
	ds_read_b128 v[146:149], v145
	ds_read_b128 v[150:153], v145 offset:1024
	ds_read_b128 v[154:157], v145 offset:2048
	ds_read_b128 v[158:161], v145 offset:3072
	v_add_u32_e32 v145, s67, v137
	ds_read_b128 v[162:165], v145
	ds_read_b128 v[166:169], v145 offset:1024
	ds_read_b128 v[170:173], v145 offset:2048
	ds_read_b128 v[174:177], v145 offset:3072
	s_mov_b32 m0, s57
	v_lshl_add_u64 v[218:219], s[46:47], 0, v[128:129]
	ds_read_b128 v[178:181], v141 offset:32768
	ds_read_b128 v[182:185], v141 offset:33792
	ds_read_b128 v[186:189], v141 offset:34816
	ds_read_b128 v[190:193], v141 offset:35840
	ds_read_b128 v[194:197], v141 offset:36864
	ds_read_b128 v[198:201], v141 offset:37888
	ds_read_b128 v[204:207], v141 offset:38912
	ds_read_b128 v[208:211], v141 offset:39936
	global_load_lds_dwordx4 v[218:219], off
	v_lshl_add_u64 v[218:219], s[46:47], 0, v[132:133]
	s_mov_b32 m0, s58
	s_nop 0
	global_load_lds_dwordx4 v[218:219], off
	s_waitcnt vmcnt(8)
	s_waitcnt lgkmcnt(0)
	s_barrier
	s_setprio 1
	v_mfma_f32_16x16x32_bf16 v[124:127], v[146:149], v[178:181], v[124:127]
	v_mfma_f32_16x16x32_bf16 v[120:123], v[154:157], v[178:181], v[120:123]
	v_mfma_f32_16x16x32_bf16 v[116:119], v[146:149], v[186:189], v[116:119]
	v_mfma_f32_16x16x32_bf16 v[112:115], v[154:157], v[186:189], v[112:115]
	v_mfma_f32_16x16x32_bf16 v[100:103], v[146:149], v[194:197], v[100:103]
	v_mfma_f32_16x16x32_bf16 v[96:99], v[154:157], v[194:197], v[96:99]
	v_mfma_f32_16x16x32_bf16 v[84:87], v[146:149], v[204:207], v[84:87]
	v_mfma_f32_16x16x32_bf16 v[80:83], v[154:157], v[204:207], v[80:83]
	v_mfma_f32_16x16x32_bf16 v[124:127], v[150:153], v[182:185], v[124:127]
	v_mfma_f32_16x16x32_bf16 v[120:123], v[158:161], v[182:185], v[120:123]
	v_mfma_f32_16x16x32_bf16 v[116:119], v[150:153], v[190:193], v[116:119]
	v_mfma_f32_16x16x32_bf16 v[112:115], v[158:161], v[190:193], v[112:115]
	v_mfma_f32_16x16x32_bf16 v[100:103], v[150:153], v[198:201], v[100:103]
	v_mfma_f32_16x16x32_bf16 v[96:99], v[158:161], v[198:201], v[96:99]
	v_mfma_f32_16x16x32_bf16 v[84:87], v[150:153], v[208:211], v[84:87]
	v_mfma_f32_16x16x32_bf16 v[80:83], v[158:161], v[208:211], v[80:83]
	v_mfma_f32_16x16x32_bf16 v[108:111], v[162:165], v[178:181], v[108:111]
	v_mfma_f32_16x16x32_bf16 v[104:107], v[170:173], v[178:181], v[104:107]
	v_mfma_f32_16x16x32_bf16 v[92:95], v[162:165], v[186:189], v[92:95]
	v_mfma_f32_16x16x32_bf16 v[88:91], v[170:173], v[186:189], v[88:91]
	v_mfma_f32_16x16x32_bf16 v[76:79], v[162:165], v[194:197], v[76:79]
	v_mfma_f32_16x16x32_bf16 v[72:75], v[170:173], v[194:197], v[72:75]
	v_mfma_f32_16x16x32_bf16 v[68:71], v[162:165], v[204:207], v[68:71]
	v_mfma_f32_16x16x32_bf16 v[64:67], v[170:173], v[204:207], v[64:67]
	v_mfma_f32_16x16x32_bf16 v[108:111], v[166:169], v[182:185], v[108:111]
	v_mfma_f32_16x16x32_bf16 v[104:107], v[174:177], v[182:185], v[104:107]
	v_mfma_f32_16x16x32_bf16 v[92:95], v[166:169], v[190:193], v[92:95]
	v_mfma_f32_16x16x32_bf16 v[88:91], v[174:177], v[190:193], v[88:91]
	v_mfma_f32_16x16x32_bf16 v[76:79], v[166:169], v[198:201], v[76:79]
	v_mfma_f32_16x16x32_bf16 v[72:75], v[174:177], v[198:201], v[72:75]
	v_mfma_f32_16x16x32_bf16 v[68:71], v[166:169], v[208:211], v[68:71]
	v_mfma_f32_16x16x32_bf16 v[64:67], v[174:177], v[208:211], v[64:67]
	s_setprio 0
	s_barrier
; #define PG8_STAGE(bufoff, gbase, voff) do { _Pragma("unroll") for (int _i = 0; _i < 2; ++_i) \
;         __builtin_amdgcn_global_load_lds((const unsigned*)((const char*)(gbase) + (voff)[_i]), (LAS unsigned*)(lds + (bufoff) + ldsw + _i * 8192), 16, 0, 0); } while (0)
; #define PG8_LDA(dst, b, h) do { _Pragma("unroll") for (int m = 0; m < 4; ++m) _Pragma("unroll") for (int k = 0; k < 2; ++k) dst[m][k] = *(const LAS bf16x8*)(lds + PG8_SA(b, h) + aoff + m * 2048 + k * 1024); } while (0)
; #define PG8_MMA(ai, bj, At, Bt) do { __builtin_amdgcn_s_setprio(1); _Pragma("unroll") for (int m = 0; m < 4; ++m) _Pragma("unroll") for (int n = 0; n < 2; ++n) _Pragma("unroll") for (int k = 0; k < 2; ++k) \
;         acc[ai][bj][m][n] = __builtin_amdgcn_mfma_f32_16x16x32_bf16(Bt[n][k], At[m][k], acc[ai][bj][m][n], 0, 0, 0); __builtin_amdgcn_s_setprio(0); } while (0)
; #define PG8_WAIT_V(n) asm volatile("s_waitcnt vmcnt(" #n ")" ::: "memory")
; #define PG8_WAIT_L(n) asm volatile("s_waitcnt lgkmcnt(" #n ")" ::: "memory")
; #define PG8_BAR __builtin_amdgcn_s_barrier()
; #define PG8_SCHED __builtin_amdgcn_sched_barrier(0)
; template <class Epi>
; __device__ __forceinline__ void gemm_phase(LAS unsigned char* lds, const Gemm g, const Sched& S, const Epi& E) {
;     ...
;             PG8_LDA(At, 1, 1); PG8_STAGE(PG8_SB(1, 0), b3, voffB); PG8_STAGE(PG8_SB(1, 1), b3 + hstepB, voffB); PG8_STAGE(PG8_SA(1, 0), a3, voffA);
;             PG8_WAIT_V(8); PG8_WAIT_L(0); PG8_BAR; PG8_MMA(1, 0, At, B0); PG8_MMA(1, 1, At, B1); PG8_BAR; PG8_SCHED;
;         }
;         if (wr == 0) PG8_BAR;
	s_mov_b32 m0, s66
	v_lshl_add_u64 v[142:143], v[142:143], 0, s[18:19]
	ds_read_b128 v[178:181], v141 offset:49152
	ds_read_b128 v[182:185], v141 offset:50176
	ds_read_b128 v[186:189], v141 offset:51200
	ds_read_b128 v[190:193], v141 offset:52224
	ds_read_b128 v[194:197], v141 offset:53248
	ds_read_b128 v[198:201], v141 offset:54272
	ds_read_b128 v[204:207], v141 offset:55296
	ds_read_b128 v[208:211], v141 offset:56320
	global_load_lds_dwordx4 v[142:143], off
	v_lshl_add_u64 v[142:143], v[212:213], 0, s[18:19]
	s_mov_b32 m0, s65
	s_nop 0
	global_load_lds_dwordx4 v[142:143], off
	v_lshl_add_u64 v[142:143], s[44:45], 0, v[130:131]
	s_mov_b32 m0, s74
	s_nop 0
	global_load_lds_dwordx4 v[142:143], off
	v_lshl_add_u64 v[142:143], s[44:45], 0, v[134:135]
	s_mov_b32 m0, s73
	s_nop 0
	global_load_lds_dwordx4 v[142:143], off
	v_lshl_add_u64 v[142:143], v[214:215], 0, s[18:19]
	s_mov_b32 m0, s60
	s_nop 0
	global_load_lds_dwordx4 v[142:143], off
	v_lshl_add_u64 v[142:143], v[216:217], 0, s[18:19]
	s_mov_b32 m0, s61
	s_nop 0
	global_load_lds_dwordx4 v[142:143], off
	s_waitcnt vmcnt(8)
	s_waitcnt lgkmcnt(0)
	s_barrier
	s_setprio 1
	v_mfma_f32_16x16x32_bf16 v[60:63], v[146:149], v[178:181], v[60:63]
	v_mfma_f32_16x16x32_bf16 v[56:59], v[154:157], v[178:181], v[56:59]
	v_mfma_f32_16x16x32_bf16 v[52:55], v[146:149], v[186:189], v[52:55]
	v_mfma_f32_16x16x32_bf16 v[48:51], v[154:157], v[186:189], v[48:51]
	v_mfma_f32_16x16x32_bf16 v[36:39], v[146:149], v[194:197], v[36:39]
	v_mfma_f32_16x16x32_bf16 v[32:35], v[154:157], v[194:197], v[32:35]
	v_mfma_f32_16x16x32_bf16 v[20:23], v[146:149], v[204:207], v[20:23]
	v_mfma_f32_16x16x32_bf16 v[16:19], v[154:157], v[204:207], v[16:19]
	v_mfma_f32_16x16x32_bf16 v[60:63], v[150:153], v[182:185], v[60:63]
	v_mfma_f32_16x16x32_bf16 v[56:59], v[158:161], v[182:185], v[56:59]
	v_mfma_f32_16x16x32_bf16 v[52:55], v[150:153], v[190:193], v[52:55]
	v_mfma_f32_16x16x32_bf16 v[48:51], v[158:161], v[190:193], v[48:51]
	v_mfma_f32_16x16x32_bf16 v[36:39], v[150:153], v[198:201], v[36:39]
	v_mfma_f32_16x16x32_bf16 v[32:35], v[158:161], v[198:201], v[32:35]
	v_mfma_f32_16x16x32_bf16 v[20:23], v[150:153], v[208:211], v[20:23]
	v_mfma_f32_16x16x32_bf16 v[16:19], v[158:161], v[208:211], v[16:19]
	v_mfma_f32_16x16x32_bf16 v[44:47], v[162:165], v[178:181], v[44:47]
	v_mfma_f32_16x16x32_bf16 v[40:43], v[170:173], v[178:181], v[40:43]
	v_mfma_f32_16x16x32_bf16 v[28:31], v[162:165], v[186:189], v[28:31]
	v_mfma_f32_16x16x32_bf16 v[24:27], v[170:173], v[186:189], v[24:27]
	v_mfma_f32_16x16x32_bf16 v[12:15], v[162:165], v[194:197], v[12:15]
	v_mfma_f32_16x16x32_bf16 v[8:11], v[170:173], v[194:197], v[8:11]
	v_mfma_f32_16x16x32_bf16 v[4:7], v[162:165], v[204:207], v[4:7]
	v_mfma_f32_16x16x32_bf16 v[0:3], v[170:173], v[204:207], v[0:3]
	v_mfma_f32_16x16x32_bf16 v[44:47], v[166:169], v[182:185], v[44:47]
	v_mfma_f32_16x16x32_bf16 v[40:43], v[174:177], v[182:185], v[40:43]
	v_mfma_f32_16x16x32_bf16 v[28:31], v[166:169], v[190:193], v[28:31]
	v_mfma_f32_16x16x32_bf16 v[24:27], v[174:177], v[190:193], v[24:27]
	v_mfma_f32_16x16x32_bf16 v[12:15], v[166:169], v[198:201], v[12:15]
	v_mfma_f32_16x16x32_bf16 v[8:11], v[174:177], v[198:201], v[8:11]
	v_mfma_f32_16x16x32_bf16 v[4:7], v[166:169], v[208:211], v[4:7]
	v_mfma_f32_16x16x32_bf16 v[0:3], v[174:177], v[208:211], v[0:3]
	s_setprio 0
	s_barrier
	s_movk_i32 s46, 0x100
	s_andn2_b64 vcc, exec, s[42:43]
	s_mov_b64 s[44:45], -1
	s_mov_b64 s[42:43], 0
	s_cbranch_vccz .LBB0_1439
	s_and_b64 vcc, exec, s[20:21]
	s_cbranch_vccz .LBB0_1442
	s_barrier

; #define PG8_STAGE(bufoff, gbase, voff) do { _Pragma("unroll") for (int _i = 0; _i < 2; ++_i) \
;         __builtin_amdgcn_global_load_lds((const unsigned*)((const char*)(gbase) + (voff)[_i]), (LAS unsigned*)(lds + (bufoff) + ldsw + _i * 8192), 16, 0, 0); } while (0)
; #define PG8_LDA(dst, b, h) do { _Pragma("unroll") for (int m = 0; m < 4; ++m) _Pragma("unroll") for (int k = 0; k < 2; ++k) dst[m][k] = *(const LAS bf16x8*)(lds + PG8_SA(b, h) + aoff + m * 2048 + k * 1024); } while (0)
; #define PG8_LDB(dst, b, h) do { _Pragma("unroll") for (int n = 0; n < 2; ++n) _Pragma("unroll") for (int k = 0; k < 2; ++k) dst[n][k] = *(const LAS bf16x8*)(lds + PG8_SB(b, h) + boff + n * 2048 + k * 1024); } while (0)
; #define PG8_MMA(ai, bj, At, Bt) do { __builtin_amdgcn_s_setprio(1); _Pragma("unroll") for (int m = 0; m < 4; ++m) _Pragma("unroll") for (int n = 0; n < 2; ++n) _Pragma("unroll") for (int k = 0; k < 2; ++k) \
;         acc[ai][bj][m][n] = __builtin_amdgcn_mfma_f32_16x16x32_bf16(Bt[n][k], At[m][k], acc[ai][bj][m][n], 0, 0, 0); __builtin_amdgcn_s_setprio(0); } while (0)
; #define PG8_WAIT_V(n) asm volatile("s_waitcnt vmcnt(" #n ")" ::: "memory")
; #define PG8_WAIT_L(n) asm volatile("s_waitcnt lgkmcnt(" #n ")" ::: "memory")
; #define PG8_BAR __builtin_amdgcn_s_barrier()
; #define PG8_SCHED __builtin_amdgcn_sched_barrier(0)
; template <class Epi>
; __device__ __forceinline__ void gemm_phase(LAS unsigned char* lds, const Gemm g, const Sched& S, const Epi& E) {
;     ...
;         for (int t = 0; t < nt; t += 2) {
;             const bool last = (t == nt - 2);
;             const char* a1 = cA + (size_t)(t + 1) * kstep;
;             const char* a2 = last ? nA : cA + (size_t)(t + 2) * kstep; const char* b2 = last ? nB : cB + (size_t)(t + 2) * kstep;
;             const char* a3 = a2 + kstep; const char* b3 = b2 + kstep;
;             PG8_LDB(B0, 0, 0); PG8_LDB(B1, 0, 1); PG8_SCHED; PG8_LDA(At, 0, 0); PG8_STAGE(PG8_SA(1, 1), a1 + hstepA, voffA);
;             PG8_WAIT_V(8); PG8_WAIT_L(0); PG8_BAR; PG8_MMA(0, 0, At, B0); PG8_MMA(0, 1, At, B1); PG8_BAR; PG8_SCHED;
;             PG8_LDA(At, 0, 1); PG8_STAGE(PG8_SB(0, 0), b2, voffB); PG8_STAGE(PG8_SB(0, 1), b2 + hstepB, voffB); PG8_STAGE(PG8_SA(0, 0), a2, voffA);
;             PG8_WAIT_V(8); PG8_WAIT_L(0); PG8_BAR; PG8_MMA(1, 0, At, B0); PG8_MMA(1, 1, At, B1); PG8_BAR; PG8_SCHED;
.LBB0_1731:
	ds_read_b128 v[148:151], v145
	ds_read_b128 v[152:155], v145 offset:1024
	ds_read_b128 v[156:159], v145 offset:2048
	ds_read_b128 v[160:163], v145 offset:3072
	ds_read_b128 v[164:167], v146
	ds_read_b128 v[168:171], v146 offset:1024
	ds_read_b128 v[172:175], v146 offset:2048
	ds_read_b128 v[176:179], v146 offset:3072
	s_add_u32 s28, s26, 0xfffc0080
	s_addc_u32 s29, s27, -1
	s_cmp_eq_u32 s53, 12
	s_cselect_b32 s37, s17, s29
	s_cselect_b32 s36, s23, s28
	s_cselect_b32 s29, s15, s52
	s_cselect_b32 s28, s50, s51
	v_lshl_add_u64 v[140:141], s[26:27], 0, v[136:137]
	s_add_i32 m0, s25, 0xc000
	ds_read_b128 v[180:183], v147
	ds_read_b128 v[184:187], v147 offset:1024
	ds_read_b128 v[188:191], v147 offset:2048
	ds_read_b128 v[192:195], v147 offset:3072
	ds_read_b128 v[196:199], v147 offset:4096
	ds_read_b128 v[204:207], v147 offset:5120
	ds_read_b128 v[208:211], v147 offset:6144
	ds_read_b128 v[212:215], v147 offset:7168
	global_load_lds_dwordx4 v[140:141], off
	v_lshl_add_u64 v[140:141], s[26:27], 0, v[138:139]
	s_add_i32 m0, s25, 0xe000
	s_nop 0
	global_load_lds_dwordx4 v[140:141], off
	s_waitcnt vmcnt(8)
	s_waitcnt lgkmcnt(0)
	s_barrier
	s_setprio 1
	v_mfma_f32_16x16x32_bf16 v[116:119], v[148:151], v[180:183], v[116:119]
	v_mfma_f32_16x16x32_bf16 v[124:127], v[156:159], v[180:183], v[124:127]
	v_mfma_f32_16x16x32_bf16 v[100:103], v[148:151], v[188:191], v[100:103]
	v_mfma_f32_16x16x32_bf16 v[108:111], v[156:159], v[188:191], v[108:111]
	v_mfma_f32_16x16x32_bf16 v[84:87], v[148:151], v[196:199], v[84:87]
	v_mfma_f32_16x16x32_bf16 v[92:95], v[156:159], v[196:199], v[92:95]
	v_mfma_f32_16x16x32_bf16 v[68:71], v[148:151], v[208:211], v[68:71]
	v_mfma_f32_16x16x32_bf16 v[76:79], v[156:159], v[208:211], v[76:79]
	v_mfma_f32_16x16x32_bf16 v[116:119], v[152:155], v[184:187], v[116:119]
	v_mfma_f32_16x16x32_bf16 v[124:127], v[160:163], v[184:187], v[124:127]
	v_mfma_f32_16x16x32_bf16 v[100:103], v[152:155], v[192:195], v[100:103]
	v_mfma_f32_16x16x32_bf16 v[108:111], v[160:163], v[192:195], v[108:111]
	v_mfma_f32_16x16x32_bf16 v[84:87], v[152:155], v[204:207], v[84:87]
	v_mfma_f32_16x16x32_bf16 v[92:95], v[160:163], v[204:207], v[92:95]
	v_mfma_f32_16x16x32_bf16 v[68:71], v[152:155], v[212:215], v[68:71]
	v_mfma_f32_16x16x32_bf16 v[76:79], v[160:163], v[212:215], v[76:79]
	v_mfma_f32_16x16x32_bf16 v[112:115], v[164:167], v[180:183], v[112:115]
	v_mfma_f32_16x16x32_bf16 v[120:123], v[172:175], v[180:183], v[120:123]
	v_mfma_f32_16x16x32_bf16 v[96:99], v[164:167], v[188:191], v[96:99]
	v_mfma_f32_16x16x32_bf16 v[104:107], v[172:175], v[188:191], v[104:107]
	v_mfma_f32_16x16x32_bf16 v[80:83], v[164:167], v[196:199], v[80:83]
	v_mfma_f32_16x16x32_bf16 v[88:91], v[172:175], v[196:199], v[88:91]
	v_mfma_f32_16x16x32_bf16 v[64:67], v[164:167], v[208:211], v[64:67]
	v_mfma_f32_16x16x32_bf16 v[72:75], v[172:175], v[208:211], v[72:75]
	v_mfma_f32_16x16x32_bf16 v[112:115], v[168:171], v[184:187], v[112:115]
	v_mfma_f32_16x16x32_bf16 v[120:123], v[176:179], v[184:187], v[120:123]
	v_mfma_f32_16x16x32_bf16 v[96:99], v[168:171], v[192:195], v[96:99]
	v_mfma_f32_16x16x32_bf16 v[104:107], v[176:179], v[192:195], v[104:107]
	v_mfma_f32_16x16x32_bf16 v[80:83], v[168:171], v[204:207], v[80:83]
	v_mfma_f32_16x16x32_bf16 v[88:91], v[176:179], v[204:207], v[88:91]
	v_mfma_f32_16x16x32_bf16 v[64:67], v[168:171], v[212:215], v[64:67]
	v_mfma_f32_16x16x32_bf16 v[72:75], v[176:179], v[212:215], v[72:75]
	s_setprio 0
	s_barrier
	s_add_i32 s54, s46, s39
	v_lshl_add_u64 v[140:141], s[28:29], 0, v[130:131]
	s_mov_b32 m0, s54
	ds_read_b128 v[180:183], v147 offset:16384
	ds_read_b128 v[184:187], v147 offset:17408
	ds_read_b128 v[188:191], v147 offset:18432
	ds_read_b128 v[192:195], v147 offset:19456
	ds_read_b128 v[196:199], v147 offset:20480
	ds_read_b128 v[204:207], v147 offset:21504
	ds_read_b128 v[208:211], v147 offset:22528
	ds_read_b128 v[212:215], v147 offset:23552
	global_load_lds_dwordx4 v[140:141], off
	s_add_i32 m0, s54, 0x2000
	s_add_u32 s54, s28, 0x40000
	v_lshl_add_u64 v[200:201], s[28:29], 0, v[134:135]
	s_addc_u32 s55, s29, 0
	s_add_i32 s56, s47, s39
	global_load_lds_dwordx4 v[200:201], off
	v_lshl_add_u64 v[216:217], s[54:55], 0, v[130:131]
	s_mov_b32 m0, s56
	v_lshl_add_u64 v[218:219], s[36:37], 0, v[132:133]
	global_load_lds_dwordx4 v[216:217], off
	v_lshl_add_u64 v[216:217], s[54:55], 0, v[134:135]
	s_add_i32 m0, s56, 0x2000
	s_nop 0
	global_load_lds_dwordx4 v[216:217], off
	v_lshl_add_u64 v[216:217], s[36:37], 0, v[128:129]
	s_mov_b32 m0, s25
	s_nop 0
	global_load_lds_dwordx4 v[216:217], off
	s_mov_b32 m0, s40
	s_nop 0
	global_load_lds_dwordx4 v[218:219], off
	s_waitcnt vmcnt(8)
	s_waitcnt lgkmcnt(0)
	s_barrier
; #define PG8_STAGE(bufoff, gbase, voff) do { _Pragma("unroll") for (int _i = 0; _i < 2; ++_i) \
;         __builtin_amdgcn_global_load_lds((const unsigned*)((const char*)(gbase) + (voff)[_i]), (LAS unsigned*)(lds + (bufoff) + ldsw + _i * 8192), 16, 0, 0); } while (0)
; #define PG8_LDA(dst, b, h) do { _Pragma("unroll") for (int m = 0; m < 4; ++m) _Pragma("unroll") for (int k = 0; k < 2; ++k) dst[m][k] = *(const LAS bf16x8*)(lds + PG8_SA(b, h) + aoff + m * 2048 + k * 1024); } while (0)
; #define PG8_LDB(dst, b, h) do { _Pragma("unroll") for (int n = 0; n < 2; ++n) _Pragma("unroll") for (int k = 0; k < 2; ++k) dst[n][k] = *(const LAS bf16x8*)(lds + PG8_SB(b, h) + boff + n * 2048 + k * 1024); } while (0)
; #define PG8_MMA(ai, bj, At, Bt) do { __builtin_amdgcn_s_setprio(1); _Pragma("unroll") for (int m = 0; m < 4; ++m) _Pragma("unroll") for (int n = 0; n < 2; ++n) _Pragma("unroll") for (int k = 0; k < 2; ++k) \
;         acc[ai][bj][m][n] = __builtin_amdgcn_mfma_f32_16x16x32_bf16(Bt[n][k], At[m][k], acc[ai][bj][m][n], 0, 0, 0); __builtin_amdgcn_s_setprio(0); } while (0)
; #define PG8_WAIT_V(n) asm volatile("s_waitcnt vmcnt(" #n ")" ::: "memory")
; #define PG8_WAIT_L(n) asm volatile("s_waitcnt lgkmcnt(" #n ")" ::: "memory")
; #define PG8_BAR __builtin_amdgcn_s_barrier()
; #define PG8_SCHED __builtin_amdgcn_sched_barrier(0)
; template <class Epi>
; __device__ __forceinline__ void gemm_phase(LAS unsigned char* lds, const Gemm g, const Sched& S, const Epi& E) {
;     ...
;             PG8_WAIT_V(8); PG8_WAIT_L(0); PG8_BAR; PG8_MMA(1, 0, At, B0); PG8_MMA(1, 1, At, B1); PG8_BAR; PG8_SCHED;
;             PG8_LDB(B0, 1, 0); PG8_LDB(B1, 1, 1); PG8_SCHED; PG8_LDA(At, 1, 0); PG8_STAGE(PG8_SA(0, 1), a2 + hstepA, voffA);
;             PG8_WAIT_V(8); PG8_WAIT_L(0); PG8_BAR; PG8_MMA(0, 0, At, B0); PG8_MMA(0, 1, At, B1); PG8_BAR; PG8_SCHED;
	s_setprio 1
	v_mfma_f32_16x16x32_bf16 v[52:55], v[148:151], v[180:183], v[52:55]
	v_mfma_f32_16x16x32_bf16 v[60:63], v[156:159], v[180:183], v[60:63]
	v_mfma_f32_16x16x32_bf16 v[36:39], v[148:151], v[188:191], v[36:39]
	v_mfma_f32_16x16x32_bf16 v[44:47], v[156:159], v[188:191], v[44:47]
	v_mfma_f32_16x16x32_bf16 v[20:23], v[148:151], v[196:199], v[20:23]
	v_mfma_f32_16x16x32_bf16 v[28:31], v[156:159], v[196:199], v[28:31]
	v_mfma_f32_16x16x32_bf16 v[4:7], v[148:151], v[208:211], v[4:7]
	v_mfma_f32_16x16x32_bf16 v[12:15], v[156:159], v[208:211], v[12:15]
	v_mfma_f32_16x16x32_bf16 v[52:55], v[152:155], v[184:187], v[52:55]
	v_mfma_f32_16x16x32_bf16 v[60:63], v[160:163], v[184:187], v[60:63]
	v_mfma_f32_16x16x32_bf16 v[36:39], v[152:155], v[192:195], v[36:39]
	v_mfma_f32_16x16x32_bf16 v[44:47], v[160:163], v[192:195], v[44:47]
	v_mfma_f32_16x16x32_bf16 v[20:23], v[152:155], v[204:207], v[20:23]
	v_mfma_f32_16x16x32_bf16 v[28:31], v[160:163], v[204:207], v[28:31]
	v_mfma_f32_16x16x32_bf16 v[4:7], v[152:155], v[212:215], v[4:7]
	v_mfma_f32_16x16x32_bf16 v[12:15], v[160:163], v[212:215], v[12:15]
	v_mfma_f32_16x16x32_bf16 v[48:51], v[164:167], v[180:183], v[48:51]
	v_mfma_f32_16x16x32_bf16 v[56:59], v[172:175], v[180:183], v[56:59]
	v_mfma_f32_16x16x32_bf16 v[32:35], v[164:167], v[188:191], v[32:35]
	v_mfma_f32_16x16x32_bf16 v[40:43], v[172:175], v[188:191], v[40:43]
	v_mfma_f32_16x16x32_bf16 v[16:19], v[164:167], v[196:199], v[16:19]
	v_mfma_f32_16x16x32_bf16 v[24:27], v[172:175], v[196:199], v[24:27]
	v_mfma_f32_16x16x32_bf16 v[0:3], v[164:167], v[208:211], v[0:3]
	v_mfma_f32_16x16x32_bf16 v[8:11], v[172:175], v[208:211], v[8:11]
	v_mfma_f32_16x16x32_bf16 v[48:51], v[168:171], v[184:187], v[48:51]
	v_mfma_f32_16x16x32_bf16 v[56:59], v[176:179], v[184:187], v[56:59]
	v_mfma_f32_16x16x32_bf16 v[32:35], v[168:171], v[192:195], v[32:35]
	v_mfma_f32_16x16x32_bf16 v[40:43], v[176:179], v[192:195], v[40:43]
	v_mfma_f32_16x16x32_bf16 v[16:19], v[168:171], v[204:207], v[16:19]
	v_mfma_f32_16x16x32_bf16 v[24:27], v[176:179], v[204:207], v[24:27]
	v_mfma_f32_16x16x32_bf16 v[0:3], v[168:171], v[212:215], v[0:3]
	v_mfma_f32_16x16x32_bf16 v[8:11], v[176:179], v[212:215], v[8:11]
	s_setprio 0
	s_barrier
	s_add_i32 s54, 0, 0x18000
	s_add_i32 s55, 0, 0x1c000
	v_add_u32_e32 v160, s54, v143
	v_add_u32_e32 v176, s55, v143
	ds_read_b128 v[148:151], v160
	ds_read_b128 v[152:155], v160 offset:1024
	ds_read_b128 v[156:159], v160 offset:2048
	ds_read_b128 v[160:163], v160 offset:3072
	ds_read_b128 v[164:167], v176
	ds_read_b128 v[168:171], v176 offset:1024
	ds_read_b128 v[172:175], v176 offset:2048
	ds_read_b128 v[176:179], v176 offset:3072
	s_add_u32 s36, s36, 0x40000
	s_addc_u32 s37, s37, 0
	s_mov_b32 m0, s41
	v_lshl_add_u64 v[220:221], s[36:37], 0, v[128:129]
	ds_read_b128 v[180:183], v147 offset:32768
	ds_read_b128 v[184:187], v147 offset:33792
	ds_read_b128 v[188:191], v147 offset:34816
	ds_read_b128 v[192:195], v147 offset:35840
	ds_read_b128 v[196:199], v147 offset:36864
	ds_read_b128 v[204:207], v147 offset:37888
	ds_read_b128 v[208:211], v147 offset:38912
	ds_read_b128 v[212:215], v147 offset:39936
	global_load_lds_dwordx4 v[220:221], off
	v_lshl_add_u64 v[220:221], s[36:37], 0, v[132:133]
	s_mov_b32 m0, s42
	s_nop 0
	global_load_lds_dwordx4 v[220:221], off
	s_waitcnt vmcnt(8)
	s_waitcnt lgkmcnt(0)
	s_barrier
	s_setprio 1
	v_mfma_f32_16x16x32_bf16 v[116:119], v[148:151], v[180:183], v[116:119]
	v_mfma_f32_16x16x32_bf16 v[124:127], v[156:159], v[180:183], v[124:127]
	v_mfma_f32_16x16x32_bf16 v[100:103], v[148:151], v[188:191], v[100:103]
	v_mfma_f32_16x16x32_bf16 v[108:111], v[156:159], v[188:191], v[108:111]
	v_mfma_f32_16x16x32_bf16 v[84:87], v[148:151], v[196:199], v[84:87]
	v_mfma_f32_16x16x32_bf16 v[92:95], v[156:159], v[196:199], v[92:95]
	v_mfma_f32_16x16x32_bf16 v[68:71], v[148:151], v[208:211], v[68:71]
	v_mfma_f32_16x16x32_bf16 v[76:79], v[156:159], v[208:211], v[76:79]
	v_mfma_f32_16x16x32_bf16 v[116:119], v[152:155], v[184:187], v[116:119]
	v_mfma_f32_16x16x32_bf16 v[124:127], v[160:163], v[184:187], v[124:127]
	v_mfma_f32_16x16x32_bf16 v[100:103], v[152:155], v[192:195], v[100:103]
	v_mfma_f32_16x16x32_bf16 v[108:111], v[160:163], v[192:195], v[108:111]
	v_mfma_f32_16x16x32_bf16 v[84:87], v[152:155], v[204:207], v[84:87]
	v_mfma_f32_16x16x32_bf16 v[92:95], v[160:163], v[204:207], v[92:95]
	v_mfma_f32_16x16x32_bf16 v[68:71], v[152:155], v[212:215], v[68:71]
	v_mfma_f32_16x16x32_bf16 v[76:79], v[160:163], v[212:215], v[76:79]
	v_mfma_f32_16x16x32_bf16 v[112:115], v[164:167], v[180:183], v[112:115]
	v_mfma_f32_16x16x32_bf16 v[120:123], v[172:175], v[180:183], v[120:123]
	v_mfma_f32_16x16x32_bf16 v[96:99], v[164:167], v[188:191], v[96:99]
	v_mfma_f32_16x16x32_bf16 v[104:107], v[172:175], v[188:191], v[104:107]
	v_mfma_f32_16x16x32_bf16 v[80:83], v[164:167], v[196:199], v[80:83]
	v_mfma_f32_16x16x32_bf16 v[88:91], v[172:175], v[196:199], v[88:91]
	v_mfma_f32_16x16x32_bf16 v[64:67], v[164:167], v[208:211], v[64:67]
	v_mfma_f32_16x16x32_bf16 v[72:75], v[172:175], v[208:211], v[72:75]
	v_mfma_f32_16x16x32_bf16 v[112:115], v[168:171], v[184:187], v[112:115]
	v_mfma_f32_16x16x32_bf16 v[120:123], v[176:179], v[184:187], v[120:123]
	v_mfma_f32_16x16x32_bf16 v[96:99], v[168:171], v[192:195], v[96:99]
	v_mfma_f32_16x16x32_bf16 v[104:107], v[176:179], v[192:195], v[104:107]
	v_mfma_f32_16x16x32_bf16 v[80:83], v[168:171], v[204:207], v[80:83]
	v_mfma_f32_16x16x32_bf16 v[88:91], v[176:179], v[204:207], v[88:91]
	v_mfma_f32_16x16x32_bf16 v[64:67], v[168:171], v[212:215], v[64:67]
	v_mfma_f32_16x16x32_bf16 v[72:75], v[176:179], v[212:215], v[72:75]
	s_setprio 0
	s_barrier
; #define PG8_STAGE(bufoff, gbase, voff) do { _Pragma("unroll") for (int _i = 0; _i < 2; ++_i) \
;         __builtin_amdgcn_global_load_lds((const unsigned*)((const char*)(gbase) + (voff)[_i]), (LAS unsigned*)(lds + (bufoff) + ldsw + _i * 8192), 16, 0, 0); } while (0)
; #define PG8_LDA(dst, b, h) do { _Pragma("unroll") for (int m = 0; m < 4; ++m) _Pragma("unroll") for (int k = 0; k < 2; ++k) dst[m][k] = *(const LAS bf16x8*)(lds + PG8_SA(b, h) + aoff + m * 2048 + k * 1024); } while (0)
; #define PG8_MMA(ai, bj, At, Bt) do { __builtin_amdgcn_s_setprio(1); _Pragma("unroll") for (int m = 0; m < 4; ++m) _Pragma("unroll") for (int n = 0; n < 2; ++n) _Pragma("unroll") for (int k = 0; k < 2; ++k) \
;         acc[ai][bj][m][n] = __builtin_amdgcn_mfma_f32_16x16x32_bf16(Bt[n][k], At[m][k], acc[ai][bj][m][n], 0, 0, 0); __builtin_amdgcn_s_setprio(0); } while (0)
; #define PG8_WAIT_V(n) asm volatile("s_waitcnt vmcnt(" #n ")" ::: "memory")
; #define PG8_WAIT_L(n) asm volatile("s_waitcnt lgkmcnt(" #n ")" ::: "memory")
; #define PG8_BAR __builtin_amdgcn_s_barrier()
; #define PG8_SCHED __builtin_amdgcn_sched_barrier(0)
; template <class Epi>
; __device__ __forceinline__ void gemm_phase(LAS unsigned char* lds, const Gemm g, const Sched& S, const Epi& E) {
;     ...
;             PG8_LDA(At, 1, 1); PG8_STAGE(PG8_SB(1, 0), b3, voffB); PG8_STAGE(PG8_SB(1, 1), b3 + hstepB, voffB); PG8_STAGE(PG8_SA(1, 0), a3, voffA);
;             PG8_WAIT_V(8); PG8_WAIT_L(0); PG8_BAR; PG8_MMA(1, 0, At, B0); PG8_MMA(1, 1, At, B1); PG8_BAR; PG8_SCHED;
;         }
;         if (wr == 0) PG8_BAR;
	s_add_i32 s36, s54, s39
	v_lshl_add_u64 v[140:141], v[140:141], 0, s[4:5]
	s_mov_b32 m0, s36
	ds_read_b128 v[180:183], v147 offset:49152
	ds_read_b128 v[184:187], v147 offset:50176
	ds_read_b128 v[188:191], v147 offset:51200
	ds_read_b128 v[192:195], v147 offset:52224
	ds_read_b128 v[196:199], v147 offset:53248
	ds_read_b128 v[204:207], v147 offset:54272
	ds_read_b128 v[208:211], v147 offset:55296
	ds_read_b128 v[212:215], v147 offset:56320
	global_load_lds_dwordx4 v[140:141], off
	s_add_i32 m0, s36, 0x2000
	s_add_u32 s28, s28, 0x40080
	v_lshl_add_u64 v[140:141], v[200:201], 0, s[4:5]
	s_addc_u32 s29, s29, 0
	s_add_i32 s36, s55, s39
	global_load_lds_dwordx4 v[140:141], off
	v_lshl_add_u64 v[140:141], s[28:29], 0, v[130:131]
	s_mov_b32 m0, s36
	s_nop 0
	global_load_lds_dwordx4 v[140:141], off
	v_lshl_add_u64 v[140:141], s[28:29], 0, v[134:135]
	s_add_i32 m0, s36, 0x2000
	s_nop 0
	global_load_lds_dwordx4 v[140:141], off
	v_lshl_add_u64 v[140:141], v[216:217], 0, s[4:5]
	s_mov_b32 m0, s44
	s_nop 0
	global_load_lds_dwordx4 v[140:141], off
	v_lshl_add_u64 v[140:141], v[218:219], 0, s[4:5]
	s_mov_b32 m0, s45
	s_nop 0
	global_load_lds_dwordx4 v[140:141], off
	s_waitcnt vmcnt(8)
	s_waitcnt lgkmcnt(0)
	s_barrier
	s_setprio 1
	v_mfma_f32_16x16x32_bf16 v[52:55], v[148:151], v[180:183], v[52:55]
	v_mfma_f32_16x16x32_bf16 v[60:63], v[156:159], v[180:183], v[60:63]
	v_mfma_f32_16x16x32_bf16 v[36:39], v[148:151], v[188:191], v[36:39]
	v_mfma_f32_16x16x32_bf16 v[44:47], v[156:159], v[188:191], v[44:47]
	v_mfma_f32_16x16x32_bf16 v[20:23], v[148:151], v[196:199], v[20:23]
	v_mfma_f32_16x16x32_bf16 v[28:31], v[156:159], v[196:199], v[28:31]
	v_mfma_f32_16x16x32_bf16 v[4:7], v[148:151], v[208:211], v[4:7]
	v_mfma_f32_16x16x32_bf16 v[12:15], v[156:159], v[208:211], v[12:15]
	v_mfma_f32_16x16x32_bf16 v[52:55], v[152:155], v[184:187], v[52:55]
	v_mfma_f32_16x16x32_bf16 v[60:63], v[160:163], v[184:187], v[60:63]
	v_mfma_f32_16x16x32_bf16 v[36:39], v[152:155], v[192:195], v[36:39]
	v_mfma_f32_16x16x32_bf16 v[44:47], v[160:163], v[192:195], v[44:47]
	v_mfma_f32_16x16x32_bf16 v[20:23], v[152:155], v[204:207], v[20:23]
	v_mfma_f32_16x16x32_bf16 v[28:31], v[160:163], v[204:207], v[28:31]
	v_mfma_f32_16x16x32_bf16 v[4:7], v[152:155], v[212:215], v[4:7]
	v_mfma_f32_16x16x32_bf16 v[12:15], v[160:163], v[212:215], v[12:15]
	v_mfma_f32_16x16x32_bf16 v[48:51], v[164:167], v[180:183], v[48:51]
	v_mfma_f32_16x16x32_bf16 v[56:59], v[172:175], v[180:183], v[56:59]
	v_mfma_f32_16x16x32_bf16 v[32:35], v[164:167], v[188:191], v[32:35]
	v_mfma_f32_16x16x32_bf16 v[40:43], v[172:175], v[188:191], v[40:43]
	v_mfma_f32_16x16x32_bf16 v[16:19], v[164:167], v[196:199], v[16:19]
	v_mfma_f32_16x16x32_bf16 v[24:27], v[172:175], v[196:199], v[24:27]
	v_mfma_f32_16x16x32_bf16 v[0:3], v[164:167], v[208:211], v[0:3]
	v_mfma_f32_16x16x32_bf16 v[8:11], v[172:175], v[208:211], v[8:11]
	v_mfma_f32_16x16x32_bf16 v[48:51], v[168:171], v[184:187], v[48:51]
	v_mfma_f32_16x16x32_bf16 v[56:59], v[176:179], v[184:187], v[56:59]
	v_mfma_f32_16x16x32_bf16 v[32:35], v[168:171], v[192:195], v[32:35]
	v_mfma_f32_16x16x32_bf16 v[40:43], v[176:179], v[192:195], v[40:43]
	v_mfma_f32_16x16x32_bf16 v[16:19], v[168:171], v[204:207], v[16:19]
	v_mfma_f32_16x16x32_bf16 v[24:27], v[176:179], v[204:207], v[24:27]
	v_mfma_f32_16x16x32_bf16 v[0:3], v[168:171], v[212:215], v[0:3]
	v_mfma_f32_16x16x32_bf16 v[8:11], v[176:179], v[212:215], v[8:11]
	s_setprio 0
	s_barrier
	s_add_i32 s53, s53, 2
	s_add_u32 s26, s26, 0x100
	s_addc_u32 s27, s27, 0
	s_add_u32 s51, s51, 0x100
	s_addc_u32 s52, s52, 0
	s_cmp_gt_u32 s53, 13
	s_cbranch_scc0 .LBB0_1731
	s_and_b64 vcc, exec, s[6:7]
	s_cbranch_vccz .LBB0_1734
	s_barrier

; #define PG8_STAGE(bufoff, gbase, voff) do { _Pragma("unroll") for (int _i = 0; _i < 2; ++_i) \
;         __builtin_amdgcn_global_load_lds((const unsigned*)((const char*)(gbase) + (voff)[_i]), (LAS unsigned*)(lds + (bufoff) + ldsw + _i * 8192), 16, 0, 0); } while (0)
; #define PG8_LDA(dst, b, h) do { _Pragma("unroll") for (int m = 0; m < 4; ++m) _Pragma("unroll") for (int k = 0; k < 2; ++k) dst[m][k] = *(const LAS bf16x8*)(lds + PG8_SA(b, h) + aoff + m * 2048 + k * 1024); } while (0)
; #define PG8_LDB(dst, b, h) do { _Pragma("unroll") for (int n = 0; n < 2; ++n) _Pragma("unroll") for (int k = 0; k < 2; ++k) dst[n][k] = *(const LAS bf16x8*)(lds + PG8_SB(b, h) + boff + n * 2048 + k * 1024); } while (0)
; #define PG8_MMA(ai, bj, At, Bt) do { __builtin_amdgcn_s_setprio(1); _Pragma("unroll") for (int m = 0; m < 4; ++m) _Pragma("unroll") for (int n = 0; n < 2; ++n) _Pragma("unroll") for (int k = 0; k < 2; ++k) \
;         acc[ai][bj][m][n] = __builtin_amdgcn_mfma_f32_16x16x32_bf16(Bt[n][k], At[m][k], acc[ai][bj][m][n], 0, 0, 0); __builtin_amdgcn_s_setprio(0); } while (0)
; #define PG8_WAIT_V(n) asm volatile("s_waitcnt vmcnt(" #n ")" ::: "memory")
; #define PG8_WAIT_L(n) asm volatile("s_waitcnt lgkmcnt(" #n ")" ::: "memory")
; #define PG8_BAR __builtin_amdgcn_s_barrier()
; #define PG8_SCHED __builtin_amdgcn_sched_barrier(0)
; template <class Epi>
; __device__ __forceinline__ void gemm_phase(LAS unsigned char* lds, const Gemm g, const Sched& S, const Epi& E) {
;     ...
;         for (int t = 0; t < nt; t += 2) {
;             const bool last = (t == nt - 2);
;             const char* a1 = cA + (size_t)(t + 1) * kstep;
;             const char* a2 = last ? nA : cA + (size_t)(t + 2) * kstep; const char* b2 = last ? nB : cB + (size_t)(t + 2) * kstep;
;             const char* a3 = a2 + kstep; const char* b3 = b2 + kstep;
;             PG8_LDB(B0, 0, 0); PG8_LDB(B1, 0, 1); PG8_SCHED; PG8_LDA(At, 0, 0); PG8_STAGE(PG8_SA(1, 1), a1 + hstepA, voffA);
;             PG8_WAIT_V(8); PG8_WAIT_L(0); PG8_BAR; PG8_MMA(0, 0, At, B0); PG8_MMA(0, 1, At, B1); PG8_BAR; PG8_SCHED;
;             PG8_LDA(At, 0, 1); PG8_STAGE(PG8_SB(0, 0), b2, voffB); PG8_STAGE(PG8_SB(0, 1), b2 + hstepB, voffB); PG8_STAGE(PG8_SA(0, 0), a2, voffA);
;             PG8_WAIT_V(8); PG8_WAIT_L(0); PG8_BAR; PG8_MMA(1, 0, At, B0); PG8_MMA(1, 1, At, B1); PG8_BAR; PG8_SCHED;
.LBB0_1827:
	v_add_u32_e32 v158, s54, v144
	v_add_u32_e32 v174, s55, v144
	s_add_u32 s36, s26, s28
	ds_read_b128 v[146:149], v158
	ds_read_b128 v[150:153], v158 offset:1024
	ds_read_b128 v[154:157], v158 offset:2048
	ds_read_b128 v[158:161], v158 offset:3072
	ds_read_b128 v[162:165], v174
	ds_read_b128 v[166:169], v174 offset:1024
	ds_read_b128 v[170:173], v174 offset:2048
	ds_read_b128 v[174:177], v174 offset:3072
	s_addc_u32 s37, s27, s29
	s_add_u32 s36, s36, 0x100
	s_addc_u32 s37, s37, 0
	s_add_u32 s66, s63, s28
	s_addc_u32 s67, s64, s29
	s_cmpk_eq_i32 s28, 0x1500
	s_cselect_b32 s39, s23, s37
	s_cselect_b32 s38, s22, s36
	s_cselect_b32 s37, s25, s67
	s_cselect_b32 s36, s24, s66
	s_mov_b32 m0, s56
	v_lshl_add_u64 v[214:215], v[140:141], 0, s[28:29]
	ds_read_b128 v[178:181], v145
	ds_read_b128 v[182:185], v145 offset:1024
	ds_read_b128 v[186:189], v145 offset:2048
	ds_read_b128 v[190:193], v145 offset:3072
	ds_read_b128 v[194:197], v145 offset:4096
	ds_read_b128 v[198:201], v145 offset:5120
	ds_read_b128 v[206:209], v145 offset:6144
	ds_read_b128 v[210:213], v145 offset:7168
	global_load_lds_dwordx4 v[214:215], off
	v_lshl_add_u64 v[214:215], v[142:143], 0, s[28:29]
	s_mov_b32 m0, s57
	s_nop 0
	global_load_lds_dwordx4 v[214:215], off
	s_waitcnt vmcnt(8)
	s_waitcnt lgkmcnt(0)
	s_barrier
	s_setprio 1
	v_mfma_f32_16x16x32_bf16 v[124:127], v[146:149], v[178:181], v[124:127]
	v_mfma_f32_16x16x32_bf16 v[120:123], v[154:157], v[178:181], v[120:123]
	v_mfma_f32_16x16x32_bf16 v[108:111], v[146:149], v[186:189], v[108:111]
	v_mfma_f32_16x16x32_bf16 v[104:107], v[154:157], v[186:189], v[104:107]
	v_mfma_f32_16x16x32_bf16 v[92:95], v[146:149], v[194:197], v[92:95]
	v_mfma_f32_16x16x32_bf16 v[88:91], v[154:157], v[194:197], v[88:91]
	v_mfma_f32_16x16x32_bf16 v[76:79], v[146:149], v[206:209], v[76:79]
	v_mfma_f32_16x16x32_bf16 v[72:75], v[154:157], v[206:209], v[72:75]
	v_mfma_f32_16x16x32_bf16 v[124:127], v[150:153], v[182:185], v[124:127]
	v_mfma_f32_16x16x32_bf16 v[120:123], v[158:161], v[182:185], v[120:123]
	v_mfma_f32_16x16x32_bf16 v[108:111], v[150:153], v[190:193], v[108:111]
	v_mfma_f32_16x16x32_bf16 v[104:107], v[158:161], v[190:193], v[104:107]
	v_mfma_f32_16x16x32_bf16 v[92:95], v[150:153], v[198:201], v[92:95]
	v_mfma_f32_16x16x32_bf16 v[88:91], v[158:161], v[198:201], v[88:91]
	v_mfma_f32_16x16x32_bf16 v[76:79], v[150:153], v[210:213], v[76:79]
	v_mfma_f32_16x16x32_bf16 v[72:75], v[158:161], v[210:213], v[72:75]
	v_mfma_f32_16x16x32_bf16 v[116:119], v[162:165], v[178:181], v[116:119]
	v_mfma_f32_16x16x32_bf16 v[112:115], v[170:173], v[178:181], v[112:115]
	v_mfma_f32_16x16x32_bf16 v[100:103], v[162:165], v[186:189], v[100:103]
	v_mfma_f32_16x16x32_bf16 v[96:99], v[170:173], v[186:189], v[96:99]
	v_mfma_f32_16x16x32_bf16 v[84:87], v[162:165], v[194:197], v[84:87]
	v_mfma_f32_16x16x32_bf16 v[80:83], v[170:173], v[194:197], v[80:83]
	v_mfma_f32_16x16x32_bf16 v[68:71], v[162:165], v[206:209], v[68:71]
	v_mfma_f32_16x16x32_bf16 v[64:67], v[170:173], v[206:209], v[64:67]
	v_mfma_f32_16x16x32_bf16 v[116:119], v[166:169], v[182:185], v[116:119]
	v_mfma_f32_16x16x32_bf16 v[112:115], v[174:177], v[182:185], v[112:115]
	v_mfma_f32_16x16x32_bf16 v[100:103], v[166:169], v[190:193], v[100:103]
	v_mfma_f32_16x16x32_bf16 v[96:99], v[174:177], v[190:193], v[96:99]
	v_mfma_f32_16x16x32_bf16 v[84:87], v[166:169], v[198:201], v[84:87]
	v_mfma_f32_16x16x32_bf16 v[80:83], v[174:177], v[198:201], v[80:83]
	v_mfma_f32_16x16x32_bf16 v[68:71], v[166:169], v[210:213], v[68:71]
	v_mfma_f32_16x16x32_bf16 v[64:67], v[174:177], v[210:213], v[64:67]
	s_setprio 0
	s_barrier
	s_mov_b32 m0, s58
	v_lshl_add_u64 v[214:215], s[36:37], 0, v[130:131]
	ds_read_b128 v[178:181], v145 offset:16384
	ds_read_b128 v[182:185], v145 offset:17408
	ds_read_b128 v[186:189], v145 offset:18432
	ds_read_b128 v[190:193], v145 offset:19456
	ds_read_b128 v[194:197], v145 offset:20480
	ds_read_b128 v[198:201], v145 offset:21504
	ds_read_b128 v[206:209], v145 offset:22528
	ds_read_b128 v[210:213], v145 offset:23552
	global_load_lds_dwordx4 v[214:215], off
	s_add_i32 m0, s58, 0x2000
	s_add_u32 s66, s36, 0xb0000
	v_lshl_add_u64 v[216:217], s[36:37], 0, v[134:135]
	s_addc_u32 s67, s37, 0
	s_add_i32 s68, s55, s46
	global_load_lds_dwordx4 v[216:217], off
	v_lshl_add_u64 v[218:219], s[66:67], 0, v[130:131]
	s_mov_b32 m0, s68
	v_lshl_add_u64 v[220:221], s[38:39], 0, v[132:133]
	global_load_lds_dwordx4 v[218:219], off
	v_lshl_add_u64 v[218:219], s[66:67], 0, v[134:135]
	s_add_i32 m0, s68, 0x2000
	s_nop 0
	global_load_lds_dwordx4 v[218:219], off
	v_lshl_add_u64 v[218:219], s[38:39], 0, v[128:129]
	s_mov_b32 m0, s47
	s_nop 0
	global_load_lds_dwordx4 v[218:219], off
	s_mov_b32 m0, s48
	s_nop 0
	global_load_lds_dwordx4 v[220:221], off
	s_waitcnt vmcnt(8)
	s_waitcnt lgkmcnt(0)
	s_barrier
; #define PG8_STAGE(bufoff, gbase, voff) do { _Pragma("unroll") for (int _i = 0; _i < 2; ++_i) \
;         __builtin_amdgcn_global_load_lds((const unsigned*)((const char*)(gbase) + (voff)[_i]), (LAS unsigned*)(lds + (bufoff) + ldsw + _i * 8192), 16, 0, 0); } while (0)
; #define PG8_LDA(dst, b, h) do { _Pragma("unroll") for (int m = 0; m < 4; ++m) _Pragma("unroll") for (int k = 0; k < 2; ++k) dst[m][k] = *(const LAS bf16x8*)(lds + PG8_SA(b, h) + aoff + m * 2048 + k * 1024); } while (0)
; #define PG8_LDB(dst, b, h) do { _Pragma("unroll") for (int n = 0; n < 2; ++n) _Pragma("unroll") for (int k = 0; k < 2; ++k) dst[n][k] = *(const LAS bf16x8*)(lds + PG8_SB(b, h) + boff + n * 2048 + k * 1024); } while (0)
; #define PG8_MMA(ai, bj, At, Bt) do { __builtin_amdgcn_s_setprio(1); _Pragma("unroll") for (int m = 0; m < 4; ++m) _Pragma("unroll") for (int n = 0; n < 2; ++n) _Pragma("unroll") for (int k = 0; k < 2; ++k) \
;         acc[ai][bj][m][n] = __builtin_amdgcn_mfma_f32_16x16x32_bf16(Bt[n][k], At[m][k], acc[ai][bj][m][n], 0, 0, 0); __builtin_amdgcn_s_setprio(0); } while (0)
; #define PG8_WAIT_V(n) asm volatile("s_waitcnt vmcnt(" #n ")" ::: "memory")
; #define PG8_WAIT_L(n) asm volatile("s_waitcnt lgkmcnt(" #n ")" ::: "memory")
; #define PG8_BAR __builtin_amdgcn_s_barrier()
; #define PG8_SCHED __builtin_amdgcn_sched_barrier(0)
; template <class Epi>
; __device__ __forceinline__ void gemm_phase(LAS unsigned char* lds, const Gemm g, const Sched& S, const Epi& E) {
;     ...
;             PG8_WAIT_V(8); PG8_WAIT_L(0); PG8_BAR; PG8_MMA(1, 0, At, B0); PG8_MMA(1, 1, At, B1); PG8_BAR; PG8_SCHED;
;             PG8_LDB(B0, 1, 0); PG8_LDB(B1, 1, 1); PG8_SCHED; PG8_LDA(At, 1, 0); PG8_STAGE(PG8_SA(0, 1), a2 + hstepA, voffA);
;             PG8_WAIT_V(8); PG8_WAIT_L(0); PG8_BAR; PG8_MMA(0, 0, At, B0); PG8_MMA(0, 1, At, B1); PG8_BAR; PG8_SCHED;
	s_setprio 1
	v_mfma_f32_16x16x32_bf16 v[60:63], v[146:149], v[178:181], v[60:63]
	v_mfma_f32_16x16x32_bf16 v[56:59], v[154:157], v[178:181], v[56:59]
	v_mfma_f32_16x16x32_bf16 v[44:47], v[146:149], v[186:189], v[44:47]
	v_mfma_f32_16x16x32_bf16 v[40:43], v[154:157], v[186:189], v[40:43]
	v_mfma_f32_16x16x32_bf16 v[28:31], v[146:149], v[194:197], v[28:31]
	v_mfma_f32_16x16x32_bf16 v[24:27], v[154:157], v[194:197], v[24:27]
	v_mfma_f32_16x16x32_bf16 v[12:15], v[146:149], v[206:209], v[12:15]
	v_mfma_f32_16x16x32_bf16 v[8:11], v[154:157], v[206:209], v[8:11]
	v_mfma_f32_16x16x32_bf16 v[60:63], v[150:153], v[182:185], v[60:63]
	v_mfma_f32_16x16x32_bf16 v[56:59], v[158:161], v[182:185], v[56:59]
	v_mfma_f32_16x16x32_bf16 v[44:47], v[150:153], v[190:193], v[44:47]
	v_mfma_f32_16x16x32_bf16 v[40:43], v[158:161], v[190:193], v[40:43]
	v_mfma_f32_16x16x32_bf16 v[28:31], v[150:153], v[198:201], v[28:31]
	v_mfma_f32_16x16x32_bf16 v[24:27], v[158:161], v[198:201], v[24:27]
	v_mfma_f32_16x16x32_bf16 v[12:15], v[150:153], v[210:213], v[12:15]
	v_mfma_f32_16x16x32_bf16 v[8:11], v[158:161], v[210:213], v[8:11]
	v_mfma_f32_16x16x32_bf16 v[52:55], v[162:165], v[178:181], v[52:55]
	v_mfma_f32_16x16x32_bf16 v[48:51], v[170:173], v[178:181], v[48:51]
	v_mfma_f32_16x16x32_bf16 v[36:39], v[162:165], v[186:189], v[36:39]
	v_mfma_f32_16x16x32_bf16 v[32:35], v[170:173], v[186:189], v[32:35]
	v_mfma_f32_16x16x32_bf16 v[20:23], v[162:165], v[194:197], v[20:23]
	v_mfma_f32_16x16x32_bf16 v[16:19], v[170:173], v[194:197], v[16:19]
	v_mfma_f32_16x16x32_bf16 v[4:7], v[162:165], v[206:209], v[4:7]
	v_mfma_f32_16x16x32_bf16 v[0:3], v[170:173], v[206:209], v[0:3]
	v_mfma_f32_16x16x32_bf16 v[52:55], v[166:169], v[182:185], v[52:55]
	v_mfma_f32_16x16x32_bf16 v[48:51], v[174:177], v[182:185], v[48:51]
	v_mfma_f32_16x16x32_bf16 v[36:39], v[166:169], v[190:193], v[36:39]
	v_mfma_f32_16x16x32_bf16 v[32:35], v[174:177], v[190:193], v[32:35]
	v_mfma_f32_16x16x32_bf16 v[20:23], v[166:169], v[198:201], v[20:23]
	v_mfma_f32_16x16x32_bf16 v[16:19], v[174:177], v[198:201], v[16:19]
	v_mfma_f32_16x16x32_bf16 v[4:7], v[166:169], v[210:213], v[4:7]
	v_mfma_f32_16x16x32_bf16 v[0:3], v[174:177], v[210:213], v[0:3]
	s_setprio 0
	s_barrier
	s_add_i32 s66, 0, 0x18000
	s_add_i32 s67, 0, 0x1c000
	v_add_u32_e32 v158, s66, v144
	v_add_u32_e32 v174, s67, v144
	ds_read_b128 v[146:149], v158
	ds_read_b128 v[150:153], v158 offset:1024
	ds_read_b128 v[154:157], v158 offset:2048
	ds_read_b128 v[158:161], v158 offset:3072
	ds_read_b128 v[162:165], v174
	ds_read_b128 v[166:169], v174 offset:1024
	ds_read_b128 v[170:173], v174 offset:2048
	ds_read_b128 v[174:177], v174 offset:3072
	s_add_u32 s38, s38, 0xb0000
	s_addc_u32 s39, s39, 0
	s_mov_b32 m0, s49
	v_lshl_add_u64 v[222:223], s[38:39], 0, v[128:129]
	ds_read_b128 v[178:181], v145 offset:32768
	ds_read_b128 v[182:185], v145 offset:33792
	ds_read_b128 v[186:189], v145 offset:34816
	ds_read_b128 v[190:193], v145 offset:35840
	ds_read_b128 v[194:197], v145 offset:36864
	ds_read_b128 v[198:201], v145 offset:37888
	ds_read_b128 v[206:209], v145 offset:38912
	ds_read_b128 v[210:213], v145 offset:39936
	global_load_lds_dwordx4 v[222:223], off
	v_lshl_add_u64 v[222:223], s[38:39], 0, v[132:133]
	s_mov_b32 m0, s50
	s_nop 0
	global_load_lds_dwordx4 v[222:223], off
	s_waitcnt vmcnt(8)
	s_waitcnt lgkmcnt(0)
	s_barrier
	s_setprio 1
	v_mfma_f32_16x16x32_bf16 v[124:127], v[146:149], v[178:181], v[124:127]
	v_mfma_f32_16x16x32_bf16 v[120:123], v[154:157], v[178:181], v[120:123]
	v_mfma_f32_16x16x32_bf16 v[108:111], v[146:149], v[186:189], v[108:111]
	v_mfma_f32_16x16x32_bf16 v[104:107], v[154:157], v[186:189], v[104:107]
	v_mfma_f32_16x16x32_bf16 v[92:95], v[146:149], v[194:197], v[92:95]
	v_mfma_f32_16x16x32_bf16 v[88:91], v[154:157], v[194:197], v[88:91]
	v_mfma_f32_16x16x32_bf16 v[76:79], v[146:149], v[206:209], v[76:79]
	v_mfma_f32_16x16x32_bf16 v[72:75], v[154:157], v[206:209], v[72:75]
	v_mfma_f32_16x16x32_bf16 v[124:127], v[150:153], v[182:185], v[124:127]
	v_mfma_f32_16x16x32_bf16 v[120:123], v[158:161], v[182:185], v[120:123]
	v_mfma_f32_16x16x32_bf16 v[108:111], v[150:153], v[190:193], v[108:111]
	v_mfma_f32_16x16x32_bf16 v[104:107], v[158:161], v[190:193], v[104:107]
	v_mfma_f32_16x16x32_bf16 v[92:95], v[150:153], v[198:201], v[92:95]
	v_mfma_f32_16x16x32_bf16 v[88:91], v[158:161], v[198:201], v[88:91]
	v_mfma_f32_16x16x32_bf16 v[76:79], v[150:153], v[210:213], v[76:79]
	v_mfma_f32_16x16x32_bf16 v[72:75], v[158:161], v[210:213], v[72:75]
	v_mfma_f32_16x16x32_bf16 v[116:119], v[162:165], v[178:181], v[116:119]
	v_mfma_f32_16x16x32_bf16 v[112:115], v[170:173], v[178:181], v[112:115]
	v_mfma_f32_16x16x32_bf16 v[100:103], v[162:165], v[186:189], v[100:103]
	v_mfma_f32_16x16x32_bf16 v[96:99], v[170:173], v[186:189], v[96:99]
	v_mfma_f32_16x16x32_bf16 v[84:87], v[162:165], v[194:197], v[84:87]
	v_mfma_f32_16x16x32_bf16 v[80:83], v[170:173], v[194:197], v[80:83]
	v_mfma_f32_16x16x32_bf16 v[68:71], v[162:165], v[206:209], v[68:71]
	v_mfma_f32_16x16x32_bf16 v[64:67], v[170:173], v[206:209], v[64:67]
	v_mfma_f32_16x16x32_bf16 v[116:119], v[166:169], v[182:185], v[116:119]
	v_mfma_f32_16x16x32_bf16 v[112:115], v[174:177], v[182:185], v[112:115]
	v_mfma_f32_16x16x32_bf16 v[100:103], v[166:169], v[190:193], v[100:103]
	v_mfma_f32_16x16x32_bf16 v[96:99], v[174:177], v[190:193], v[96:99]
	v_mfma_f32_16x16x32_bf16 v[84:87], v[166:169], v[198:201], v[84:87]
	v_mfma_f32_16x16x32_bf16 v[80:83], v[174:177], v[198:201], v[80:83]
	v_mfma_f32_16x16x32_bf16 v[68:71], v[166:169], v[210:213], v[68:71]
	v_mfma_f32_16x16x32_bf16 v[64:67], v[174:177], v[210:213], v[64:67]
	s_setprio 0
	s_barrier
; #define PG8_STAGE(bufoff, gbase, voff) do { _Pragma("unroll") for (int _i = 0; _i < 2; ++_i) \
;         __builtin_amdgcn_global_load_lds((const unsigned*)((const char*)(gbase) + (voff)[_i]), (LAS unsigned*)(lds + (bufoff) + ldsw + _i * 8192), 16, 0, 0); } while (0)
; #define PG8_LDA(dst, b, h) do { _Pragma("unroll") for (int m = 0; m < 4; ++m) _Pragma("unroll") for (int k = 0; k < 2; ++k) dst[m][k] = *(const LAS bf16x8*)(lds + PG8_SA(b, h) + aoff + m * 2048 + k * 1024); } while (0)
; #define PG8_MMA(ai, bj, At, Bt) do { __builtin_amdgcn_s_setprio(1); _Pragma("unroll") for (int m = 0; m < 4; ++m) _Pragma("unroll") for (int n = 0; n < 2; ++n) _Pragma("unroll") for (int k = 0; k < 2; ++k) \
;         acc[ai][bj][m][n] = __builtin_amdgcn_mfma_f32_16x16x32_bf16(Bt[n][k], At[m][k], acc[ai][bj][m][n], 0, 0, 0); __builtin_amdgcn_s_setprio(0); } while (0)
; #define PG8_WAIT_V(n) asm volatile("s_waitcnt vmcnt(" #n ")" ::: "memory")
; #define PG8_WAIT_L(n) asm volatile("s_waitcnt lgkmcnt(" #n ")" ::: "memory")
; #define PG8_BAR __builtin_amdgcn_s_barrier()
; #define PG8_SCHED __builtin_amdgcn_sched_barrier(0)
; template <class Epi>
; __device__ __forceinline__ void gemm_phase(LAS unsigned char* lds, const Gemm g, const Sched& S, const Epi& E) {
;     ...
;             PG8_LDA(At, 1, 1); PG8_STAGE(PG8_SB(1, 0), b3, voffB); PG8_STAGE(PG8_SB(1, 1), b3 + hstepB, voffB); PG8_STAGE(PG8_SA(1, 0), a3, voffA);
;             PG8_WAIT_V(8); PG8_WAIT_L(0); PG8_BAR; PG8_MMA(1, 0, At, B0); PG8_MMA(1, 1, At, B1); PG8_BAR; PG8_SCHED;
;         }
;         if (wr == 0) PG8_BAR;
	s_add_i32 s38, s66, s46
	v_lshl_add_u64 v[214:215], v[214:215], 0, s[16:17]
	s_mov_b32 m0, s38
	ds_read_b128 v[178:181], v145 offset:49152
	ds_read_b128 v[182:185], v145 offset:50176
	ds_read_b128 v[186:189], v145 offset:51200
	ds_read_b128 v[190:193], v145 offset:52224
	ds_read_b128 v[194:197], v145 offset:53248
	ds_read_b128 v[198:201], v145 offset:54272
	ds_read_b128 v[206:209], v145 offset:55296
	ds_read_b128 v[210:213], v145 offset:56320
	global_load_lds_dwordx4 v[214:215], off
	s_add_i32 m0, s38, 0x2000
	s_add_u32 s36, s36, 0xb0080
	v_lshl_add_u64 v[214:215], v[216:217], 0, s[16:17]
	s_addc_u32 s37, s37, 0
	s_add_i32 s38, s67, s46
	global_load_lds_dwordx4 v[214:215], off
	v_lshl_add_u64 v[214:215], s[36:37], 0, v[130:131]
	s_mov_b32 m0, s38
	s_nop 0
	global_load_lds_dwordx4 v[214:215], off
	v_lshl_add_u64 v[214:215], s[36:37], 0, v[134:135]
	s_add_i32 m0, s38, 0x2000
	s_nop 0
	global_load_lds_dwordx4 v[214:215], off
	v_lshl_add_u64 v[214:215], v[218:219], 0, s[16:17]
	s_mov_b32 m0, s52
	s_nop 0
	global_load_lds_dwordx4 v[214:215], off
	v_lshl_add_u64 v[214:215], v[220:221], 0, s[16:17]
	s_mov_b32 m0, s53
	s_nop 0
	global_load_lds_dwordx4 v[214:215], off
	s_waitcnt vmcnt(8)
	s_waitcnt lgkmcnt(0)
	s_barrier
	s_setprio 1
	v_mfma_f32_16x16x32_bf16 v[60:63], v[146:149], v[178:181], v[60:63]
	v_mfma_f32_16x16x32_bf16 v[56:59], v[154:157], v[178:181], v[56:59]
	v_mfma_f32_16x16x32_bf16 v[44:47], v[146:149], v[186:189], v[44:47]
	v_mfma_f32_16x16x32_bf16 v[40:43], v[154:157], v[186:189], v[40:43]
	v_mfma_f32_16x16x32_bf16 v[28:31], v[146:149], v[194:197], v[28:31]
	v_mfma_f32_16x16x32_bf16 v[24:27], v[154:157], v[194:197], v[24:27]
	v_mfma_f32_16x16x32_bf16 v[12:15], v[146:149], v[206:209], v[12:15]
	v_mfma_f32_16x16x32_bf16 v[8:11], v[154:157], v[206:209], v[8:11]
	v_mfma_f32_16x16x32_bf16 v[60:63], v[150:153], v[182:185], v[60:63]
	v_mfma_f32_16x16x32_bf16 v[56:59], v[158:161], v[182:185], v[56:59]
	v_mfma_f32_16x16x32_bf16 v[44:47], v[150:153], v[190:193], v[44:47]
	v_mfma_f32_16x16x32_bf16 v[40:43], v[158:161], v[190:193], v[40:43]
	v_mfma_f32_16x16x32_bf16 v[28:31], v[150:153], v[198:201], v[28:31]
	v_mfma_f32_16x16x32_bf16 v[24:27], v[158:161], v[198:201], v[24:27]
	v_mfma_f32_16x16x32_bf16 v[12:15], v[150:153], v[210:213], v[12:15]
	v_mfma_f32_16x16x32_bf16 v[8:11], v[158:161], v[210:213], v[8:11]
	v_mfma_f32_16x16x32_bf16 v[52:55], v[162:165], v[178:181], v[52:55]
	v_mfma_f32_16x16x32_bf16 v[48:51], v[170:173], v[178:181], v[48:51]
	v_mfma_f32_16x16x32_bf16 v[36:39], v[162:165], v[186:189], v[36:39]
	v_mfma_f32_16x16x32_bf16 v[32:35], v[170:173], v[186:189], v[32:35]
	v_mfma_f32_16x16x32_bf16 v[20:23], v[162:165], v[194:197], v[20:23]
	v_mfma_f32_16x16x32_bf16 v[16:19], v[170:173], v[194:197], v[16:19]
	v_mfma_f32_16x16x32_bf16 v[4:7], v[162:165], v[206:209], v[4:7]
	v_mfma_f32_16x16x32_bf16 v[0:3], v[170:173], v[206:209], v[0:3]
	v_mfma_f32_16x16x32_bf16 v[52:55], v[166:169], v[182:185], v[52:55]
	v_mfma_f32_16x16x32_bf16 v[48:51], v[174:177], v[182:185], v[48:51]
	v_mfma_f32_16x16x32_bf16 v[36:39], v[166:169], v[190:193], v[36:39]
	v_mfma_f32_16x16x32_bf16 v[32:35], v[174:177], v[190:193], v[32:35]
	v_mfma_f32_16x16x32_bf16 v[20:23], v[166:169], v[198:201], v[20:23]
	v_mfma_f32_16x16x32_bf16 v[16:19], v[174:177], v[198:201], v[16:19]
	v_mfma_f32_16x16x32_bf16 v[4:7], v[166:169], v[210:213], v[4:7]
	v_mfma_f32_16x16x32_bf16 v[0:3], v[174:177], v[210:213], v[0:3]
	s_setprio 0
	s_barrier
	s_add_i32 s65, s65, 2
	s_add_u32 s28, s28, 0x100
	s_addc_u32 s29, s29, 0
	s_cmp_gt_u32 s65, 41
	s_cbranch_scc0 .LBB0_1827
	s_and_b64 vcc, exec, s[18:19]
	s_cbranch_vccz .LBB0_1830
	s_barrier
